# balanced K-loops + saddr-form LDS-DMA (SGPR base + 32-bit VGPR offset) where the 64-bit VGPR address is dead: 96 v_lshl_add_u64 removed from the load segments
# speedup vs baseline: 1.0080x; 1.0080x over previous
; #define PG8_STAGE(bufoff, gbase, voff) do { _Pragma("unroll") for (int _i = 0; _i < 2; ++_i) \
;         __builtin_amdgcn_global_load_lds((const unsigned*)((const char*)(gbase) + (voff)[_i]), (PG8_LAS unsigned*)(lds + (bufoff) + ldsw + _i * 8192), 16, 0, 0); } while (0)
; #define PG8_LDA(dst, b, h) do { _Pragma("unroll") for (int m = 0; m < 4; ++m) _Pragma("unroll") for (int k = 0; k < 2; ++k) dst[m][k] = *(const PG8_LAS bf16x8*)(lds + PG8_SA(b, h) + aoff + m * 2048 + k * 1024); } while (0)
; #define PG8_LDB(dst, b, h) do { _Pragma("unroll") for (int n = 0; n < 2; ++n) _Pragma("unroll") for (int k = 0; k < 2; ++k) dst[n][k] = *(const PG8_LAS bf16x8*)(lds + PG8_SB(b, h) + boff + n * 2048 + k * 1024); } while (0)
; #define PG8_WAIT_V(n) asm volatile("s_waitcnt vmcnt(" #n ")" ::: "memory")
; #define PG8_WAIT_L(n) asm volatile("s_waitcnt lgkmcnt(" #n ")" ::: "memory")
; #define PG8_BAR __builtin_amdgcn_s_barrier()
; #define PG8_SCHED __builtin_amdgcn_sched_barrier(0)
; template <class Epi, class Sched, bool ALIGN_EPI = false, bool SP2 = false, bool I8 = false>
; __device__ __forceinline__ void gemm_phase(PG8_LAS unsigned char* lds, const Gemm g, const Sched& S, const Epi& E) {
;     ...
;     for (;;) {
;         const bool has_next = S.next(ui + 1, nxt);
;         const char* nA = has_next ? (const char*)g.A + (size_t)nxt.pm * tstep : cA; const char* nB = has_next ? (const char*)g.Bt + (size_t)nxt.pn * tstep : cB;
;         for (int t = 0; t < nt; t += 2) {
;             const bool last = (t == nt - 2);
;             const char* a1 = cA + (size_t)(t + 1) * kstep;
;             const char* a2 = last ? nA : cA + (size_t)(t + 2) * kstep; const char* b2 = last ? nB : cB + (size_t)(t + 2) * kstep;
;             const char* a3 = a2 + kstep; const char* b3 = b2 + kstep;
;             if (last && has_next) S.a_ready(nxt);
;             if constexpr (SP2) {
;             PG8_LDB(B0, 0, 0); PG8_LDB(B1, 0, 1); PG8_SCHED; PG8_LDA(At, 0, 0); PG8_STAGE(PG8_SA(1, 1), a1 + hstep, voffA);
;             PG8_WAIT_V(8); PG8_WAIT_L(0); PG8_BAR; PG8_MMA(0, 0, At, B0); PG8_MMA(0, 1, At, B1); PG8_BAR; PG8_SCHED;
;             PG8_LDA(At, 0, 1); PG8_STAGE(PG8_SB(0, 0), b2, voffB); PG8_STAGE(PG8_SB(0, 1), b2 + hstep, voffB); PG8_STAGE(PG8_SA(0, 0), a2, voffA);
.LBB0_207:
	s_ashr_i32 s19, s18, 31
	s_lshl_b64 s[22:23], s[18:19], 20
	s_add_u32 s22, s28, s22
	s_addc_u32 s23, s34, s23
	s_and_b64 s[24:25], s[6:7], exec
	s_cselect_b32 s19, s23, s27
	s_cselect_b32 s64, s22, s26
	s_ashr_i32 s17, s16, 31
	s_lshl_b64 s[24:25], s[16:17], 20
	s_add_u32 s24, s35, s24
	s_addc_u32 s25, s42, s25
	s_and_b64 s[40:41], s[6:7], exec
	s_cselect_b32 s17, s25, s37
	s_cselect_b32 s65, s24, s36
	s_add_u32 s26, s26, 0x80080
	s_addc_u32 s27, s27, 0
	s_add_u32 s72, s36, 0x100
	s_addc_u32 s73, s37, 0
	s_mov_b32 s76, -2
	s_add_u32 s36, s26, 0xfff80080
	s_addc_u32 s37, s27, -1
	s_add_i32 s50, 0, 0x10000
	s_cmp_eq_u32 s76, 28
	s_cselect_b32 s41, s19, s37
	s_cselect_b32 s40, s64, s36
	s_cselect_b32 s37, s17, s73
	s_cselect_b32 s36, s65, s72
	s_add_i32 s56, 0, 0x14000
	v_add_u32_e32 v136, s50, v175
	v_add_u32_e32 v172, s56, v175
	ds_read_b128 v[116:119], v136
	ds_read_b128 v[124:127], v136 offset:1024
	ds_read_b128 v[132:135], v136 offset:2048
	ds_read_b128 v[136:139], v136 offset:3072
	ds_read_b128 v[160:163], v172
	ds_read_b128 v[164:167], v172 offset:1024
	ds_read_b128 v[168:171], v172 offset:2048
	ds_read_b128 v[178:181], v172 offset:3072
	s_add_i32 m0, s44, 0xc000
	ds_read_b128 v[182:185], v177
	ds_read_b128 v[186:189], v177 offset:1024
	ds_read_b128 v[204:207], v177 offset:2048
	ds_read_b128 v[208:211], v177 offset:3072
	ds_read_b128 v[212:215], v177 offset:4096
	ds_read_b128 v[216:219], v177 offset:5120
	ds_read_b128 v[220:223], v177 offset:6144
	ds_read_b128 v[224:227], v177 offset:7168
	global_load_lds_dwordx4 v156, s[26:27]
	s_add_i32 m0, s44, 0xe000
	s_nop 0
	global_load_lds_dwordx4 v158, s[26:27]
	s_waitcnt vmcnt(8)
	s_waitcnt lgkmcnt(0)
	s_barrier
	s_setprio 1
	s_waitcnt lgkmcnt(0)
	v_mfma_i32_16x16x64_i8 v[144:147], v[116:119], v[182:185], 0
	v_mfma_i32_16x16x64_i8 v[144:147], v[124:127], v[186:189], v[144:147]
	v_mfma_i32_16x16x64_i8 v[112:115], v[124:127], v[208:211], 0
	v_mfma_i32_16x16x64_i8 v[112:115], v[116:119], v[204:207], v[112:115]
	v_mfma_i32_16x16x64_i8 v[96:99], v[116:119], v[212:215], 0
	v_mfma_i32_16x16x64_i8 v[96:99], v[124:127], v[216:219], v[96:99]
	v_mfma_i32_16x16x64_i8 v[80:83], v[124:127], v[224:227], 0
	v_mfma_i32_16x16x64_i8 v[80:83], v[116:119], v[220:223], v[80:83]
	v_mfma_i32_16x16x64_i8 v[76:79], v[132:135], v[220:223], 0
	v_mfma_i32_16x16x64_i8 v[76:79], v[136:139], v[224:227], v[76:79]
	v_mfma_i32_16x16x64_i8 v[92:95], v[136:139], v[216:219], 0
	v_mfma_i32_16x16x64_i8 v[92:95], v[132:135], v[212:215], v[92:95]
	v_mfma_i32_16x16x64_i8 v[108:111], v[132:135], v[204:207], 0
	v_mfma_i32_16x16x64_i8 v[108:111], v[136:139], v[208:211], v[108:111]
	v_mfma_i32_16x16x64_i8 v[140:143], v[136:139], v[186:189], 0
	v_mfma_i32_16x16x64_i8 v[140:143], v[132:135], v[182:185], v[140:143]
	v_mfma_i32_16x16x64_i8 v[128:131], v[160:163], v[182:185], 0
	v_mfma_i32_16x16x64_i8 v[128:131], v[164:167], v[186:189], v[128:131]
	v_mfma_i32_16x16x64_i8 v[104:107], v[164:167], v[208:211], 0
	v_mfma_i32_16x16x64_i8 v[104:107], v[160:163], v[204:207], v[104:107]
	v_mfma_i32_16x16x64_i8 v[88:91], v[160:163], v[212:215], 0
	v_mfma_i32_16x16x64_i8 v[88:91], v[164:167], v[216:219], v[88:91]
	v_mfma_i32_16x16x64_i8 v[72:75], v[164:167], v[224:227], 0
	v_mfma_i32_16x16x64_i8 v[72:75], v[160:163], v[220:223], v[72:75]
	v_mfma_i32_16x16x64_i8 v[68:71], v[168:171], v[220:223], 0
	v_mfma_i32_16x16x64_i8 v[68:71], v[178:181], v[224:227], v[68:71]
	v_mfma_i32_16x16x64_i8 v[84:87], v[178:181], v[216:219], 0
	v_mfma_i32_16x16x64_i8 v[84:87], v[168:171], v[212:215], v[84:87]
	v_mfma_i32_16x16x64_i8 v[100:103], v[168:171], v[204:207], 0
	v_mfma_i32_16x16x64_i8 v[100:103], v[178:181], v[208:211], v[100:103]
	v_mfma_i32_16x16x64_i8 v[120:123], v[178:181], v[186:189], 0
	v_mfma_i32_16x16x64_i8 v[120:123], v[168:171], v[182:185], v[120:123]
	s_setprio 0
	s_barrier
	s_add_i32 s50, s50, s43
	v_lshl_add_u64 v[172:173], s[36:37], 0, v[2:3]
	s_mov_b32 m0, s50
	ds_read_b128 v[182:185], v177 offset:16384
	ds_read_b128 v[186:189], v177 offset:17408
	ds_read_b128 v[204:207], v177 offset:18432
	ds_read_b128 v[208:211], v177 offset:19456
	ds_read_b128 v[212:215], v177 offset:20480
	ds_read_b128 v[216:219], v177 offset:21504
	ds_read_b128 v[220:223], v177 offset:22528
	ds_read_b128 v[224:227], v177 offset:23552
	global_load_lds_dwordx4 v[172:173], off
	s_add_i32 m0, s50, 0x2000
	s_add_u32 s50, s36, 0x80000
	v_lshl_add_u64 v[190:191], s[36:37], 0, v[148:149]
	s_addc_u32 s51, s37, 0
	s_add_i32 s56, s56, s43
	global_load_lds_dwordx4 v[190:191], off
	s_mov_b32 m0, s56
	v_lshl_add_u64 v[240:241], s[40:41], 0, v[150:151]
	global_load_lds_dwordx4 v2, s[50:51]
	s_add_i32 m0, s56, 0x2000
	s_nop 0
	global_load_lds_dwordx4 v148, s[50:51]
	v_lshl_add_u64 v[228:229], s[40:41], 0, v[152:153]
	s_waitcnt vmcnt(6)
	s_waitcnt lgkmcnt(0)
	s_barrier
; #define PG8_STAGE(bufoff, gbase, voff) do { _Pragma("unroll") for (int _i = 0; _i < 2; ++_i) \
;         __builtin_amdgcn_global_load_lds((const unsigned*)((const char*)(gbase) + (voff)[_i]), (PG8_LAS unsigned*)(lds + (bufoff) + ldsw + _i * 8192), 16, 0, 0); } while (0)
; #define PG8_LDA(dst, b, h) do { _Pragma("unroll") for (int m = 0; m < 4; ++m) _Pragma("unroll") for (int k = 0; k < 2; ++k) dst[m][k] = *(const PG8_LAS bf16x8*)(lds + PG8_SA(b, h) + aoff + m * 2048 + k * 1024); } while (0)
; #define PG8_LDB(dst, b, h) do { _Pragma("unroll") for (int n = 0; n < 2; ++n) _Pragma("unroll") for (int k = 0; k < 2; ++k) dst[n][k] = *(const PG8_LAS bf16x8*)(lds + PG8_SB(b, h) + boff + n * 2048 + k * 1024); } while (0)
; #define PG8_WAIT_V(n) asm volatile("s_waitcnt vmcnt(" #n ")" ::: "memory")
; #define PG8_WAIT_L(n) asm volatile("s_waitcnt lgkmcnt(" #n ")" ::: "memory")
; #define PG8_BAR __builtin_amdgcn_s_barrier()
; #define PG8_SCHED __builtin_amdgcn_sched_barrier(0)
; template <class Epi, class Sched, bool ALIGN_EPI = false, bool SP2 = false, bool I8 = false>
; __device__ __forceinline__ void gemm_phase(PG8_LAS unsigned char* lds, const Gemm g, const Sched& S, const Epi& E) {
;     ...
;             PG8_WAIT_V(8); PG8_WAIT_L(0); PG8_BAR; PG8_MMA(0, 0, At, B0); PG8_MMA(0, 1, At, B1); PG8_BAR; PG8_SCHED;
;             PG8_LDA(At, 0, 1); PG8_STAGE(PG8_SB(0, 0), b2, voffB); PG8_STAGE(PG8_SB(0, 1), b2 + hstep, voffB); PG8_STAGE(PG8_SA(0, 0), a2, voffA);
;             PG8_WAIT_V(8); PG8_WAIT_L(0); PG8_BAR; PG8_MMA(1, 0, At, B0); PG8_MMA(1, 1, At, B1); PG8_BAR; PG8_SCHED;
;             PG8_LDB(B0, 1, 0); PG8_LDB(B1, 1, 1); PG8_SCHED; PG8_LDA(At, 1, 0); PG8_STAGE(PG8_SA(0, 1), a2 + hstep, voffA);
;             PG8_WAIT_V(8); PG8_WAIT_L(0); PG8_BAR; PG8_MMA(0, 0, At, B0); PG8_MMA(0, 1, At, B1); PG8_BAR; PG8_SCHED;
;             PG8_LDA(At, 1, 1); PG8_STAGE(PG8_SB(1, 0), b3, voffB); PG8_STAGE(PG8_SB(1, 1), b3 + hstep, voffB); PG8_STAGE(PG8_SA(1, 0), a3, voffA);
;             PG8_WAIT_V(8); PG8_WAIT_L(0); PG8_BAR; PG8_MMA(1, 0, At, B0); PG8_MMA(1, 1, At, B1); PG8_BAR; PG8_SCHED;
	s_setprio 1
	s_waitcnt lgkmcnt(0)
	v_mfma_i32_16x16x64_i8 v[64:67], v[116:119], v[182:185], 0
	v_mfma_i32_16x16x64_i8 v[64:67], v[124:127], v[186:189], v[64:67]
	v_mfma_i32_16x16x64_i8 v[48:51], v[124:127], v[208:211], 0
	v_mfma_i32_16x16x64_i8 v[48:51], v[116:119], v[204:207], v[48:51]
	v_mfma_i32_16x16x64_i8 v[32:35], v[116:119], v[212:215], 0
	v_mfma_i32_16x16x64_i8 v[32:35], v[124:127], v[216:219], v[32:35]
	v_mfma_i32_16x16x64_i8 v[16:19], v[124:127], v[224:227], 0
	v_mfma_i32_16x16x64_i8 v[16:19], v[116:119], v[220:223], v[16:19]
	v_mfma_i32_16x16x64_i8 v[12:15], v[132:135], v[220:223], 0
	v_mfma_i32_16x16x64_i8 v[12:15], v[136:139], v[224:227], v[12:15]
	v_mfma_i32_16x16x64_i8 v[28:31], v[136:139], v[216:219], 0
	v_mfma_i32_16x16x64_i8 v[28:31], v[132:135], v[212:215], v[28:31]
	v_mfma_i32_16x16x64_i8 v[44:47], v[132:135], v[204:207], 0
	v_mfma_i32_16x16x64_i8 v[44:47], v[136:139], v[208:211], v[44:47]
	v_mfma_i32_16x16x64_i8 v[60:63], v[136:139], v[186:189], 0
	v_mfma_i32_16x16x64_i8 v[60:63], v[132:135], v[182:185], v[60:63]
	v_mfma_i32_16x16x64_i8 v[56:59], v[160:163], v[182:185], 0
	v_mfma_i32_16x16x64_i8 v[56:59], v[164:167], v[186:189], v[56:59]
	v_mfma_i32_16x16x64_i8 v[40:43], v[164:167], v[208:211], 0
	v_mfma_i32_16x16x64_i8 v[40:43], v[160:163], v[204:207], v[40:43]
	v_mfma_i32_16x16x64_i8 v[24:27], v[160:163], v[212:215], 0
	v_mfma_i32_16x16x64_i8 v[24:27], v[164:167], v[216:219], v[24:27]
	v_mfma_i32_16x16x64_i8 v[8:11], v[164:167], v[224:227], 0
	v_mfma_i32_16x16x64_i8 v[8:11], v[160:163], v[220:223], v[8:11]
	v_mfma_i32_16x16x64_i8 v[4:7], v[168:171], v[220:223], 0
	v_mfma_i32_16x16x64_i8 v[4:7], v[178:181], v[224:227], v[4:7]
	v_mfma_i32_16x16x64_i8 v[20:23], v[178:181], v[216:219], 0
	v_mfma_i32_16x16x64_i8 v[20:23], v[168:171], v[212:215], v[20:23]
	v_mfma_i32_16x16x64_i8 v[36:39], v[168:171], v[204:207], 0
	v_mfma_i32_16x16x64_i8 v[36:39], v[178:181], v[208:211], v[36:39]
	v_mfma_i32_16x16x64_i8 v[52:55], v[178:181], v[186:189], 0
	v_mfma_i32_16x16x64_i8 v[52:55], v[168:171], v[182:185], v[52:55]
	s_setprio 0
	s_barrier
	s_mov_b32 m0, s44
	s_nop 0
	global_load_lds_dwordx4 v[228:229], off
	s_mov_b32 m0, s45
	s_nop 0
	global_load_lds_dwordx4 v[240:241], off
	s_add_i32 s50, 0, 0x18000
	s_add_i32 s51, 0, 0x1c000
	v_add_u32_e32 v136, s50, v175
	v_add_u32_e32 v178, s51, v175
	ds_read_b128 v[116:119], v136
	ds_read_b128 v[124:127], v136 offset:1024
	ds_read_b128 v[132:135], v136 offset:2048
	ds_read_b128 v[136:139], v136 offset:3072
	ds_read_b128 v[160:163], v178
	ds_read_b128 v[164:167], v178 offset:1024
	ds_read_b128 v[168:171], v178 offset:2048
	ds_read_b128 v[178:181], v178 offset:3072
	s_add_u32 s40, s40, 0x80000
	s_addc_u32 s41, s41, 0
	s_mov_b32 m0, s46
	ds_read_b128 v[182:185], v177 offset:32768
	ds_read_b128 v[186:189], v177 offset:33792
	ds_read_b128 v[204:207], v177 offset:34816
	ds_read_b128 v[208:211], v177 offset:35840
	ds_read_b128 v[212:215], v177 offset:36864
	ds_read_b128 v[216:219], v177 offset:37888
	ds_read_b128 v[220:223], v177 offset:38912
	ds_read_b128 v[224:227], v177 offset:39936
	global_load_lds_dwordx4 v152, s[40:41]
	s_mov_b32 m0, s47
	s_nop 0
	global_load_lds_dwordx4 v150, s[40:41]
	s_waitcnt vmcnt(8)
	s_waitcnt lgkmcnt(0)
	s_barrier
	s_setprio 1
	s_waitcnt lgkmcnt(0)
	v_mfma_i32_16x16x64_i8 v[144:147], v[116:119], v[182:185], v[144:147]
	v_mfma_i32_16x16x64_i8 v[144:147], v[124:127], v[186:189], v[144:147]
	v_mfma_i32_16x16x64_i8 v[112:115], v[124:127], v[208:211], v[112:115]
	v_mfma_i32_16x16x64_i8 v[112:115], v[116:119], v[204:207], v[112:115]
	v_mfma_i32_16x16x64_i8 v[96:99], v[116:119], v[212:215], v[96:99]
	v_mfma_i32_16x16x64_i8 v[96:99], v[124:127], v[216:219], v[96:99]
	v_mfma_i32_16x16x64_i8 v[80:83], v[124:127], v[224:227], v[80:83]
	v_mfma_i32_16x16x64_i8 v[80:83], v[116:119], v[220:223], v[80:83]
	v_mfma_i32_16x16x64_i8 v[76:79], v[132:135], v[220:223], v[76:79]
	v_mfma_i32_16x16x64_i8 v[76:79], v[136:139], v[224:227], v[76:79]
	v_mfma_i32_16x16x64_i8 v[92:95], v[136:139], v[216:219], v[92:95]
	v_mfma_i32_16x16x64_i8 v[92:95], v[132:135], v[212:215], v[92:95]
	v_mfma_i32_16x16x64_i8 v[108:111], v[132:135], v[204:207], v[108:111]
	v_mfma_i32_16x16x64_i8 v[108:111], v[136:139], v[208:211], v[108:111]
	v_mfma_i32_16x16x64_i8 v[140:143], v[136:139], v[186:189], v[140:143]
	v_mfma_i32_16x16x64_i8 v[140:143], v[132:135], v[182:185], v[140:143]
	v_mfma_i32_16x16x64_i8 v[128:131], v[160:163], v[182:185], v[128:131]
	v_mfma_i32_16x16x64_i8 v[128:131], v[164:167], v[186:189], v[128:131]
	v_mfma_i32_16x16x64_i8 v[104:107], v[164:167], v[208:211], v[104:107]
	v_mfma_i32_16x16x64_i8 v[104:107], v[160:163], v[204:207], v[104:107]
	v_mfma_i32_16x16x64_i8 v[88:91], v[160:163], v[212:215], v[88:91]
	v_mfma_i32_16x16x64_i8 v[88:91], v[164:167], v[216:219], v[88:91]
	v_mfma_i32_16x16x64_i8 v[72:75], v[164:167], v[224:227], v[72:75]
	v_mfma_i32_16x16x64_i8 v[72:75], v[160:163], v[220:223], v[72:75]
	v_mfma_i32_16x16x64_i8 v[68:71], v[168:171], v[220:223], v[68:71]
	v_mfma_i32_16x16x64_i8 v[68:71], v[178:181], v[224:227], v[68:71]
	v_mfma_i32_16x16x64_i8 v[84:87], v[178:181], v[216:219], v[84:87]
	v_mfma_i32_16x16x64_i8 v[84:87], v[168:171], v[212:215], v[84:87]
	v_mfma_i32_16x16x64_i8 v[100:103], v[168:171], v[204:207], v[100:103]
	v_mfma_i32_16x16x64_i8 v[100:103], v[178:181], v[208:211], v[100:103]
	v_mfma_i32_16x16x64_i8 v[120:123], v[178:181], v[186:189], v[120:123]
	v_mfma_i32_16x16x64_i8 v[120:123], v[168:171], v[182:185], v[120:123]
	s_setprio 0
	s_barrier
	s_add_i32 s40, s50, s43
	v_lshl_add_u64 v[172:173], v[172:173], 0, s[84:85]
	s_mov_b32 m0, s40
	ds_read_b128 v[182:185], v177 offset:49152
	ds_read_b128 v[186:189], v177 offset:50176
	ds_read_b128 v[204:207], v177 offset:51200
	ds_read_b128 v[208:211], v177 offset:52224
	ds_read_b128 v[212:215], v177 offset:53248
	ds_read_b128 v[216:219], v177 offset:54272
	ds_read_b128 v[220:223], v177 offset:55296
	ds_read_b128 v[224:227], v177 offset:56320
	global_load_lds_dwordx4 v[172:173], off
	s_add_i32 m0, s40, 0x2000
	s_add_u32 s36, s36, 0x80080
	v_lshl_add_u64 v[172:173], v[190:191], 0, s[84:85]
	s_addc_u32 s37, s37, 0
	s_add_i32 s40, s51, s43
	global_load_lds_dwordx4 v[172:173], off
	s_mov_b32 m0, s40
	s_nop 0
	global_load_lds_dwordx4 v2, s[36:37]
	s_add_i32 m0, s40, 0x2000
	s_nop 0
	global_load_lds_dwordx4 v148, s[36:37]
	s_cmp_eq_u32 s76, 28
	s_cbranch_scc0 .Ldefer_208_peel
	v_lshl_add_u64 v[172:173], v[228:229], 0, s[84:85]
	s_mov_b32 m0, s52
	s_nop 0
	global_load_lds_dwordx4 v[172:173], off
	v_lshl_add_u64 v[172:173], v[240:241], 0, s[84:85]
	s_mov_b32 m0, s53
	s_nop 0
	global_load_lds_dwordx4 v[172:173], off

; #define PG8_STAGE(bufoff, gbase, voff) do { _Pragma("unroll") for (int _i = 0; _i < 2; ++_i) \
;         __builtin_amdgcn_global_load_lds((const unsigned*)((const char*)(gbase) + (voff)[_i]), (PG8_LAS unsigned*)(lds + (bufoff) + ldsw + _i * 8192), 16, 0, 0); } while (0)
; #define PG8_LDA(dst, b, h) do { _Pragma("unroll") for (int m = 0; m < 4; ++m) _Pragma("unroll") for (int k = 0; k < 2; ++k) dst[m][k] = *(const PG8_LAS bf16x8*)(lds + PG8_SA(b, h) + aoff + m * 2048 + k * 1024); } while (0)
; #define PG8_LDB(dst, b, h) do { _Pragma("unroll") for (int n = 0; n < 2; ++n) _Pragma("unroll") for (int k = 0; k < 2; ++k) dst[n][k] = *(const PG8_LAS bf16x8*)(lds + PG8_SB(b, h) + boff + n * 2048 + k * 1024); } while (0)
; #define PG8_WAIT_V(n) asm volatile("s_waitcnt vmcnt(" #n ")" ::: "memory")
; #define PG8_WAIT_L(n) asm volatile("s_waitcnt lgkmcnt(" #n ")" ::: "memory")
; #define PG8_BAR __builtin_amdgcn_s_barrier()
; #define PG8_SCHED __builtin_amdgcn_sched_barrier(0)
; template <class Epi, class Sched, bool ALIGN_EPI = false, bool SP2 = false, bool I8 = false>
; __device__ __forceinline__ void gemm_phase(PG8_LAS unsigned char* lds, const Gemm g, const Sched& S, const Epi& E) {
;     ...
;             const bool last = (t == nt - 2);
;             const char* a1 = cA + (size_t)(t + 1) * kstep;
;             const char* a2 = last ? nA : cA + (size_t)(t + 2) * kstep; const char* b2 = last ? nB : cB + (size_t)(t + 2) * kstep;
;             const char* a3 = a2 + kstep; const char* b3 = b2 + kstep;
;             if (last && has_next) S.a_ready(nxt);
;             if constexpr (SP2) {
;             PG8_LDB(B0, 0, 0); PG8_LDB(B1, 0, 1); PG8_SCHED; PG8_LDA(At, 0, 0); PG8_STAGE(PG8_SA(1, 1), a1 + hstep, voffA);
;             PG8_WAIT_V(8); PG8_WAIT_L(0); PG8_BAR; PG8_MMA(0, 0, At, B0); PG8_MMA(0, 1, At, B1); PG8_BAR; PG8_SCHED;
;             PG8_LDA(At, 0, 1); PG8_STAGE(PG8_SB(0, 0), b2, voffB); PG8_STAGE(PG8_SB(0, 1), b2 + hstep, voffB); PG8_STAGE(PG8_SA(0, 0), a2, voffA);
;             PG8_WAIT_V(8); PG8_WAIT_L(0); PG8_BAR; PG8_MMA(1, 0, At, B0); PG8_MMA(1, 1, At, B1); PG8_BAR; PG8_SCHED;
.LBB0_208:
	s_add_u32 s36, s26, 0xfff80080
	s_addc_u32 s37, s27, -1
	s_add_i32 s50, 0, 0x10000
	s_cmp_eq_u32 s76, 28
	s_cselect_b32 s41, s19, s37
	s_cselect_b32 s40, s64, s36
	s_cselect_b32 s37, s17, s73
	s_cselect_b32 s36, s65, s72
	s_add_i32 s56, 0, 0x14000
	v_add_u32_e32 v136, s50, v175
	v_add_u32_e32 v172, s56, v175
	ds_read_b128 v[116:119], v136
	ds_read_b128 v[124:127], v136 offset:1024
	ds_read_b128 v[132:135], v136 offset:2048
	ds_read_b128 v[136:139], v136 offset:3072
	ds_read_b128 v[160:163], v172
	ds_read_b128 v[164:167], v172 offset:1024
	ds_read_b128 v[168:171], v172 offset:2048
	ds_read_b128 v[178:181], v172 offset:3072
	v_lshl_add_u64 v[172:173], v[228:229], 0, s[84:85]
	s_mov_b32 m0, s52
	s_nop 0
	global_load_lds_dwordx4 v[172:173], off
	v_lshl_add_u64 v[172:173], v[240:241], 0, s[84:85]
	s_mov_b32 m0, s53
	s_nop 0
	global_load_lds_dwordx4 v[172:173], off
	s_add_i32 m0, s44, 0xc000
	ds_read_b128 v[182:185], v177
	ds_read_b128 v[186:189], v177 offset:1024
	ds_read_b128 v[204:207], v177 offset:2048
	ds_read_b128 v[208:211], v177 offset:3072
	ds_read_b128 v[212:215], v177 offset:4096
	ds_read_b128 v[216:219], v177 offset:5120
	ds_read_b128 v[220:223], v177 offset:6144
	ds_read_b128 v[224:227], v177 offset:7168
	global_load_lds_dwordx4 v156, s[26:27]
	s_add_i32 m0, s44, 0xe000
	s_nop 0
	global_load_lds_dwordx4 v158, s[26:27]
	s_waitcnt vmcnt(8)
	s_waitcnt lgkmcnt(0)
	s_barrier
	s_setprio 1
	s_waitcnt lgkmcnt(0)
	v_mfma_i32_16x16x64_i8 v[144:147], v[116:119], v[182:185], v[144:147]
	v_mfma_i32_16x16x64_i8 v[144:147], v[124:127], v[186:189], v[144:147]
	v_mfma_i32_16x16x64_i8 v[112:115], v[124:127], v[208:211], v[112:115]
	v_mfma_i32_16x16x64_i8 v[112:115], v[116:119], v[204:207], v[112:115]
	v_mfma_i32_16x16x64_i8 v[96:99], v[116:119], v[212:215], v[96:99]
	v_mfma_i32_16x16x64_i8 v[96:99], v[124:127], v[216:219], v[96:99]
	v_mfma_i32_16x16x64_i8 v[80:83], v[124:127], v[224:227], v[80:83]
	v_mfma_i32_16x16x64_i8 v[80:83], v[116:119], v[220:223], v[80:83]
	v_mfma_i32_16x16x64_i8 v[76:79], v[132:135], v[220:223], v[76:79]
	v_mfma_i32_16x16x64_i8 v[76:79], v[136:139], v[224:227], v[76:79]
	v_mfma_i32_16x16x64_i8 v[92:95], v[136:139], v[216:219], v[92:95]
	v_mfma_i32_16x16x64_i8 v[92:95], v[132:135], v[212:215], v[92:95]
	v_mfma_i32_16x16x64_i8 v[108:111], v[132:135], v[204:207], v[108:111]
	v_mfma_i32_16x16x64_i8 v[108:111], v[136:139], v[208:211], v[108:111]
	v_mfma_i32_16x16x64_i8 v[140:143], v[136:139], v[186:189], v[140:143]
	v_mfma_i32_16x16x64_i8 v[140:143], v[132:135], v[182:185], v[140:143]
	v_mfma_i32_16x16x64_i8 v[128:131], v[160:163], v[182:185], v[128:131]
	v_mfma_i32_16x16x64_i8 v[128:131], v[164:167], v[186:189], v[128:131]
	v_mfma_i32_16x16x64_i8 v[104:107], v[164:167], v[208:211], v[104:107]
	v_mfma_i32_16x16x64_i8 v[104:107], v[160:163], v[204:207], v[104:107]
	v_mfma_i32_16x16x64_i8 v[88:91], v[160:163], v[212:215], v[88:91]
	v_mfma_i32_16x16x64_i8 v[88:91], v[164:167], v[216:219], v[88:91]
	v_mfma_i32_16x16x64_i8 v[72:75], v[164:167], v[224:227], v[72:75]
	v_mfma_i32_16x16x64_i8 v[72:75], v[160:163], v[220:223], v[72:75]
	v_mfma_i32_16x16x64_i8 v[68:71], v[168:171], v[220:223], v[68:71]
	v_mfma_i32_16x16x64_i8 v[68:71], v[178:181], v[224:227], v[68:71]
	v_mfma_i32_16x16x64_i8 v[84:87], v[178:181], v[216:219], v[84:87]
	v_mfma_i32_16x16x64_i8 v[84:87], v[168:171], v[212:215], v[84:87]
	v_mfma_i32_16x16x64_i8 v[100:103], v[168:171], v[204:207], v[100:103]
	v_mfma_i32_16x16x64_i8 v[100:103], v[178:181], v[208:211], v[100:103]
	v_mfma_i32_16x16x64_i8 v[120:123], v[178:181], v[186:189], v[120:123]
	v_mfma_i32_16x16x64_i8 v[120:123], v[168:171], v[182:185], v[120:123]
	s_setprio 0
	s_barrier
	s_add_i32 s50, s50, s43
	v_lshl_add_u64 v[172:173], s[36:37], 0, v[2:3]
	s_mov_b32 m0, s50
	ds_read_b128 v[182:185], v177 offset:16384
	ds_read_b128 v[186:189], v177 offset:17408
	ds_read_b128 v[204:207], v177 offset:18432
	ds_read_b128 v[208:211], v177 offset:19456
	ds_read_b128 v[212:215], v177 offset:20480
	ds_read_b128 v[216:219], v177 offset:21504
	ds_read_b128 v[220:223], v177 offset:22528
	ds_read_b128 v[224:227], v177 offset:23552
	global_load_lds_dwordx4 v[172:173], off
	s_add_i32 m0, s50, 0x2000
	s_add_u32 s50, s36, 0x80000
	v_lshl_add_u64 v[190:191], s[36:37], 0, v[148:149]
	s_addc_u32 s51, s37, 0
	s_add_i32 s56, s56, s43
	global_load_lds_dwordx4 v[190:191], off
	s_mov_b32 m0, s56
	v_lshl_add_u64 v[240:241], s[40:41], 0, v[150:151]
	global_load_lds_dwordx4 v2, s[50:51]
	s_add_i32 m0, s56, 0x2000
	s_nop 0
	global_load_lds_dwordx4 v148, s[50:51]
	v_lshl_add_u64 v[228:229], s[40:41], 0, v[152:153]
	s_waitcnt vmcnt(6)
	s_waitcnt lgkmcnt(0)
	s_barrier
; #define PG8_STAGE(bufoff, gbase, voff) do { _Pragma("unroll") for (int _i = 0; _i < 2; ++_i) \
;         __builtin_amdgcn_global_load_lds((const unsigned*)((const char*)(gbase) + (voff)[_i]), (PG8_LAS unsigned*)(lds + (bufoff) + ldsw + _i * 8192), 16, 0, 0); } while (0)
; #define PG8_LDA(dst, b, h) do { _Pragma("unroll") for (int m = 0; m < 4; ++m) _Pragma("unroll") for (int k = 0; k < 2; ++k) dst[m][k] = *(const PG8_LAS bf16x8*)(lds + PG8_SA(b, h) + aoff + m * 2048 + k * 1024); } while (0)
; #define PG8_LDB(dst, b, h) do { _Pragma("unroll") for (int n = 0; n < 2; ++n) _Pragma("unroll") for (int k = 0; k < 2; ++k) dst[n][k] = *(const PG8_LAS bf16x8*)(lds + PG8_SB(b, h) + boff + n * 2048 + k * 1024); } while (0)
; #define PG8_WAIT_V(n) asm volatile("s_waitcnt vmcnt(" #n ")" ::: "memory")
; #define PG8_WAIT_L(n) asm volatile("s_waitcnt lgkmcnt(" #n ")" ::: "memory")
; #define PG8_BAR __builtin_amdgcn_s_barrier()
; #define PG8_SCHED __builtin_amdgcn_sched_barrier(0)
; template <class Epi, class Sched, bool ALIGN_EPI = false, bool SP2 = false, bool I8 = false>
; __device__ __forceinline__ void gemm_phase(PG8_LAS unsigned char* lds, const Gemm g, const Sched& S, const Epi& E) {
;     ...
;             PG8_WAIT_V(8); PG8_WAIT_L(0); PG8_BAR; PG8_MMA(1, 0, At, B0); PG8_MMA(1, 1, At, B1); PG8_BAR; PG8_SCHED;
;             PG8_LDB(B0, 1, 0); PG8_LDB(B1, 1, 1); PG8_SCHED; PG8_LDA(At, 1, 0); PG8_STAGE(PG8_SA(0, 1), a2 + hstep, voffA);
;             PG8_WAIT_V(8); PG8_WAIT_L(0); PG8_BAR; PG8_MMA(0, 0, At, B0); PG8_MMA(0, 1, At, B1); PG8_BAR; PG8_SCHED;
;             PG8_LDA(At, 1, 1); PG8_STAGE(PG8_SB(1, 0), b3, voffB); PG8_STAGE(PG8_SB(1, 1), b3 + hstep, voffB); PG8_STAGE(PG8_SA(1, 0), a3, voffA);
;             PG8_WAIT_V(8); PG8_WAIT_L(0); PG8_BAR; PG8_MMA(1, 0, At, B0); PG8_MMA(1, 1, At, B1); PG8_BAR; PG8_SCHED;
	s_setprio 1
	s_waitcnt lgkmcnt(0)
	v_mfma_i32_16x16x64_i8 v[64:67], v[116:119], v[182:185], v[64:67]
	v_mfma_i32_16x16x64_i8 v[64:67], v[124:127], v[186:189], v[64:67]
	v_mfma_i32_16x16x64_i8 v[48:51], v[124:127], v[208:211], v[48:51]
	v_mfma_i32_16x16x64_i8 v[48:51], v[116:119], v[204:207], v[48:51]
	v_mfma_i32_16x16x64_i8 v[32:35], v[116:119], v[212:215], v[32:35]
	v_mfma_i32_16x16x64_i8 v[32:35], v[124:127], v[216:219], v[32:35]
	v_mfma_i32_16x16x64_i8 v[16:19], v[124:127], v[224:227], v[16:19]
	v_mfma_i32_16x16x64_i8 v[16:19], v[116:119], v[220:223], v[16:19]
	v_mfma_i32_16x16x64_i8 v[12:15], v[132:135], v[220:223], v[12:15]
	v_mfma_i32_16x16x64_i8 v[12:15], v[136:139], v[224:227], v[12:15]
	v_mfma_i32_16x16x64_i8 v[28:31], v[136:139], v[216:219], v[28:31]
	v_mfma_i32_16x16x64_i8 v[28:31], v[132:135], v[212:215], v[28:31]
	v_mfma_i32_16x16x64_i8 v[44:47], v[132:135], v[204:207], v[44:47]
	v_mfma_i32_16x16x64_i8 v[44:47], v[136:139], v[208:211], v[44:47]
	v_mfma_i32_16x16x64_i8 v[60:63], v[136:139], v[186:189], v[60:63]
	v_mfma_i32_16x16x64_i8 v[60:63], v[132:135], v[182:185], v[60:63]
	v_mfma_i32_16x16x64_i8 v[56:59], v[160:163], v[182:185], v[56:59]
	v_mfma_i32_16x16x64_i8 v[56:59], v[164:167], v[186:189], v[56:59]
	v_mfma_i32_16x16x64_i8 v[40:43], v[164:167], v[208:211], v[40:43]
	v_mfma_i32_16x16x64_i8 v[40:43], v[160:163], v[204:207], v[40:43]
	v_mfma_i32_16x16x64_i8 v[24:27], v[160:163], v[212:215], v[24:27]
	v_mfma_i32_16x16x64_i8 v[24:27], v[164:167], v[216:219], v[24:27]
	v_mfma_i32_16x16x64_i8 v[8:11], v[164:167], v[224:227], v[8:11]
	v_mfma_i32_16x16x64_i8 v[8:11], v[160:163], v[220:223], v[8:11]
	v_mfma_i32_16x16x64_i8 v[4:7], v[168:171], v[220:223], v[4:7]
	v_mfma_i32_16x16x64_i8 v[4:7], v[178:181], v[224:227], v[4:7]
	v_mfma_i32_16x16x64_i8 v[20:23], v[178:181], v[216:219], v[20:23]
	v_mfma_i32_16x16x64_i8 v[20:23], v[168:171], v[212:215], v[20:23]
	v_mfma_i32_16x16x64_i8 v[36:39], v[168:171], v[204:207], v[36:39]
	v_mfma_i32_16x16x64_i8 v[36:39], v[178:181], v[208:211], v[36:39]
	v_mfma_i32_16x16x64_i8 v[52:55], v[178:181], v[186:189], v[52:55]
	v_mfma_i32_16x16x64_i8 v[52:55], v[168:171], v[182:185], v[52:55]
	s_setprio 0
	s_barrier
	s_mov_b32 m0, s44
	s_nop 0
	global_load_lds_dwordx4 v[228:229], off
	s_mov_b32 m0, s45
	s_nop 0
	global_load_lds_dwordx4 v[240:241], off
	s_add_i32 s50, 0, 0x18000
	s_add_i32 s51, 0, 0x1c000
	v_add_u32_e32 v136, s50, v175
	v_add_u32_e32 v178, s51, v175
	ds_read_b128 v[116:119], v136
	ds_read_b128 v[124:127], v136 offset:1024
	ds_read_b128 v[132:135], v136 offset:2048
	ds_read_b128 v[136:139], v136 offset:3072
	ds_read_b128 v[160:163], v178
	ds_read_b128 v[164:167], v178 offset:1024
	ds_read_b128 v[168:171], v178 offset:2048
	ds_read_b128 v[178:181], v178 offset:3072
	s_add_u32 s40, s40, 0x80000
	s_addc_u32 s41, s41, 0
	s_mov_b32 m0, s46
	ds_read_b128 v[182:185], v177 offset:32768
	ds_read_b128 v[186:189], v177 offset:33792
	ds_read_b128 v[204:207], v177 offset:34816
	ds_read_b128 v[208:211], v177 offset:35840
	ds_read_b128 v[212:215], v177 offset:36864
	ds_read_b128 v[216:219], v177 offset:37888
	ds_read_b128 v[220:223], v177 offset:38912
	ds_read_b128 v[224:227], v177 offset:39936
	global_load_lds_dwordx4 v152, s[40:41]
	s_mov_b32 m0, s47
	s_nop 0
	global_load_lds_dwordx4 v150, s[40:41]
	s_waitcnt vmcnt(8)
	s_waitcnt lgkmcnt(0)
	s_barrier
	s_setprio 1
	s_waitcnt lgkmcnt(0)
	v_mfma_i32_16x16x64_i8 v[144:147], v[116:119], v[182:185], v[144:147]
	v_mfma_i32_16x16x64_i8 v[144:147], v[124:127], v[186:189], v[144:147]
	v_mfma_i32_16x16x64_i8 v[112:115], v[124:127], v[208:211], v[112:115]
	v_mfma_i32_16x16x64_i8 v[112:115], v[116:119], v[204:207], v[112:115]
	v_mfma_i32_16x16x64_i8 v[96:99], v[116:119], v[212:215], v[96:99]
	v_mfma_i32_16x16x64_i8 v[96:99], v[124:127], v[216:219], v[96:99]
	v_mfma_i32_16x16x64_i8 v[80:83], v[124:127], v[224:227], v[80:83]
	v_mfma_i32_16x16x64_i8 v[80:83], v[116:119], v[220:223], v[80:83]
	v_mfma_i32_16x16x64_i8 v[76:79], v[132:135], v[220:223], v[76:79]
	v_mfma_i32_16x16x64_i8 v[76:79], v[136:139], v[224:227], v[76:79]
	v_mfma_i32_16x16x64_i8 v[92:95], v[136:139], v[216:219], v[92:95]
	v_mfma_i32_16x16x64_i8 v[92:95], v[132:135], v[212:215], v[92:95]
	v_mfma_i32_16x16x64_i8 v[108:111], v[132:135], v[204:207], v[108:111]
	v_mfma_i32_16x16x64_i8 v[108:111], v[136:139], v[208:211], v[108:111]
	v_mfma_i32_16x16x64_i8 v[140:143], v[136:139], v[186:189], v[140:143]
	v_mfma_i32_16x16x64_i8 v[140:143], v[132:135], v[182:185], v[140:143]
	v_mfma_i32_16x16x64_i8 v[128:131], v[160:163], v[182:185], v[128:131]
	v_mfma_i32_16x16x64_i8 v[128:131], v[164:167], v[186:189], v[128:131]
	v_mfma_i32_16x16x64_i8 v[104:107], v[164:167], v[208:211], v[104:107]
	v_mfma_i32_16x16x64_i8 v[104:107], v[160:163], v[204:207], v[104:107]
	v_mfma_i32_16x16x64_i8 v[88:91], v[160:163], v[212:215], v[88:91]
	v_mfma_i32_16x16x64_i8 v[88:91], v[164:167], v[216:219], v[88:91]
	v_mfma_i32_16x16x64_i8 v[72:75], v[164:167], v[224:227], v[72:75]
	v_mfma_i32_16x16x64_i8 v[72:75], v[160:163], v[220:223], v[72:75]
	v_mfma_i32_16x16x64_i8 v[68:71], v[168:171], v[220:223], v[68:71]
	v_mfma_i32_16x16x64_i8 v[68:71], v[178:181], v[224:227], v[68:71]
	v_mfma_i32_16x16x64_i8 v[84:87], v[178:181], v[216:219], v[84:87]
	v_mfma_i32_16x16x64_i8 v[84:87], v[168:171], v[212:215], v[84:87]
	v_mfma_i32_16x16x64_i8 v[100:103], v[168:171], v[204:207], v[100:103]
	v_mfma_i32_16x16x64_i8 v[100:103], v[178:181], v[208:211], v[100:103]
	v_mfma_i32_16x16x64_i8 v[120:123], v[178:181], v[186:189], v[120:123]
	v_mfma_i32_16x16x64_i8 v[120:123], v[168:171], v[182:185], v[120:123]
	s_setprio 0
	s_barrier
	s_add_i32 s40, s50, s43
	v_lshl_add_u64 v[172:173], v[172:173], 0, s[84:85]
	s_mov_b32 m0, s40
	ds_read_b128 v[182:185], v177 offset:49152
	ds_read_b128 v[186:189], v177 offset:50176
	ds_read_b128 v[204:207], v177 offset:51200
	ds_read_b128 v[208:211], v177 offset:52224
	ds_read_b128 v[212:215], v177 offset:53248
	ds_read_b128 v[216:219], v177 offset:54272
	ds_read_b128 v[220:223], v177 offset:55296
	ds_read_b128 v[224:227], v177 offset:56320
	global_load_lds_dwordx4 v[172:173], off
	s_add_i32 m0, s40, 0x2000
	s_add_u32 s36, s36, 0x80080
	v_lshl_add_u64 v[172:173], v[190:191], 0, s[84:85]
	s_addc_u32 s37, s37, 0
	s_add_i32 s40, s51, s43
	global_load_lds_dwordx4 v[172:173], off
	s_mov_b32 m0, s40
	s_nop 0
	global_load_lds_dwordx4 v2, s[36:37]
	s_add_i32 m0, s40, 0x2000
	s_nop 0
	global_load_lds_dwordx4 v148, s[36:37]
	s_cmp_eq_u32 s76, 28
	s_cbranch_scc0 .Ldefer_208_body
	v_lshl_add_u64 v[172:173], v[228:229], 0, s[84:85]
	s_mov_b32 m0, s52
	s_nop 0
	global_load_lds_dwordx4 v[172:173], off
	v_lshl_add_u64 v[172:173], v[240:241], 0, s[84:85]
	s_mov_b32 m0, s53
	s_nop 0
	global_load_lds_dwordx4 v[172:173], off

; #define PG8_STAGE(bufoff, gbase, voff) do { _Pragma("unroll") for (int _i = 0; _i < 2; ++_i) \
;         __builtin_amdgcn_global_load_lds((const unsigned*)((const char*)(gbase) + (voff)[_i]), (PG8_LAS unsigned*)(lds + (bufoff) + ldsw + _i * 8192), 16, 0, 0); } while (0)
; #define PG8_LDA(dst, b, h) do { _Pragma("unroll") for (int m = 0; m < 4; ++m) _Pragma("unroll") for (int k = 0; k < 2; ++k) dst[m][k] = *(const PG8_LAS bf16x8*)(lds + PG8_SA(b, h) + aoff + m * 2048 + k * 1024); } while (0)
; #define PG8_LDB(dst, b, h) do { _Pragma("unroll") for (int n = 0; n < 2; ++n) _Pragma("unroll") for (int k = 0; k < 2; ++k) dst[n][k] = *(const PG8_LAS bf16x8*)(lds + PG8_SB(b, h) + boff + n * 2048 + k * 1024); } while (0)
; #define PG8_WAIT_V(n) asm volatile("s_waitcnt vmcnt(" #n ")" ::: "memory")
; #define PG8_WAIT_L(n) asm volatile("s_waitcnt lgkmcnt(" #n ")" ::: "memory")
; #define PG8_BAR __builtin_amdgcn_s_barrier()
; #define PG8_SCHED __builtin_amdgcn_sched_barrier(0)
; template <class Epi, class Sched, bool ALIGN_EPI = false, bool SP2 = false, bool I8 = false>
; __device__ __forceinline__ void gemm_phase(PG8_LAS unsigned char* lds, const Gemm g, const Sched& S, const Epi& E) {
;     ...
;         const bool has_next = S.next(ui + 1, nxt);
;         const char* nA = has_next ? (const char*)g.A + (size_t)nxt.pm * tstep : cA; const char* nB = has_next ? (const char*)g.Bt + (size_t)nxt.pn * tstep : cB;
;         for (int t = 0; t < nt; t += 2) {
;             const bool last = (t == nt - 2);
;             const char* a1 = cA + (size_t)(t + 1) * kstep;
;             const char* a2 = last ? nA : cA + (size_t)(t + 2) * kstep; const char* b2 = last ? nB : cB + (size_t)(t + 2) * kstep;
;             const char* a3 = a2 + kstep; const char* b3 = b2 + kstep;
;             if (last && has_next) S.a_ready(nxt);
;             if constexpr (SP2) {
;             PG8_LDB(B0, 0, 0); PG8_LDB(B1, 0, 1); PG8_SCHED; PG8_LDA(At, 0, 0); PG8_STAGE(PG8_SA(1, 1), a1 + hstep, voffA);
;             PG8_WAIT_V(8); PG8_WAIT_L(0); PG8_BAR; PG8_MMA(0, 0, At, B0); PG8_MMA(0, 1, At, B1); PG8_BAR; PG8_SCHED;
;             PG8_LDA(At, 0, 1); PG8_STAGE(PG8_SB(0, 0), b2, voffB); PG8_STAGE(PG8_SB(0, 1), b2 + hstep, voffB); PG8_STAGE(PG8_SA(0, 0), a2, voffA);
;             PG8_WAIT_V(8); PG8_WAIT_L(0); PG8_BAR; PG8_MMA(1, 0, At, B0); PG8_MMA(1, 1, At, B1); PG8_BAR; PG8_SCHED;
.LBB0_229:
	s_ashr_i32 s37, s36, 31
	s_lshl_b64 s[34:35], s[36:37], 21
	s_add_u32 s40, s42, s34
	s_addc_u32 s41, s43, s35
	s_and_b64 s[34:35], s[8:9], exec
	s_cselect_b32 s11, s41, s13
	s_cselect_b32 s34, s40, s12
	s_ashr_i32 s27, s26, 31
	s_lshl_b64 s[50:51], s[26:27], 21
	s_add_u32 s54, s44, s50
	s_addc_u32 s55, s45, s51
	s_and_b64 s[50:51], s[8:9], exec
	s_cselect_b32 s27, s55, s73
	s_cselect_b32 s35, s54, s72
	s_add_u32 s12, s12, 0x100080
	s_addc_u32 s13, s13, 0
	s_add_u32 s37, s72, 0x100
	s_addc_u32 s61, s73, 0
	s_mov_b32 s97, -2
	s_add_u32 s50, s12, 0xfff00080
	s_addc_u32 s51, s13, -1
	s_add_i32 s56, 0, 0x10000
	s_cmp_eq_u32 s97, 60
	s_cselect_b32 s77, s11, s51
	s_cselect_b32 s76, s34, s50
	s_cselect_b32 s73, s27, s61
	s_cselect_b32 s72, s35, s37
	s_add_i32 s57, 0, 0x14000
	v_add_u32_e32 v156, s56, v171
	v_add_u32_e32 v168, s57, v171
	s_waitcnt vmcnt(0)
	ds_read_b128 v[112:115], v156
	ds_read_b128 v[120:123], v156 offset:1024
	ds_read_b128 v[152:155], v156 offset:2048
	ds_read_b128 v[156:159], v156 offset:3072
	ds_read_b128 v[160:163], v168
	ds_read_b128 v[164:167], v168 offset:1024
	s_waitcnt lgkmcnt(0)
	ds_read_b128 v[176:179], v168 offset:2048
	ds_read_b128 v[180:183], v168 offset:3072
	s_add_i32 m0, s47, 0xc000
	ds_read_b128 v[184:187], v173
	ds_read_b128 v[188:191], v173 offset:1024
	ds_read_b128 v[204:207], v173 offset:2048
	ds_read_b128 v[208:211], v173 offset:3072
	ds_read_b128 v[212:215], v173 offset:4096
	ds_read_b128 v[216:219], v173 offset:5120
	ds_read_b128 v[220:223], v173 offset:6144
	ds_read_b128 v[224:227], v173 offset:7168
	global_load_lds_dwordx4 v148, s[12:13]
	s_add_i32 m0, s47, 0xe000
	s_nop 0
	global_load_lds_dwordx4 v150, s[12:13]
	s_waitcnt vmcnt(8)
	s_waitcnt lgkmcnt(0)
	s_barrier
	s_setprio 1
	s_waitcnt lgkmcnt(0)
	v_mfma_f32_16x16x32_bf16 v[136:139], v[112:115], v[184:187], 0
	v_mfma_f32_16x16x32_bf16 v[136:139], v[120:123], v[188:191], v[136:139]
	v_mfma_f32_16x16x32_bf16 v[116:119], v[120:123], v[208:211], 0
	v_mfma_f32_16x16x32_bf16 v[116:119], v[112:115], v[204:207], v[116:119]
	v_mfma_f32_16x16x32_bf16 v[96:99], v[112:115], v[212:215], 0
	v_mfma_f32_16x16x32_bf16 v[96:99], v[120:123], v[216:219], v[96:99]
	v_mfma_f32_16x16x32_bf16 v[80:83], v[120:123], v[224:227], 0
	v_mfma_f32_16x16x32_bf16 v[80:83], v[112:115], v[220:223], v[80:83]
	v_mfma_f32_16x16x32_bf16 v[76:79], v[152:155], v[220:223], 0
	v_mfma_f32_16x16x32_bf16 v[76:79], v[156:159], v[224:227], v[76:79]
	v_mfma_f32_16x16x32_bf16 v[92:95], v[156:159], v[216:219], 0
	v_mfma_f32_16x16x32_bf16 v[92:95], v[152:155], v[212:215], v[92:95]
	v_mfma_f32_16x16x32_bf16 v[108:111], v[152:155], v[204:207], 0
	v_mfma_f32_16x16x32_bf16 v[108:111], v[156:159], v[208:211], v[108:111]
	v_mfma_f32_16x16x32_bf16 v[132:135], v[156:159], v[188:191], 0
	v_mfma_f32_16x16x32_bf16 v[132:135], v[152:155], v[184:187], v[132:135]
	v_mfma_f32_16x16x32_bf16 v[128:131], v[160:163], v[184:187], 0
	v_mfma_f32_16x16x32_bf16 v[128:131], v[164:167], v[188:191], v[128:131]
	v_mfma_f32_16x16x32_bf16 v[104:107], v[164:167], v[208:211], 0
	v_mfma_f32_16x16x32_bf16 v[104:107], v[160:163], v[204:207], v[104:107]
	v_mfma_f32_16x16x32_bf16 v[88:91], v[160:163], v[212:215], 0
	v_mfma_f32_16x16x32_bf16 v[88:91], v[164:167], v[216:219], v[88:91]
	v_mfma_f32_16x16x32_bf16 v[72:75], v[164:167], v[224:227], 0
	v_mfma_f32_16x16x32_bf16 v[72:75], v[160:163], v[220:223], v[72:75]
	v_mfma_f32_16x16x32_bf16 v[68:71], v[176:179], v[220:223], 0
	v_mfma_f32_16x16x32_bf16 v[68:71], v[180:183], v[224:227], v[68:71]
	v_mfma_f32_16x16x32_bf16 v[84:87], v[180:183], v[216:219], 0
	v_mfma_f32_16x16x32_bf16 v[84:87], v[176:179], v[212:215], v[84:87]
	v_mfma_f32_16x16x32_bf16 v[100:103], v[176:179], v[204:207], 0
	v_mfma_f32_16x16x32_bf16 v[100:103], v[180:183], v[208:211], v[100:103]
	v_mfma_f32_16x16x32_bf16 v[124:127], v[180:183], v[188:191], 0
	v_mfma_f32_16x16x32_bf16 v[124:127], v[176:179], v[184:187], v[124:127]
	s_setprio 0
	s_barrier
	s_add_i32 s50, s56, s46
	v_lshl_add_u64 v[168:169], s[72:73], 0, v[2:3]
	s_mov_b32 m0, s50
	ds_read_b128 v[184:187], v173 offset:16384
	ds_read_b128 v[188:191], v173 offset:17408
	ds_read_b128 v[204:207], v173 offset:18432
	ds_read_b128 v[208:211], v173 offset:19456
	ds_read_b128 v[212:215], v173 offset:20480
	ds_read_b128 v[216:219], v173 offset:21504
	ds_read_b128 v[220:223], v173 offset:22528
	ds_read_b128 v[224:227], v173 offset:23552
	global_load_lds_dwordx4 v[168:169], off
	s_add_i32 m0, s50, 0x2000
	s_add_u32 s50, s72, 0x100000
	v_lshl_add_u64 v[228:229], s[72:73], 0, v[144:145]
	s_addc_u32 s51, s73, 0
	s_add_i32 s56, s57, s46
	global_load_lds_dwordx4 v[228:229], off
	s_mov_b32 m0, s56
	v_lshl_add_u64 v[242:243], s[76:77], 0, v[142:143]
	global_load_lds_dwordx4 v2, s[50:51]
	s_add_i32 m0, s56, 0x2000
	s_nop 0
	global_load_lds_dwordx4 v144, s[50:51]
	v_lshl_add_u64 v[240:241], s[76:77], 0, v[140:141]
	s_waitcnt vmcnt(6)
	s_waitcnt lgkmcnt(0)
	s_barrier
; #define PG8_STAGE(bufoff, gbase, voff) do { _Pragma("unroll") for (int _i = 0; _i < 2; ++_i) \
;         __builtin_amdgcn_global_load_lds((const unsigned*)((const char*)(gbase) + (voff)[_i]), (PG8_LAS unsigned*)(lds + (bufoff) + ldsw + _i * 8192), 16, 0, 0); } while (0)
; #define PG8_LDA(dst, b, h) do { _Pragma("unroll") for (int m = 0; m < 4; ++m) _Pragma("unroll") for (int k = 0; k < 2; ++k) dst[m][k] = *(const PG8_LAS bf16x8*)(lds + PG8_SA(b, h) + aoff + m * 2048 + k * 1024); } while (0)
; #define PG8_LDB(dst, b, h) do { _Pragma("unroll") for (int n = 0; n < 2; ++n) _Pragma("unroll") for (int k = 0; k < 2; ++k) dst[n][k] = *(const PG8_LAS bf16x8*)(lds + PG8_SB(b, h) + boff + n * 2048 + k * 1024); } while (0)
; #define PG8_WAIT_V(n) asm volatile("s_waitcnt vmcnt(" #n ")" ::: "memory")
; #define PG8_WAIT_L(n) asm volatile("s_waitcnt lgkmcnt(" #n ")" ::: "memory")
; #define PG8_BAR __builtin_amdgcn_s_barrier()
; #define PG8_SCHED __builtin_amdgcn_sched_barrier(0)
; template <class Epi, class Sched, bool ALIGN_EPI = false, bool SP2 = false, bool I8 = false>
; __device__ __forceinline__ void gemm_phase(PG8_LAS unsigned char* lds, const Gemm g, const Sched& S, const Epi& E) {
;     ...
;             PG8_WAIT_V(8); PG8_WAIT_L(0); PG8_BAR; PG8_MMA(1, 0, At, B0); PG8_MMA(1, 1, At, B1); PG8_BAR; PG8_SCHED;
;             PG8_LDB(B0, 1, 0); PG8_LDB(B1, 1, 1); PG8_SCHED; PG8_LDA(At, 1, 0); PG8_STAGE(PG8_SA(0, 1), a2 + hstep, voffA);
;             PG8_WAIT_V(8); PG8_WAIT_L(0); PG8_BAR; PG8_MMA(0, 0, At, B0); PG8_MMA(0, 1, At, B1); PG8_BAR; PG8_SCHED;
;             PG8_LDA(At, 1, 1); PG8_STAGE(PG8_SB(1, 0), b3, voffB); PG8_STAGE(PG8_SB(1, 1), b3 + hstep, voffB); PG8_STAGE(PG8_SA(1, 0), a3, voffA);
;             PG8_WAIT_V(8); PG8_WAIT_L(0); PG8_BAR; PG8_MMA(1, 0, At, B0); PG8_MMA(1, 1, At, B1); PG8_BAR; PG8_SCHED;
	s_setprio 1
	s_waitcnt lgkmcnt(0)
	v_mfma_f32_16x16x32_bf16 v[64:67], v[112:115], v[184:187], 0
	v_mfma_f32_16x16x32_bf16 v[64:67], v[120:123], v[188:191], v[64:67]
	v_mfma_f32_16x16x32_bf16 v[48:51], v[120:123], v[208:211], 0
	v_mfma_f32_16x16x32_bf16 v[48:51], v[112:115], v[204:207], v[48:51]
	v_mfma_f32_16x16x32_bf16 v[32:35], v[112:115], v[212:215], 0
	v_mfma_f32_16x16x32_bf16 v[32:35], v[120:123], v[216:219], v[32:35]
	v_mfma_f32_16x16x32_bf16 v[16:19], v[120:123], v[224:227], 0
	v_mfma_f32_16x16x32_bf16 v[16:19], v[112:115], v[220:223], v[16:19]
	v_mfma_f32_16x16x32_bf16 v[12:15], v[152:155], v[220:223], 0
	v_mfma_f32_16x16x32_bf16 v[12:15], v[156:159], v[224:227], v[12:15]
	v_mfma_f32_16x16x32_bf16 v[28:31], v[156:159], v[216:219], 0
	v_mfma_f32_16x16x32_bf16 v[28:31], v[152:155], v[212:215], v[28:31]
	v_mfma_f32_16x16x32_bf16 v[44:47], v[152:155], v[204:207], 0
	v_mfma_f32_16x16x32_bf16 v[44:47], v[156:159], v[208:211], v[44:47]
	v_mfma_f32_16x16x32_bf16 v[60:63], v[156:159], v[188:191], 0
	v_mfma_f32_16x16x32_bf16 v[60:63], v[152:155], v[184:187], v[60:63]
	v_mfma_f32_16x16x32_bf16 v[56:59], v[160:163], v[184:187], 0
	v_mfma_f32_16x16x32_bf16 v[56:59], v[164:167], v[188:191], v[56:59]
	v_mfma_f32_16x16x32_bf16 v[40:43], v[164:167], v[208:211], 0
	v_mfma_f32_16x16x32_bf16 v[40:43], v[160:163], v[204:207], v[40:43]
	v_mfma_f32_16x16x32_bf16 v[24:27], v[160:163], v[212:215], 0
	v_mfma_f32_16x16x32_bf16 v[24:27], v[164:167], v[216:219], v[24:27]
	v_mfma_f32_16x16x32_bf16 v[8:11], v[164:167], v[224:227], 0
	v_mfma_f32_16x16x32_bf16 v[8:11], v[160:163], v[220:223], v[8:11]
	v_mfma_f32_16x16x32_bf16 v[4:7], v[176:179], v[220:223], 0
	v_mfma_f32_16x16x32_bf16 v[4:7], v[180:183], v[224:227], v[4:7]
	v_mfma_f32_16x16x32_bf16 v[20:23], v[180:183], v[216:219], 0
	v_mfma_f32_16x16x32_bf16 v[20:23], v[176:179], v[212:215], v[20:23]
	v_mfma_f32_16x16x32_bf16 v[36:39], v[176:179], v[204:207], 0
	v_mfma_f32_16x16x32_bf16 v[36:39], v[180:183], v[208:211], v[36:39]
	v_mfma_f32_16x16x32_bf16 v[52:55], v[180:183], v[188:191], 0
	v_mfma_f32_16x16x32_bf16 v[52:55], v[176:179], v[184:187], v[52:55]
	s_setprio 0
	s_barrier
	s_mov_b32 m0, s47
	s_nop 0
	global_load_lds_dwordx4 v[240:241], off
	s_mov_b32 m0, s52
	s_nop 0
	global_load_lds_dwordx4 v[242:243], off
	s_add_i32 s56, 0, 0x18000
	s_add_i32 s57, 0, 0x1c000
	v_add_u32_e32 v156, s56, v171
	v_add_u32_e32 v175, s57, v171
	ds_read_b128 v[112:115], v156
	ds_read_b128 v[120:123], v156 offset:1024
	ds_read_b128 v[152:155], v156 offset:2048
	ds_read_b128 v[156:159], v156 offset:3072
	ds_read_b128 v[160:163], v175
	ds_read_b128 v[164:167], v175 offset:1024
	ds_read_b128 v[176:179], v175 offset:2048
	ds_read_b128 v[180:183], v175 offset:3072
	s_add_u32 s50, s76, 0x100000
	s_addc_u32 s51, s77, 0
	s_mov_b32 m0, s53
	ds_read_b128 v[184:187], v173 offset:32768
	ds_read_b128 v[188:191], v173 offset:33792
	ds_read_b128 v[204:207], v173 offset:34816
	ds_read_b128 v[208:211], v173 offset:35840
	ds_read_b128 v[212:215], v173 offset:36864
	ds_read_b128 v[216:219], v173 offset:37888
	ds_read_b128 v[220:223], v173 offset:38912
	ds_read_b128 v[224:227], v173 offset:39936
	global_load_lds_dwordx4 v140, s[50:51]
	s_mov_b32 m0, s64
	s_nop 0
	global_load_lds_dwordx4 v142, s[50:51]
	s_waitcnt vmcnt(8)
	s_waitcnt lgkmcnt(0)
	s_barrier
	s_setprio 1
	s_waitcnt lgkmcnt(0)
	v_mfma_f32_16x16x32_bf16 v[136:139], v[112:115], v[184:187], v[136:139]
	v_mfma_f32_16x16x32_bf16 v[136:139], v[120:123], v[188:191], v[136:139]
	v_mfma_f32_16x16x32_bf16 v[116:119], v[120:123], v[208:211], v[116:119]
	v_mfma_f32_16x16x32_bf16 v[116:119], v[112:115], v[204:207], v[116:119]
	v_mfma_f32_16x16x32_bf16 v[96:99], v[112:115], v[212:215], v[96:99]
	v_mfma_f32_16x16x32_bf16 v[96:99], v[120:123], v[216:219], v[96:99]
	v_mfma_f32_16x16x32_bf16 v[80:83], v[120:123], v[224:227], v[80:83]
	v_mfma_f32_16x16x32_bf16 v[80:83], v[112:115], v[220:223], v[80:83]
	v_mfma_f32_16x16x32_bf16 v[76:79], v[152:155], v[220:223], v[76:79]
	v_mfma_f32_16x16x32_bf16 v[76:79], v[156:159], v[224:227], v[76:79]
	v_mfma_f32_16x16x32_bf16 v[92:95], v[156:159], v[216:219], v[92:95]
	v_mfma_f32_16x16x32_bf16 v[92:95], v[152:155], v[212:215], v[92:95]
	v_mfma_f32_16x16x32_bf16 v[108:111], v[152:155], v[204:207], v[108:111]
	v_mfma_f32_16x16x32_bf16 v[108:111], v[156:159], v[208:211], v[108:111]
	v_mfma_f32_16x16x32_bf16 v[132:135], v[156:159], v[188:191], v[132:135]
	v_mfma_f32_16x16x32_bf16 v[132:135], v[152:155], v[184:187], v[132:135]
	v_mfma_f32_16x16x32_bf16 v[128:131], v[160:163], v[184:187], v[128:131]
	v_mfma_f32_16x16x32_bf16 v[128:131], v[164:167], v[188:191], v[128:131]
	v_mfma_f32_16x16x32_bf16 v[104:107], v[164:167], v[208:211], v[104:107]
	v_mfma_f32_16x16x32_bf16 v[104:107], v[160:163], v[204:207], v[104:107]
	v_mfma_f32_16x16x32_bf16 v[88:91], v[160:163], v[212:215], v[88:91]
	v_mfma_f32_16x16x32_bf16 v[88:91], v[164:167], v[216:219], v[88:91]
	v_mfma_f32_16x16x32_bf16 v[72:75], v[164:167], v[224:227], v[72:75]
	v_mfma_f32_16x16x32_bf16 v[72:75], v[160:163], v[220:223], v[72:75]
	v_mfma_f32_16x16x32_bf16 v[68:71], v[176:179], v[220:223], v[68:71]
	v_mfma_f32_16x16x32_bf16 v[68:71], v[180:183], v[224:227], v[68:71]
	v_mfma_f32_16x16x32_bf16 v[84:87], v[180:183], v[216:219], v[84:87]
	v_mfma_f32_16x16x32_bf16 v[84:87], v[176:179], v[212:215], v[84:87]
	v_mfma_f32_16x16x32_bf16 v[100:103], v[176:179], v[204:207], v[100:103]
	v_mfma_f32_16x16x32_bf16 v[100:103], v[180:183], v[208:211], v[100:103]
	v_mfma_f32_16x16x32_bf16 v[124:127], v[180:183], v[188:191], v[124:127]
	v_mfma_f32_16x16x32_bf16 v[124:127], v[176:179], v[184:187], v[124:127]
	s_setprio 0
	s_barrier
	s_add_i32 s50, s56, s46
	v_lshl_add_u64 v[168:169], v[168:169], 0, s[84:85]
	s_mov_b32 m0, s50
	ds_read_b128 v[184:187], v173 offset:49152
	ds_read_b128 v[188:191], v173 offset:50176
	ds_read_b128 v[204:207], v173 offset:51200
	ds_read_b128 v[208:211], v173 offset:52224
	ds_read_b128 v[212:215], v173 offset:53248
	ds_read_b128 v[216:219], v173 offset:54272
	ds_read_b128 v[220:223], v173 offset:55296
	ds_read_b128 v[224:227], v173 offset:56320
	global_load_lds_dwordx4 v[168:169], off
	s_add_i32 m0, s50, 0x2000
	s_add_u32 s50, s72, 0x100080
	v_lshl_add_u64 v[168:169], v[228:229], 0, s[84:85]
	s_addc_u32 s51, s73, 0
	s_add_i32 s56, s57, s46
	global_load_lds_dwordx4 v[168:169], off
	s_mov_b32 m0, s56
	s_nop 0
	global_load_lds_dwordx4 v2, s[50:51]
	s_add_i32 m0, s56, 0x2000
	s_nop 0
	global_load_lds_dwordx4 v144, s[50:51]
	s_cmp_eq_u32 s97, 60
	s_cbranch_scc0 .Ldefer_230_peel
	v_lshl_add_u64 v[168:169], v[240:241], 0, s[84:85]
	s_mov_b32 m0, s28
	s_nop 0
	global_load_lds_dwordx4 v[168:169], off
	v_lshl_add_u64 v[168:169], v[242:243], 0, s[84:85]
	s_mov_b32 m0, s65
	s_nop 0
	global_load_lds_dwordx4 v[168:169], off

; #define PG8_STAGE(bufoff, gbase, voff) do { _Pragma("unroll") for (int _i = 0; _i < 2; ++_i) \
;         __builtin_amdgcn_global_load_lds((const unsigned*)((const char*)(gbase) + (voff)[_i]), (PG8_LAS unsigned*)(lds + (bufoff) + ldsw + _i * 8192), 16, 0, 0); } while (0)
; #define PG8_LDA(dst, b, h) do { _Pragma("unroll") for (int m = 0; m < 4; ++m) _Pragma("unroll") for (int k = 0; k < 2; ++k) dst[m][k] = *(const PG8_LAS bf16x8*)(lds + PG8_SA(b, h) + aoff + m * 2048 + k * 1024); } while (0)
; #define PG8_LDB(dst, b, h) do { _Pragma("unroll") for (int n = 0; n < 2; ++n) _Pragma("unroll") for (int k = 0; k < 2; ++k) dst[n][k] = *(const PG8_LAS bf16x8*)(lds + PG8_SB(b, h) + boff + n * 2048 + k * 1024); } while (0)
; #define PG8_WAIT_V(n) asm volatile("s_waitcnt vmcnt(" #n ")" ::: "memory")
; #define PG8_WAIT_L(n) asm volatile("s_waitcnt lgkmcnt(" #n ")" ::: "memory")
; #define PG8_BAR __builtin_amdgcn_s_barrier()
; #define PG8_SCHED __builtin_amdgcn_sched_barrier(0)
; template <class Epi, class Sched, bool ALIGN_EPI = false, bool SP2 = false, bool I8 = false>
; __device__ __forceinline__ void gemm_phase(PG8_LAS unsigned char* lds, const Gemm g, const Sched& S, const Epi& E) {
;     ...
;             const bool last = (t == nt - 2);
;             const char* a1 = cA + (size_t)(t + 1) * kstep;
;             const char* a2 = last ? nA : cA + (size_t)(t + 2) * kstep; const char* b2 = last ? nB : cB + (size_t)(t + 2) * kstep;
;             const char* a3 = a2 + kstep; const char* b3 = b2 + kstep;
;             if (last && has_next) S.a_ready(nxt);
;             if constexpr (SP2) {
;             PG8_LDB(B0, 0, 0); PG8_LDB(B1, 0, 1); PG8_SCHED; PG8_LDA(At, 0, 0); PG8_STAGE(PG8_SA(1, 1), a1 + hstep, voffA);
;             PG8_WAIT_V(8); PG8_WAIT_L(0); PG8_BAR; PG8_MMA(0, 0, At, B0); PG8_MMA(0, 1, At, B1); PG8_BAR; PG8_SCHED;
;             PG8_LDA(At, 0, 1); PG8_STAGE(PG8_SB(0, 0), b2, voffB); PG8_STAGE(PG8_SB(0, 1), b2 + hstep, voffB); PG8_STAGE(PG8_SA(0, 0), a2, voffA);
;             PG8_WAIT_V(8); PG8_WAIT_L(0); PG8_BAR; PG8_MMA(1, 0, At, B0); PG8_MMA(1, 1, At, B1); PG8_BAR; PG8_SCHED;
.LBB0_230:
	s_add_u32 s50, s12, 0xfff00080
	s_addc_u32 s51, s13, -1
	s_add_i32 s56, 0, 0x10000
	s_cmp_eq_u32 s97, 60
	s_cselect_b32 s77, s11, s51
	s_cselect_b32 s76, s34, s50
	s_cselect_b32 s73, s27, s61
	s_cselect_b32 s72, s35, s37
	s_add_i32 s57, 0, 0x14000
	v_add_u32_e32 v156, s56, v171
	v_add_u32_e32 v168, s57, v171
	ds_read_b128 v[112:115], v156
	ds_read_b128 v[120:123], v156 offset:1024
	ds_read_b128 v[152:155], v156 offset:2048
	ds_read_b128 v[156:159], v156 offset:3072
	ds_read_b128 v[160:163], v168
	ds_read_b128 v[164:167], v168 offset:1024
	ds_read_b128 v[176:179], v168 offset:2048
	ds_read_b128 v[180:183], v168 offset:3072
	v_lshl_add_u64 v[168:169], v[240:241], 0, s[84:85]
	s_mov_b32 m0, s28
	s_nop 0
	global_load_lds_dwordx4 v[168:169], off
	v_lshl_add_u64 v[168:169], v[242:243], 0, s[84:85]
	s_mov_b32 m0, s65
	s_nop 0
	global_load_lds_dwordx4 v[168:169], off
	s_add_i32 m0, s47, 0xc000
	ds_read_b128 v[184:187], v173
	ds_read_b128 v[188:191], v173 offset:1024
	ds_read_b128 v[204:207], v173 offset:2048
	ds_read_b128 v[208:211], v173 offset:3072
	ds_read_b128 v[212:215], v173 offset:4096
	ds_read_b128 v[216:219], v173 offset:5120
	ds_read_b128 v[220:223], v173 offset:6144
	ds_read_b128 v[224:227], v173 offset:7168
	global_load_lds_dwordx4 v148, s[12:13]
	s_add_i32 m0, s47, 0xe000
	s_nop 0
	global_load_lds_dwordx4 v150, s[12:13]
	s_waitcnt vmcnt(8)
	s_waitcnt lgkmcnt(0)
	s_barrier
	s_setprio 1
	s_waitcnt lgkmcnt(0)
	v_mfma_f32_16x16x32_bf16 v[136:139], v[112:115], v[184:187], v[136:139]
	v_mfma_f32_16x16x32_bf16 v[136:139], v[120:123], v[188:191], v[136:139]
	v_mfma_f32_16x16x32_bf16 v[116:119], v[120:123], v[208:211], v[116:119]
	v_mfma_f32_16x16x32_bf16 v[116:119], v[112:115], v[204:207], v[116:119]
	v_mfma_f32_16x16x32_bf16 v[96:99], v[112:115], v[212:215], v[96:99]
	v_mfma_f32_16x16x32_bf16 v[96:99], v[120:123], v[216:219], v[96:99]
	v_mfma_f32_16x16x32_bf16 v[80:83], v[120:123], v[224:227], v[80:83]
	v_mfma_f32_16x16x32_bf16 v[80:83], v[112:115], v[220:223], v[80:83]
	v_mfma_f32_16x16x32_bf16 v[76:79], v[152:155], v[220:223], v[76:79]
	v_mfma_f32_16x16x32_bf16 v[76:79], v[156:159], v[224:227], v[76:79]
	v_mfma_f32_16x16x32_bf16 v[92:95], v[156:159], v[216:219], v[92:95]
	v_mfma_f32_16x16x32_bf16 v[92:95], v[152:155], v[212:215], v[92:95]
	v_mfma_f32_16x16x32_bf16 v[108:111], v[152:155], v[204:207], v[108:111]
	v_mfma_f32_16x16x32_bf16 v[108:111], v[156:159], v[208:211], v[108:111]
	v_mfma_f32_16x16x32_bf16 v[132:135], v[156:159], v[188:191], v[132:135]
	v_mfma_f32_16x16x32_bf16 v[132:135], v[152:155], v[184:187], v[132:135]
	v_mfma_f32_16x16x32_bf16 v[128:131], v[160:163], v[184:187], v[128:131]
	v_mfma_f32_16x16x32_bf16 v[128:131], v[164:167], v[188:191], v[128:131]
	v_mfma_f32_16x16x32_bf16 v[104:107], v[164:167], v[208:211], v[104:107]
	v_mfma_f32_16x16x32_bf16 v[104:107], v[160:163], v[204:207], v[104:107]
	v_mfma_f32_16x16x32_bf16 v[88:91], v[160:163], v[212:215], v[88:91]
	v_mfma_f32_16x16x32_bf16 v[88:91], v[164:167], v[216:219], v[88:91]
	v_mfma_f32_16x16x32_bf16 v[72:75], v[164:167], v[224:227], v[72:75]
	v_mfma_f32_16x16x32_bf16 v[72:75], v[160:163], v[220:223], v[72:75]
	v_mfma_f32_16x16x32_bf16 v[68:71], v[176:179], v[220:223], v[68:71]
	v_mfma_f32_16x16x32_bf16 v[68:71], v[180:183], v[224:227], v[68:71]
	v_mfma_f32_16x16x32_bf16 v[84:87], v[180:183], v[216:219], v[84:87]
	v_mfma_f32_16x16x32_bf16 v[84:87], v[176:179], v[212:215], v[84:87]
	v_mfma_f32_16x16x32_bf16 v[100:103], v[176:179], v[204:207], v[100:103]
	v_mfma_f32_16x16x32_bf16 v[100:103], v[180:183], v[208:211], v[100:103]
	v_mfma_f32_16x16x32_bf16 v[124:127], v[180:183], v[188:191], v[124:127]
	v_mfma_f32_16x16x32_bf16 v[124:127], v[176:179], v[184:187], v[124:127]
	s_setprio 0
	s_barrier
	s_add_i32 s50, s56, s46
	v_lshl_add_u64 v[168:169], s[72:73], 0, v[2:3]
	s_mov_b32 m0, s50
	ds_read_b128 v[184:187], v173 offset:16384
	ds_read_b128 v[188:191], v173 offset:17408
	ds_read_b128 v[204:207], v173 offset:18432
	ds_read_b128 v[208:211], v173 offset:19456
	ds_read_b128 v[212:215], v173 offset:20480
	ds_read_b128 v[216:219], v173 offset:21504
	ds_read_b128 v[220:223], v173 offset:22528
	ds_read_b128 v[224:227], v173 offset:23552
	global_load_lds_dwordx4 v[168:169], off
	s_add_i32 m0, s50, 0x2000
	s_add_u32 s50, s72, 0x100000
	v_lshl_add_u64 v[228:229], s[72:73], 0, v[144:145]
	s_addc_u32 s51, s73, 0
	s_add_i32 s56, s57, s46
	global_load_lds_dwordx4 v[228:229], off
	s_mov_b32 m0, s56
	v_lshl_add_u64 v[242:243], s[76:77], 0, v[142:143]
	global_load_lds_dwordx4 v2, s[50:51]
	s_add_i32 m0, s56, 0x2000
	s_nop 0
	global_load_lds_dwordx4 v144, s[50:51]
	v_lshl_add_u64 v[240:241], s[76:77], 0, v[140:141]
	s_waitcnt vmcnt(6)
	s_waitcnt lgkmcnt(0)
	s_barrier
; #define PG8_STAGE(bufoff, gbase, voff) do { _Pragma("unroll") for (int _i = 0; _i < 2; ++_i) \
;         __builtin_amdgcn_global_load_lds((const unsigned*)((const char*)(gbase) + (voff)[_i]), (PG8_LAS unsigned*)(lds + (bufoff) + ldsw + _i * 8192), 16, 0, 0); } while (0)
; #define PG8_LDA(dst, b, h) do { _Pragma("unroll") for (int m = 0; m < 4; ++m) _Pragma("unroll") for (int k = 0; k < 2; ++k) dst[m][k] = *(const PG8_LAS bf16x8*)(lds + PG8_SA(b, h) + aoff + m * 2048 + k * 1024); } while (0)
; #define PG8_LDB(dst, b, h) do { _Pragma("unroll") for (int n = 0; n < 2; ++n) _Pragma("unroll") for (int k = 0; k < 2; ++k) dst[n][k] = *(const PG8_LAS bf16x8*)(lds + PG8_SB(b, h) + boff + n * 2048 + k * 1024); } while (0)
; #define PG8_WAIT_V(n) asm volatile("s_waitcnt vmcnt(" #n ")" ::: "memory")
; #define PG8_WAIT_L(n) asm volatile("s_waitcnt lgkmcnt(" #n ")" ::: "memory")
; #define PG8_BAR __builtin_amdgcn_s_barrier()
; #define PG8_SCHED __builtin_amdgcn_sched_barrier(0)
; template <class Epi, class Sched, bool ALIGN_EPI = false, bool SP2 = false, bool I8 = false>
; __device__ __forceinline__ void gemm_phase(PG8_LAS unsigned char* lds, const Gemm g, const Sched& S, const Epi& E) {
;     ...
;             PG8_WAIT_V(8); PG8_WAIT_L(0); PG8_BAR; PG8_MMA(1, 0, At, B0); PG8_MMA(1, 1, At, B1); PG8_BAR; PG8_SCHED;
;             PG8_LDB(B0, 1, 0); PG8_LDB(B1, 1, 1); PG8_SCHED; PG8_LDA(At, 1, 0); PG8_STAGE(PG8_SA(0, 1), a2 + hstep, voffA);
;             PG8_WAIT_V(8); PG8_WAIT_L(0); PG8_BAR; PG8_MMA(0, 0, At, B0); PG8_MMA(0, 1, At, B1); PG8_BAR; PG8_SCHED;
;             PG8_LDA(At, 1, 1); PG8_STAGE(PG8_SB(1, 0), b3, voffB); PG8_STAGE(PG8_SB(1, 1), b3 + hstep, voffB); PG8_STAGE(PG8_SA(1, 0), a3, voffA);
;             PG8_WAIT_V(8); PG8_WAIT_L(0); PG8_BAR; PG8_MMA(1, 0, At, B0); PG8_MMA(1, 1, At, B1); PG8_BAR; PG8_SCHED;
	s_setprio 1
	s_waitcnt lgkmcnt(0)
	v_mfma_f32_16x16x32_bf16 v[64:67], v[112:115], v[184:187], v[64:67]
	v_mfma_f32_16x16x32_bf16 v[64:67], v[120:123], v[188:191], v[64:67]
	v_mfma_f32_16x16x32_bf16 v[48:51], v[120:123], v[208:211], v[48:51]
	v_mfma_f32_16x16x32_bf16 v[48:51], v[112:115], v[204:207], v[48:51]
	v_mfma_f32_16x16x32_bf16 v[32:35], v[112:115], v[212:215], v[32:35]
	v_mfma_f32_16x16x32_bf16 v[32:35], v[120:123], v[216:219], v[32:35]
	v_mfma_f32_16x16x32_bf16 v[16:19], v[120:123], v[224:227], v[16:19]
	v_mfma_f32_16x16x32_bf16 v[16:19], v[112:115], v[220:223], v[16:19]
	v_mfma_f32_16x16x32_bf16 v[12:15], v[152:155], v[220:223], v[12:15]
	v_mfma_f32_16x16x32_bf16 v[12:15], v[156:159], v[224:227], v[12:15]
	v_mfma_f32_16x16x32_bf16 v[28:31], v[156:159], v[216:219], v[28:31]
	v_mfma_f32_16x16x32_bf16 v[28:31], v[152:155], v[212:215], v[28:31]
	v_mfma_f32_16x16x32_bf16 v[44:47], v[152:155], v[204:207], v[44:47]
	v_mfma_f32_16x16x32_bf16 v[44:47], v[156:159], v[208:211], v[44:47]
	v_mfma_f32_16x16x32_bf16 v[60:63], v[156:159], v[188:191], v[60:63]
	v_mfma_f32_16x16x32_bf16 v[60:63], v[152:155], v[184:187], v[60:63]
	v_mfma_f32_16x16x32_bf16 v[56:59], v[160:163], v[184:187], v[56:59]
	v_mfma_f32_16x16x32_bf16 v[56:59], v[164:167], v[188:191], v[56:59]
	v_mfma_f32_16x16x32_bf16 v[40:43], v[164:167], v[208:211], v[40:43]
	v_mfma_f32_16x16x32_bf16 v[40:43], v[160:163], v[204:207], v[40:43]
	v_mfma_f32_16x16x32_bf16 v[24:27], v[160:163], v[212:215], v[24:27]
	v_mfma_f32_16x16x32_bf16 v[24:27], v[164:167], v[216:219], v[24:27]
	v_mfma_f32_16x16x32_bf16 v[8:11], v[164:167], v[224:227], v[8:11]
	v_mfma_f32_16x16x32_bf16 v[8:11], v[160:163], v[220:223], v[8:11]
	v_mfma_f32_16x16x32_bf16 v[4:7], v[176:179], v[220:223], v[4:7]
	v_mfma_f32_16x16x32_bf16 v[4:7], v[180:183], v[224:227], v[4:7]
	v_mfma_f32_16x16x32_bf16 v[20:23], v[180:183], v[216:219], v[20:23]
	v_mfma_f32_16x16x32_bf16 v[20:23], v[176:179], v[212:215], v[20:23]
	v_mfma_f32_16x16x32_bf16 v[36:39], v[176:179], v[204:207], v[36:39]
	v_mfma_f32_16x16x32_bf16 v[36:39], v[180:183], v[208:211], v[36:39]
	v_mfma_f32_16x16x32_bf16 v[52:55], v[180:183], v[188:191], v[52:55]
	v_mfma_f32_16x16x32_bf16 v[52:55], v[176:179], v[184:187], v[52:55]
	s_setprio 0
	s_barrier
	s_mov_b32 m0, s47
	s_nop 0
	global_load_lds_dwordx4 v[240:241], off
	s_mov_b32 m0, s52
	s_nop 0
	global_load_lds_dwordx4 v[242:243], off
	s_add_i32 s56, 0, 0x18000
	s_add_i32 s57, 0, 0x1c000
	v_add_u32_e32 v156, s56, v171
	v_add_u32_e32 v175, s57, v171
	ds_read_b128 v[112:115], v156
	ds_read_b128 v[120:123], v156 offset:1024
	ds_read_b128 v[152:155], v156 offset:2048
	ds_read_b128 v[156:159], v156 offset:3072
	ds_read_b128 v[160:163], v175
	ds_read_b128 v[164:167], v175 offset:1024
	ds_read_b128 v[176:179], v175 offset:2048
	ds_read_b128 v[180:183], v175 offset:3072
	s_add_u32 s50, s76, 0x100000
	s_addc_u32 s51, s77, 0
	s_mov_b32 m0, s53
	ds_read_b128 v[184:187], v173 offset:32768
	ds_read_b128 v[188:191], v173 offset:33792
	ds_read_b128 v[204:207], v173 offset:34816
	ds_read_b128 v[208:211], v173 offset:35840
	ds_read_b128 v[212:215], v173 offset:36864
	ds_read_b128 v[216:219], v173 offset:37888
	ds_read_b128 v[220:223], v173 offset:38912
	ds_read_b128 v[224:227], v173 offset:39936
	global_load_lds_dwordx4 v140, s[50:51]
	s_mov_b32 m0, s64
	s_nop 0
	global_load_lds_dwordx4 v142, s[50:51]
	s_waitcnt vmcnt(8)
	s_waitcnt lgkmcnt(0)
	s_barrier
	s_setprio 1
	s_waitcnt lgkmcnt(0)
	v_mfma_f32_16x16x32_bf16 v[136:139], v[112:115], v[184:187], v[136:139]
	v_mfma_f32_16x16x32_bf16 v[136:139], v[120:123], v[188:191], v[136:139]
	v_mfma_f32_16x16x32_bf16 v[116:119], v[120:123], v[208:211], v[116:119]
	v_mfma_f32_16x16x32_bf16 v[116:119], v[112:115], v[204:207], v[116:119]
	v_mfma_f32_16x16x32_bf16 v[96:99], v[112:115], v[212:215], v[96:99]
	v_mfma_f32_16x16x32_bf16 v[96:99], v[120:123], v[216:219], v[96:99]
	v_mfma_f32_16x16x32_bf16 v[80:83], v[120:123], v[224:227], v[80:83]
	v_mfma_f32_16x16x32_bf16 v[80:83], v[112:115], v[220:223], v[80:83]
	v_mfma_f32_16x16x32_bf16 v[76:79], v[152:155], v[220:223], v[76:79]
	v_mfma_f32_16x16x32_bf16 v[76:79], v[156:159], v[224:227], v[76:79]
	v_mfma_f32_16x16x32_bf16 v[92:95], v[156:159], v[216:219], v[92:95]
	v_mfma_f32_16x16x32_bf16 v[92:95], v[152:155], v[212:215], v[92:95]
	v_mfma_f32_16x16x32_bf16 v[108:111], v[152:155], v[204:207], v[108:111]
	v_mfma_f32_16x16x32_bf16 v[108:111], v[156:159], v[208:211], v[108:111]
	v_mfma_f32_16x16x32_bf16 v[132:135], v[156:159], v[188:191], v[132:135]
	v_mfma_f32_16x16x32_bf16 v[132:135], v[152:155], v[184:187], v[132:135]
	v_mfma_f32_16x16x32_bf16 v[128:131], v[160:163], v[184:187], v[128:131]
	v_mfma_f32_16x16x32_bf16 v[128:131], v[164:167], v[188:191], v[128:131]
	v_mfma_f32_16x16x32_bf16 v[104:107], v[164:167], v[208:211], v[104:107]
	v_mfma_f32_16x16x32_bf16 v[104:107], v[160:163], v[204:207], v[104:107]
	v_mfma_f32_16x16x32_bf16 v[88:91], v[160:163], v[212:215], v[88:91]
	v_mfma_f32_16x16x32_bf16 v[88:91], v[164:167], v[216:219], v[88:91]
	v_mfma_f32_16x16x32_bf16 v[72:75], v[164:167], v[224:227], v[72:75]
	v_mfma_f32_16x16x32_bf16 v[72:75], v[160:163], v[220:223], v[72:75]
	v_mfma_f32_16x16x32_bf16 v[68:71], v[176:179], v[220:223], v[68:71]
	v_mfma_f32_16x16x32_bf16 v[68:71], v[180:183], v[224:227], v[68:71]
	v_mfma_f32_16x16x32_bf16 v[84:87], v[180:183], v[216:219], v[84:87]
	v_mfma_f32_16x16x32_bf16 v[84:87], v[176:179], v[212:215], v[84:87]
	v_mfma_f32_16x16x32_bf16 v[100:103], v[176:179], v[204:207], v[100:103]
	v_mfma_f32_16x16x32_bf16 v[100:103], v[180:183], v[208:211], v[100:103]
	v_mfma_f32_16x16x32_bf16 v[124:127], v[180:183], v[188:191], v[124:127]
	v_mfma_f32_16x16x32_bf16 v[124:127], v[176:179], v[184:187], v[124:127]
	s_setprio 0
	s_barrier
	s_add_i32 s50, s56, s46
	v_lshl_add_u64 v[168:169], v[168:169], 0, s[84:85]
	s_mov_b32 m0, s50
	ds_read_b128 v[184:187], v173 offset:49152
	ds_read_b128 v[188:191], v173 offset:50176
	ds_read_b128 v[204:207], v173 offset:51200
	ds_read_b128 v[208:211], v173 offset:52224
	ds_read_b128 v[212:215], v173 offset:53248
	ds_read_b128 v[216:219], v173 offset:54272
	ds_read_b128 v[220:223], v173 offset:55296
	ds_read_b128 v[224:227], v173 offset:56320
	global_load_lds_dwordx4 v[168:169], off
	s_add_i32 m0, s50, 0x2000
	s_add_u32 s50, s72, 0x100080
	v_lshl_add_u64 v[168:169], v[228:229], 0, s[84:85]
	s_addc_u32 s51, s73, 0
	s_add_i32 s56, s57, s46
	global_load_lds_dwordx4 v[168:169], off
	s_mov_b32 m0, s56
	s_nop 0
	global_load_lds_dwordx4 v2, s[50:51]
	s_add_i32 m0, s56, 0x2000
	s_nop 0
	global_load_lds_dwordx4 v144, s[50:51]
	s_cmp_eq_u32 s97, 60
	s_cbranch_scc0 .Ldefer_230_body
	v_lshl_add_u64 v[168:169], v[240:241], 0, s[84:85]
	s_mov_b32 m0, s28
	s_nop 0
	global_load_lds_dwordx4 v[168:169], off
	v_lshl_add_u64 v[168:169], v[242:243], 0, s[84:85]
	s_mov_b32 m0, s65
	s_nop 0
	global_load_lds_dwordx4 v[168:169], off

; #define PG8_STAGE(bufoff, gbase, voff) do { _Pragma("unroll") for (int _i = 0; _i < 2; ++_i) \
;         __builtin_amdgcn_global_load_lds((const unsigned*)((const char*)(gbase) + (voff)[_i]), (PG8_LAS unsigned*)(lds + (bufoff) + ldsw + _i * 8192), 16, 0, 0); } while (0)
; #define PG8_LDA(dst, b, h) do { _Pragma("unroll") for (int m = 0; m < 4; ++m) _Pragma("unroll") for (int k = 0; k < 2; ++k) dst[m][k] = *(const PG8_LAS bf16x8*)(lds + PG8_SA(b, h) + aoff + m * 2048 + k * 1024); } while (0)
; #define PG8_LDB(dst, b, h) do { _Pragma("unroll") for (int n = 0; n < 2; ++n) _Pragma("unroll") for (int k = 0; k < 2; ++k) dst[n][k] = *(const PG8_LAS bf16x8*)(lds + PG8_SB(b, h) + boff + n * 2048 + k * 1024); } while (0)
; #define PG8_WAIT_V(n) asm volatile("s_waitcnt vmcnt(" #n ")" ::: "memory")
; #define PG8_WAIT_L(n) asm volatile("s_waitcnt lgkmcnt(" #n ")" ::: "memory")
; #define PG8_BAR __builtin_amdgcn_s_barrier()
; #define PG8_SCHED __builtin_amdgcn_sched_barrier(0)
; template <class Epi, class Sched, bool ALIGN_EPI = false, bool SP2 = false, bool I8 = false>
; __device__ __forceinline__ void gemm_phase(PG8_LAS unsigned char* lds, const Gemm g, const Sched& S, const Epi& E) {
;     ...
;         const bool has_next = S.next(ui + 1, nxt);
;         const char* nA = has_next ? (const char*)g.A + (size_t)nxt.pm * tstep : cA; const char* nB = has_next ? (const char*)g.Bt + (size_t)nxt.pn * tstep : cB;
;         for (int t = 0; t < nt; t += 2) {
;             const bool last = (t == nt - 2);
;             const char* a1 = cA + (size_t)(t + 1) * kstep;
;             const char* a2 = last ? nA : cA + (size_t)(t + 2) * kstep; const char* b2 = last ? nB : cB + (size_t)(t + 2) * kstep;
;             const char* a3 = a2 + kstep; const char* b3 = b2 + kstep;
;             if (last && has_next) S.a_ready(nxt);
;             if constexpr (SP2) {
;             PG8_LDB(B0, 0, 0); PG8_LDB(B1, 0, 1); PG8_SCHED; PG8_LDA(At, 0, 0); PG8_STAGE(PG8_SA(1, 1), a1 + hstep, voffA);
;             PG8_WAIT_V(8); PG8_WAIT_L(0); PG8_BAR; PG8_MMA(0, 0, At, B0); PG8_MMA(0, 1, At, B1); PG8_BAR; PG8_SCHED;
;             PG8_LDA(At, 0, 1); PG8_STAGE(PG8_SB(0, 0), b2, voffB); PG8_STAGE(PG8_SB(0, 1), b2 + hstep, voffB); PG8_STAGE(PG8_SA(0, 0), a2, voffA);
;             PG8_WAIT_V(8); PG8_WAIT_L(0); PG8_BAR; PG8_MMA(1, 0, At, B0); PG8_MMA(1, 1, At, B1); PG8_BAR; PG8_SCHED;
.LBB0_1455:
	s_ashr_i32 s17, s16, 31
	s_lshl_b64 s[20:21], s[16:17], 21
	s_add_u32 s20, s28, s20
	s_addc_u32 s21, s34, s21
	s_and_b64 s[22:23], s[8:9], exec
	s_cselect_b32 s17, s21, s25
	s_cselect_b32 s51, s20, s24
	s_ashr_i32 s19, s18, 31
	s_lshl_b64 s[22:23], s[18:19], 21
	s_add_u32 s22, s35, s22
	s_addc_u32 s23, s39, s23
	s_and_b64 s[36:37], s[8:9], exec
	s_cselect_b32 s19, s23, s27
	s_cselect_b32 s52, s22, s26
	s_add_u32 s24, s24, 0x100080
	s_addc_u32 s25, s25, 0
	s_add_u32 s53, s26, 0x100
	s_addc_u32 s54, s27, 0
	s_mov_b32 s55, -2
	s_waitcnt vmcnt(0)
	s_add_u32 s26, s24, 0xfff00080
	s_addc_u32 s27, s25, -1
	s_add_i32 s56, 0, 0x10000
	s_cmp_eq_u32 s55, 60
	s_cselect_b32 s37, s17, s27
	s_cselect_b32 s36, s51, s26
	s_cselect_b32 s27, s19, s54
	s_cselect_b32 s26, s52, s53
	s_add_i32 s58, 0, 0x14000
	v_add_u32_e32 v144, s56, v240
	v_add_u32_e32 v160, s58, v240
	ds_read_b128 v[124:127], v144
	ds_read_b128 v[128:131], v144 offset:1024
	ds_read_b128 v[132:135], v144 offset:2048
	ds_read_b128 v[144:147], v144 offset:3072
	ds_read_b128 v[148:151], v160
	ds_read_b128 v[152:155], v160 offset:1024
	ds_read_b128 v[156:159], v160 offset:2048
	ds_read_b128 v[160:163], v160 offset:3072
	s_add_i32 m0, s41, 0xc000
	ds_read_b128 v[164:167], v242
	ds_read_b128 v[168:171], v242 offset:1024
	ds_read_b128 v[172:175], v242 offset:2048
	ds_read_b128 v[176:179], v242 offset:3072
	ds_read_b128 v[180:183], v242 offset:4096
	ds_read_b128 v[184:187], v242 offset:5120
	ds_read_b128 v[188:191], v242 offset:6144
	ds_read_b128 v[214:217], v242 offset:7168
	global_load_lds_dwordx4 v210, s[24:25]
	s_add_i32 m0, s41, 0xe000
	s_nop 0
	global_load_lds_dwordx4 v212, s[24:25]
	s_waitcnt vmcnt(8)
	s_waitcnt lgkmcnt(0)
	s_barrier
	s_setprio 1
	s_waitcnt lgkmcnt(0)
	v_mfma_f32_16x16x32_bf16 v[140:143], v[124:127], v[164:167], 0
	v_mfma_f32_16x16x32_bf16 v[140:143], v[128:131], v[168:171], v[140:143]
	v_mfma_f32_16x16x32_bf16 v[112:115], v[128:131], v[176:179], 0
	v_mfma_f32_16x16x32_bf16 v[112:115], v[124:127], v[172:175], v[112:115]
	v_mfma_f32_16x16x32_bf16 v[96:99], v[124:127], v[180:183], 0
	v_mfma_f32_16x16x32_bf16 v[96:99], v[128:131], v[184:187], v[96:99]
	v_mfma_f32_16x16x32_bf16 v[80:83], v[128:131], v[214:217], 0
	v_mfma_f32_16x16x32_bf16 v[80:83], v[124:127], v[188:191], v[80:83]
	v_mfma_f32_16x16x32_bf16 v[76:79], v[132:135], v[188:191], 0
	v_mfma_f32_16x16x32_bf16 v[76:79], v[144:147], v[214:217], v[76:79]
	v_mfma_f32_16x16x32_bf16 v[92:95], v[144:147], v[184:187], 0
	v_mfma_f32_16x16x32_bf16 v[92:95], v[132:135], v[180:183], v[92:95]
	v_mfma_f32_16x16x32_bf16 v[108:111], v[132:135], v[172:175], 0
	v_mfma_f32_16x16x32_bf16 v[108:111], v[144:147], v[176:179], v[108:111]
	v_mfma_f32_16x16x32_bf16 v[136:139], v[144:147], v[168:171], 0
	v_mfma_f32_16x16x32_bf16 v[136:139], v[132:135], v[164:167], v[136:139]
	v_mfma_f32_16x16x32_bf16 v[120:123], v[148:151], v[164:167], 0
	v_mfma_f32_16x16x32_bf16 v[120:123], v[152:155], v[168:171], v[120:123]
	v_mfma_f32_16x16x32_bf16 v[104:107], v[152:155], v[176:179], 0
	v_mfma_f32_16x16x32_bf16 v[104:107], v[148:151], v[172:175], v[104:107]
	v_mfma_f32_16x16x32_bf16 v[88:91], v[148:151], v[180:183], 0
	v_mfma_f32_16x16x32_bf16 v[88:91], v[152:155], v[184:187], v[88:91]
	v_mfma_f32_16x16x32_bf16 v[72:75], v[152:155], v[214:217], 0
	v_mfma_f32_16x16x32_bf16 v[72:75], v[148:151], v[188:191], v[72:75]
	v_mfma_f32_16x16x32_bf16 v[68:71], v[156:159], v[188:191], 0
	v_mfma_f32_16x16x32_bf16 v[68:71], v[160:163], v[214:217], v[68:71]
	v_mfma_f32_16x16x32_bf16 v[84:87], v[160:163], v[184:187], 0
	v_mfma_f32_16x16x32_bf16 v[84:87], v[156:159], v[180:183], v[84:87]
	v_mfma_f32_16x16x32_bf16 v[100:103], v[156:159], v[172:175], 0
	v_mfma_f32_16x16x32_bf16 v[100:103], v[160:163], v[176:179], v[100:103]
	v_mfma_f32_16x16x32_bf16 v[116:119], v[160:163], v[168:171], 0
	v_mfma_f32_16x16x32_bf16 v[116:119], v[156:159], v[164:167], v[116:119]
	s_setprio 0
	s_barrier
	s_add_i32 s56, s56, s40
	v_lshl_add_u64 v[218:219], s[26:27], 0, v[2:3]
	s_mov_b32 m0, s56
	ds_read_b128 v[164:167], v242 offset:16384
	ds_read_b128 v[168:171], v242 offset:17408
	ds_read_b128 v[172:175], v242 offset:18432
	ds_read_b128 v[176:179], v242 offset:19456
	ds_read_b128 v[180:183], v242 offset:20480
	ds_read_b128 v[184:187], v242 offset:21504
	ds_read_b128 v[188:191], v242 offset:22528
	ds_read_b128 v[214:217], v242 offset:23552
	global_load_lds_dwordx4 v[218:219], off
	s_add_i32 m0, s56, 0x2000
	s_add_u32 s56, s26, 0x100000
	v_lshl_add_u64 v[220:221], s[26:27], 0, v[204:205]
	s_addc_u32 s57, s27, 0
	s_add_i32 s58, s58, s40
	global_load_lds_dwordx4 v[220:221], off
	s_mov_b32 m0, s58
	v_lshl_add_u64 v[224:225], s[36:37], 0, v[206:207]
	global_load_lds_dwordx4 v2, s[56:57]
	s_add_i32 m0, s58, 0x2000
	s_nop 0
	global_load_lds_dwordx4 v204, s[56:57]
	v_lshl_add_u64 v[222:223], s[36:37], 0, v[208:209]
	s_waitcnt vmcnt(6)
	s_waitcnt lgkmcnt(0)
	s_barrier
; #define PG8_STAGE(bufoff, gbase, voff) do { _Pragma("unroll") for (int _i = 0; _i < 2; ++_i) \
;         __builtin_amdgcn_global_load_lds((const unsigned*)((const char*)(gbase) + (voff)[_i]), (PG8_LAS unsigned*)(lds + (bufoff) + ldsw + _i * 8192), 16, 0, 0); } while (0)
; #define PG8_LDA(dst, b, h) do { _Pragma("unroll") for (int m = 0; m < 4; ++m) _Pragma("unroll") for (int k = 0; k < 2; ++k) dst[m][k] = *(const PG8_LAS bf16x8*)(lds + PG8_SA(b, h) + aoff + m * 2048 + k * 1024); } while (0)
; #define PG8_LDB(dst, b, h) do { _Pragma("unroll") for (int n = 0; n < 2; ++n) _Pragma("unroll") for (int k = 0; k < 2; ++k) dst[n][k] = *(const PG8_LAS bf16x8*)(lds + PG8_SB(b, h) + boff + n * 2048 + k * 1024); } while (0)
; #define PG8_WAIT_V(n) asm volatile("s_waitcnt vmcnt(" #n ")" ::: "memory")
; #define PG8_WAIT_L(n) asm volatile("s_waitcnt lgkmcnt(" #n ")" ::: "memory")
; #define PG8_BAR __builtin_amdgcn_s_barrier()
; #define PG8_SCHED __builtin_amdgcn_sched_barrier(0)
; template <class Epi, class Sched, bool ALIGN_EPI = false, bool SP2 = false, bool I8 = false>
; __device__ __forceinline__ void gemm_phase(PG8_LAS unsigned char* lds, const Gemm g, const Sched& S, const Epi& E) {
;     ...
;             PG8_WAIT_V(8); PG8_WAIT_L(0); PG8_BAR; PG8_MMA(1, 0, At, B0); PG8_MMA(1, 1, At, B1); PG8_BAR; PG8_SCHED;
;             PG8_LDB(B0, 1, 0); PG8_LDB(B1, 1, 1); PG8_SCHED; PG8_LDA(At, 1, 0); PG8_STAGE(PG8_SA(0, 1), a2 + hstep, voffA);
;             PG8_WAIT_V(8); PG8_WAIT_L(0); PG8_BAR; PG8_MMA(0, 0, At, B0); PG8_MMA(0, 1, At, B1); PG8_BAR; PG8_SCHED;
;             PG8_LDA(At, 1, 1); PG8_STAGE(PG8_SB(1, 0), b3, voffB); PG8_STAGE(PG8_SB(1, 1), b3 + hstep, voffB); PG8_STAGE(PG8_SA(1, 0), a3, voffA);
;             PG8_WAIT_V(8); PG8_WAIT_L(0); PG8_BAR; PG8_MMA(1, 0, At, B0); PG8_MMA(1, 1, At, B1); PG8_BAR; PG8_SCHED;
	s_setprio 1
	s_waitcnt lgkmcnt(0)
	v_mfma_f32_16x16x32_bf16 v[64:67], v[124:127], v[164:167], 0
	v_mfma_f32_16x16x32_bf16 v[64:67], v[128:131], v[168:171], v[64:67]
	v_mfma_f32_16x16x32_bf16 v[48:51], v[128:131], v[176:179], 0
	v_mfma_f32_16x16x32_bf16 v[48:51], v[124:127], v[172:175], v[48:51]
	v_mfma_f32_16x16x32_bf16 v[32:35], v[124:127], v[180:183], 0
	v_mfma_f32_16x16x32_bf16 v[32:35], v[128:131], v[184:187], v[32:35]
	v_mfma_f32_16x16x32_bf16 v[16:19], v[128:131], v[214:217], 0
	v_mfma_f32_16x16x32_bf16 v[16:19], v[124:127], v[188:191], v[16:19]
	v_mfma_f32_16x16x32_bf16 v[12:15], v[132:135], v[188:191], 0
	v_mfma_f32_16x16x32_bf16 v[12:15], v[144:147], v[214:217], v[12:15]
	v_mfma_f32_16x16x32_bf16 v[28:31], v[144:147], v[184:187], 0
	v_mfma_f32_16x16x32_bf16 v[28:31], v[132:135], v[180:183], v[28:31]
	v_mfma_f32_16x16x32_bf16 v[44:47], v[132:135], v[172:175], 0
	v_mfma_f32_16x16x32_bf16 v[44:47], v[144:147], v[176:179], v[44:47]
	v_mfma_f32_16x16x32_bf16 v[60:63], v[144:147], v[168:171], 0
	v_mfma_f32_16x16x32_bf16 v[60:63], v[132:135], v[164:167], v[60:63]
	v_mfma_f32_16x16x32_bf16 v[56:59], v[148:151], v[164:167], 0
	v_mfma_f32_16x16x32_bf16 v[56:59], v[152:155], v[168:171], v[56:59]
	v_mfma_f32_16x16x32_bf16 v[40:43], v[152:155], v[176:179], 0
	v_mfma_f32_16x16x32_bf16 v[40:43], v[148:151], v[172:175], v[40:43]
	v_mfma_f32_16x16x32_bf16 v[24:27], v[148:151], v[180:183], 0
	v_mfma_f32_16x16x32_bf16 v[24:27], v[152:155], v[184:187], v[24:27]
	v_mfma_f32_16x16x32_bf16 v[8:11], v[152:155], v[214:217], 0
	v_mfma_f32_16x16x32_bf16 v[8:11], v[148:151], v[188:191], v[8:11]
	v_mfma_f32_16x16x32_bf16 v[4:7], v[156:159], v[188:191], 0
	v_mfma_f32_16x16x32_bf16 v[4:7], v[160:163], v[214:217], v[4:7]
	v_mfma_f32_16x16x32_bf16 v[20:23], v[160:163], v[184:187], 0
	v_mfma_f32_16x16x32_bf16 v[20:23], v[156:159], v[180:183], v[20:23]
	v_mfma_f32_16x16x32_bf16 v[36:39], v[156:159], v[172:175], 0
	v_mfma_f32_16x16x32_bf16 v[36:39], v[160:163], v[176:179], v[36:39]
	v_mfma_f32_16x16x32_bf16 v[52:55], v[160:163], v[168:171], 0
	v_mfma_f32_16x16x32_bf16 v[52:55], v[156:159], v[164:167], v[52:55]
	s_setprio 0
	s_barrier
	s_mov_b32 m0, s41
	s_nop 0
	global_load_lds_dwordx4 v[222:223], off
	s_mov_b32 m0, s42
	s_nop 0
	global_load_lds_dwordx4 v[224:225], off
	s_add_i32 s56, 0, 0x18000
	s_add_i32 s57, 0, 0x1c000
	v_add_u32_e32 v144, s56, v240
	v_add_u32_e32 v160, s57, v240
	ds_read_b128 v[124:127], v144
	ds_read_b128 v[128:131], v144 offset:1024
	ds_read_b128 v[132:135], v144 offset:2048
	ds_read_b128 v[144:147], v144 offset:3072
	ds_read_b128 v[148:151], v160
	ds_read_b128 v[152:155], v160 offset:1024
	ds_read_b128 v[156:159], v160 offset:2048
	ds_read_b128 v[160:163], v160 offset:3072
	s_add_u32 s36, s36, 0x100000
	s_addc_u32 s37, s37, 0
	s_mov_b32 m0, s43
	ds_read_b128 v[164:167], v242 offset:32768
	ds_read_b128 v[168:171], v242 offset:33792
	ds_read_b128 v[172:175], v242 offset:34816
	ds_read_b128 v[176:179], v242 offset:35840
	ds_read_b128 v[180:183], v242 offset:36864
	ds_read_b128 v[184:187], v242 offset:37888
	ds_read_b128 v[188:191], v242 offset:38912
	ds_read_b128 v[214:217], v242 offset:39936
	global_load_lds_dwordx4 v208, s[36:37]
	s_mov_b32 m0, s44
	s_nop 0
	global_load_lds_dwordx4 v206, s[36:37]
	s_waitcnt vmcnt(8)
	s_waitcnt lgkmcnt(0)
	s_barrier
	s_setprio 1
	s_waitcnt lgkmcnt(0)
	v_mfma_f32_16x16x32_bf16 v[140:143], v[124:127], v[164:167], v[140:143]
	v_mfma_f32_16x16x32_bf16 v[140:143], v[128:131], v[168:171], v[140:143]
	v_mfma_f32_16x16x32_bf16 v[112:115], v[128:131], v[176:179], v[112:115]
	v_mfma_f32_16x16x32_bf16 v[112:115], v[124:127], v[172:175], v[112:115]
	v_mfma_f32_16x16x32_bf16 v[96:99], v[124:127], v[180:183], v[96:99]
	v_mfma_f32_16x16x32_bf16 v[96:99], v[128:131], v[184:187], v[96:99]
	v_mfma_f32_16x16x32_bf16 v[80:83], v[128:131], v[214:217], v[80:83]
	v_mfma_f32_16x16x32_bf16 v[80:83], v[124:127], v[188:191], v[80:83]
	v_mfma_f32_16x16x32_bf16 v[76:79], v[132:135], v[188:191], v[76:79]
	v_mfma_f32_16x16x32_bf16 v[76:79], v[144:147], v[214:217], v[76:79]
	v_mfma_f32_16x16x32_bf16 v[92:95], v[144:147], v[184:187], v[92:95]
	v_mfma_f32_16x16x32_bf16 v[92:95], v[132:135], v[180:183], v[92:95]
	v_mfma_f32_16x16x32_bf16 v[108:111], v[132:135], v[172:175], v[108:111]
	v_mfma_f32_16x16x32_bf16 v[108:111], v[144:147], v[176:179], v[108:111]
	v_mfma_f32_16x16x32_bf16 v[136:139], v[144:147], v[168:171], v[136:139]
	v_mfma_f32_16x16x32_bf16 v[136:139], v[132:135], v[164:167], v[136:139]
	v_mfma_f32_16x16x32_bf16 v[120:123], v[148:151], v[164:167], v[120:123]
	v_mfma_f32_16x16x32_bf16 v[120:123], v[152:155], v[168:171], v[120:123]
	v_mfma_f32_16x16x32_bf16 v[104:107], v[152:155], v[176:179], v[104:107]
	v_mfma_f32_16x16x32_bf16 v[104:107], v[148:151], v[172:175], v[104:107]
	v_mfma_f32_16x16x32_bf16 v[88:91], v[148:151], v[180:183], v[88:91]
	v_mfma_f32_16x16x32_bf16 v[88:91], v[152:155], v[184:187], v[88:91]
	v_mfma_f32_16x16x32_bf16 v[72:75], v[152:155], v[214:217], v[72:75]
	v_mfma_f32_16x16x32_bf16 v[72:75], v[148:151], v[188:191], v[72:75]
	v_mfma_f32_16x16x32_bf16 v[68:71], v[156:159], v[188:191], v[68:71]
	v_mfma_f32_16x16x32_bf16 v[68:71], v[160:163], v[214:217], v[68:71]
	v_mfma_f32_16x16x32_bf16 v[84:87], v[160:163], v[184:187], v[84:87]
	v_mfma_f32_16x16x32_bf16 v[84:87], v[156:159], v[180:183], v[84:87]
	v_mfma_f32_16x16x32_bf16 v[100:103], v[156:159], v[172:175], v[100:103]
	v_mfma_f32_16x16x32_bf16 v[100:103], v[160:163], v[176:179], v[100:103]
	v_mfma_f32_16x16x32_bf16 v[116:119], v[160:163], v[168:171], v[116:119]
	v_mfma_f32_16x16x32_bf16 v[116:119], v[156:159], v[164:167], v[116:119]
	s_setprio 0
	s_barrier
	s_add_i32 s36, s56, s40
	v_lshl_add_u64 v[218:219], v[218:219], 0, s[84:85]
	s_mov_b32 m0, s36
	ds_read_b128 v[164:167], v242 offset:49152
	ds_read_b128 v[168:171], v242 offset:50176
	ds_read_b128 v[172:175], v242 offset:51200
	ds_read_b128 v[176:179], v242 offset:52224
	ds_read_b128 v[180:183], v242 offset:53248
	ds_read_b128 v[184:187], v242 offset:54272
	ds_read_b128 v[188:191], v242 offset:55296
	ds_read_b128 v[214:217], v242 offset:56320
	global_load_lds_dwordx4 v[218:219], off
	s_add_i32 m0, s36, 0x2000
	s_add_u32 s26, s26, 0x100080
	v_lshl_add_u64 v[218:219], v[220:221], 0, s[84:85]
	s_addc_u32 s27, s27, 0
	s_add_i32 s36, s57, s40
	global_load_lds_dwordx4 v[218:219], off
	s_mov_b32 m0, s36
	s_nop 0
	global_load_lds_dwordx4 v2, s[26:27]
	s_add_i32 m0, s36, 0x2000
	s_nop 0
	global_load_lds_dwordx4 v204, s[26:27]
	s_cmp_eq_u32 s55, 60
	s_cbranch_scc0 .Ldefer_1456_peel
	v_lshl_add_u64 v[218:219], v[222:223], 0, s[84:85]
	s_mov_b32 m0, s45
	s_nop 0
	global_load_lds_dwordx4 v[218:219], off
	v_lshl_add_u64 v[218:219], v[224:225], 0, s[84:85]
	s_mov_b32 m0, s46
	s_nop 0
	global_load_lds_dwordx4 v[218:219], off

; #define PG8_STAGE(bufoff, gbase, voff) do { _Pragma("unroll") for (int _i = 0; _i < 2; ++_i) \
;         __builtin_amdgcn_global_load_lds((const unsigned*)((const char*)(gbase) + (voff)[_i]), (PG8_LAS unsigned*)(lds + (bufoff) + ldsw + _i * 8192), 16, 0, 0); } while (0)
; #define PG8_LDA(dst, b, h) do { _Pragma("unroll") for (int m = 0; m < 4; ++m) _Pragma("unroll") for (int k = 0; k < 2; ++k) dst[m][k] = *(const PG8_LAS bf16x8*)(lds + PG8_SA(b, h) + aoff + m * 2048 + k * 1024); } while (0)
; #define PG8_LDB(dst, b, h) do { _Pragma("unroll") for (int n = 0; n < 2; ++n) _Pragma("unroll") for (int k = 0; k < 2; ++k) dst[n][k] = *(const PG8_LAS bf16x8*)(lds + PG8_SB(b, h) + boff + n * 2048 + k * 1024); } while (0)
; #define PG8_WAIT_V(n) asm volatile("s_waitcnt vmcnt(" #n ")" ::: "memory")
; #define PG8_WAIT_L(n) asm volatile("s_waitcnt lgkmcnt(" #n ")" ::: "memory")
; #define PG8_BAR __builtin_amdgcn_s_barrier()
; #define PG8_SCHED __builtin_amdgcn_sched_barrier(0)
; template <class Epi, class Sched, bool ALIGN_EPI = false, bool SP2 = false, bool I8 = false>
; __device__ __forceinline__ void gemm_phase(PG8_LAS unsigned char* lds, const Gemm g, const Sched& S, const Epi& E) {
;     ...
;             const bool last = (t == nt - 2);
;             const char* a1 = cA + (size_t)(t + 1) * kstep;
;             const char* a2 = last ? nA : cA + (size_t)(t + 2) * kstep; const char* b2 = last ? nB : cB + (size_t)(t + 2) * kstep;
;             const char* a3 = a2 + kstep; const char* b3 = b2 + kstep;
;             if (last && has_next) S.a_ready(nxt);
;             if constexpr (SP2) {
;             PG8_LDB(B0, 0, 0); PG8_LDB(B1, 0, 1); PG8_SCHED; PG8_LDA(At, 0, 0); PG8_STAGE(PG8_SA(1, 1), a1 + hstep, voffA);
;             PG8_WAIT_V(8); PG8_WAIT_L(0); PG8_BAR; PG8_MMA(0, 0, At, B0); PG8_MMA(0, 1, At, B1); PG8_BAR; PG8_SCHED;
;             PG8_LDA(At, 0, 1); PG8_STAGE(PG8_SB(0, 0), b2, voffB); PG8_STAGE(PG8_SB(0, 1), b2 + hstep, voffB); PG8_STAGE(PG8_SA(0, 0), a2, voffA);
;             PG8_WAIT_V(8); PG8_WAIT_L(0); PG8_BAR; PG8_MMA(1, 0, At, B0); PG8_MMA(1, 1, At, B1); PG8_BAR; PG8_SCHED;
.LBB0_1456:
	s_add_u32 s26, s24, 0xfff00080
	s_addc_u32 s27, s25, -1
	s_add_i32 s56, 0, 0x10000
	s_cmp_eq_u32 s55, 60
	s_cselect_b32 s37, s17, s27
	s_cselect_b32 s36, s51, s26
	s_cselect_b32 s27, s19, s54
	s_cselect_b32 s26, s52, s53
	s_add_i32 s58, 0, 0x14000
	v_add_u32_e32 v144, s56, v240
	v_add_u32_e32 v160, s58, v240
	ds_read_b128 v[124:127], v144
	ds_read_b128 v[128:131], v144 offset:1024
	ds_read_b128 v[132:135], v144 offset:2048
	ds_read_b128 v[144:147], v144 offset:3072
	ds_read_b128 v[148:151], v160
	ds_read_b128 v[152:155], v160 offset:1024
	ds_read_b128 v[156:159], v160 offset:2048
	ds_read_b128 v[160:163], v160 offset:3072
	v_lshl_add_u64 v[218:219], v[222:223], 0, s[84:85]
	s_mov_b32 m0, s45
	s_nop 0
	global_load_lds_dwordx4 v[218:219], off
	v_lshl_add_u64 v[218:219], v[224:225], 0, s[84:85]
	s_mov_b32 m0, s46
	s_nop 0
	global_load_lds_dwordx4 v[218:219], off
	s_add_i32 m0, s41, 0xc000
	ds_read_b128 v[164:167], v242
	ds_read_b128 v[168:171], v242 offset:1024
	ds_read_b128 v[172:175], v242 offset:2048
	ds_read_b128 v[176:179], v242 offset:3072
	ds_read_b128 v[180:183], v242 offset:4096
	ds_read_b128 v[184:187], v242 offset:5120
	ds_read_b128 v[188:191], v242 offset:6144
	ds_read_b128 v[214:217], v242 offset:7168
	global_load_lds_dwordx4 v210, s[24:25]
	s_add_i32 m0, s41, 0xe000
	s_nop 0
	global_load_lds_dwordx4 v212, s[24:25]
	s_waitcnt vmcnt(8)
	s_waitcnt lgkmcnt(0)
	s_barrier
	s_setprio 1
	s_waitcnt lgkmcnt(0)
	v_mfma_f32_16x16x32_bf16 v[140:143], v[124:127], v[164:167], v[140:143]
	v_mfma_f32_16x16x32_bf16 v[140:143], v[128:131], v[168:171], v[140:143]
	v_mfma_f32_16x16x32_bf16 v[112:115], v[128:131], v[176:179], v[112:115]
	v_mfma_f32_16x16x32_bf16 v[112:115], v[124:127], v[172:175], v[112:115]
	v_mfma_f32_16x16x32_bf16 v[96:99], v[124:127], v[180:183], v[96:99]
	v_mfma_f32_16x16x32_bf16 v[96:99], v[128:131], v[184:187], v[96:99]
	v_mfma_f32_16x16x32_bf16 v[80:83], v[128:131], v[214:217], v[80:83]
	v_mfma_f32_16x16x32_bf16 v[80:83], v[124:127], v[188:191], v[80:83]
	v_mfma_f32_16x16x32_bf16 v[76:79], v[132:135], v[188:191], v[76:79]
	v_mfma_f32_16x16x32_bf16 v[76:79], v[144:147], v[214:217], v[76:79]
	v_mfma_f32_16x16x32_bf16 v[92:95], v[144:147], v[184:187], v[92:95]
	v_mfma_f32_16x16x32_bf16 v[92:95], v[132:135], v[180:183], v[92:95]
	v_mfma_f32_16x16x32_bf16 v[108:111], v[132:135], v[172:175], v[108:111]
	v_mfma_f32_16x16x32_bf16 v[108:111], v[144:147], v[176:179], v[108:111]
	v_mfma_f32_16x16x32_bf16 v[136:139], v[144:147], v[168:171], v[136:139]
	v_mfma_f32_16x16x32_bf16 v[136:139], v[132:135], v[164:167], v[136:139]
	v_mfma_f32_16x16x32_bf16 v[120:123], v[148:151], v[164:167], v[120:123]
	v_mfma_f32_16x16x32_bf16 v[120:123], v[152:155], v[168:171], v[120:123]
	v_mfma_f32_16x16x32_bf16 v[104:107], v[152:155], v[176:179], v[104:107]
	v_mfma_f32_16x16x32_bf16 v[104:107], v[148:151], v[172:175], v[104:107]
	v_mfma_f32_16x16x32_bf16 v[88:91], v[148:151], v[180:183], v[88:91]
	v_mfma_f32_16x16x32_bf16 v[88:91], v[152:155], v[184:187], v[88:91]
	v_mfma_f32_16x16x32_bf16 v[72:75], v[152:155], v[214:217], v[72:75]
	v_mfma_f32_16x16x32_bf16 v[72:75], v[148:151], v[188:191], v[72:75]
	v_mfma_f32_16x16x32_bf16 v[68:71], v[156:159], v[188:191], v[68:71]
	v_mfma_f32_16x16x32_bf16 v[68:71], v[160:163], v[214:217], v[68:71]
	v_mfma_f32_16x16x32_bf16 v[84:87], v[160:163], v[184:187], v[84:87]
	v_mfma_f32_16x16x32_bf16 v[84:87], v[156:159], v[180:183], v[84:87]
	v_mfma_f32_16x16x32_bf16 v[100:103], v[156:159], v[172:175], v[100:103]
	v_mfma_f32_16x16x32_bf16 v[100:103], v[160:163], v[176:179], v[100:103]
	v_mfma_f32_16x16x32_bf16 v[116:119], v[160:163], v[168:171], v[116:119]
	v_mfma_f32_16x16x32_bf16 v[116:119], v[156:159], v[164:167], v[116:119]
	s_setprio 0
	s_barrier
	s_add_i32 s56, s56, s40
	v_lshl_add_u64 v[218:219], s[26:27], 0, v[2:3]
	s_mov_b32 m0, s56
	ds_read_b128 v[164:167], v242 offset:16384
	ds_read_b128 v[168:171], v242 offset:17408
	ds_read_b128 v[172:175], v242 offset:18432
	ds_read_b128 v[176:179], v242 offset:19456
	ds_read_b128 v[180:183], v242 offset:20480
	ds_read_b128 v[184:187], v242 offset:21504
	ds_read_b128 v[188:191], v242 offset:22528
	ds_read_b128 v[214:217], v242 offset:23552
	global_load_lds_dwordx4 v[218:219], off
	s_add_i32 m0, s56, 0x2000
	s_add_u32 s56, s26, 0x100000
	v_lshl_add_u64 v[220:221], s[26:27], 0, v[204:205]
	s_addc_u32 s57, s27, 0
	s_add_i32 s58, s58, s40
	global_load_lds_dwordx4 v[220:221], off
	s_mov_b32 m0, s58
	v_lshl_add_u64 v[224:225], s[36:37], 0, v[206:207]
	global_load_lds_dwordx4 v2, s[56:57]
	s_add_i32 m0, s58, 0x2000
	s_nop 0
	global_load_lds_dwordx4 v204, s[56:57]
	v_lshl_add_u64 v[222:223], s[36:37], 0, v[208:209]
	s_waitcnt vmcnt(6)
	s_waitcnt lgkmcnt(0)
	s_barrier
; #define PG8_STAGE(bufoff, gbase, voff) do { _Pragma("unroll") for (int _i = 0; _i < 2; ++_i) \
;         __builtin_amdgcn_global_load_lds((const unsigned*)((const char*)(gbase) + (voff)[_i]), (PG8_LAS unsigned*)(lds + (bufoff) + ldsw + _i * 8192), 16, 0, 0); } while (0)
; #define PG8_LDA(dst, b, h) do { _Pragma("unroll") for (int m = 0; m < 4; ++m) _Pragma("unroll") for (int k = 0; k < 2; ++k) dst[m][k] = *(const PG8_LAS bf16x8*)(lds + PG8_SA(b, h) + aoff + m * 2048 + k * 1024); } while (0)
; #define PG8_LDB(dst, b, h) do { _Pragma("unroll") for (int n = 0; n < 2; ++n) _Pragma("unroll") for (int k = 0; k < 2; ++k) dst[n][k] = *(const PG8_LAS bf16x8*)(lds + PG8_SB(b, h) + boff + n * 2048 + k * 1024); } while (0)
; #define PG8_WAIT_V(n) asm volatile("s_waitcnt vmcnt(" #n ")" ::: "memory")
; #define PG8_WAIT_L(n) asm volatile("s_waitcnt lgkmcnt(" #n ")" ::: "memory")
; #define PG8_BAR __builtin_amdgcn_s_barrier()
; #define PG8_SCHED __builtin_amdgcn_sched_barrier(0)
; template <class Epi, class Sched, bool ALIGN_EPI = false, bool SP2 = false, bool I8 = false>
; __device__ __forceinline__ void gemm_phase(PG8_LAS unsigned char* lds, const Gemm g, const Sched& S, const Epi& E) {
;     ...
;             PG8_WAIT_V(8); PG8_WAIT_L(0); PG8_BAR; PG8_MMA(1, 0, At, B0); PG8_MMA(1, 1, At, B1); PG8_BAR; PG8_SCHED;
;             PG8_LDB(B0, 1, 0); PG8_LDB(B1, 1, 1); PG8_SCHED; PG8_LDA(At, 1, 0); PG8_STAGE(PG8_SA(0, 1), a2 + hstep, voffA);
;             PG8_WAIT_V(8); PG8_WAIT_L(0); PG8_BAR; PG8_MMA(0, 0, At, B0); PG8_MMA(0, 1, At, B1); PG8_BAR; PG8_SCHED;
;             PG8_LDA(At, 1, 1); PG8_STAGE(PG8_SB(1, 0), b3, voffB); PG8_STAGE(PG8_SB(1, 1), b3 + hstep, voffB); PG8_STAGE(PG8_SA(1, 0), a3, voffA);
;             PG8_WAIT_V(8); PG8_WAIT_L(0); PG8_BAR; PG8_MMA(1, 0, At, B0); PG8_MMA(1, 1, At, B1); PG8_BAR; PG8_SCHED;
	s_setprio 1
	s_waitcnt lgkmcnt(0)
	v_mfma_f32_16x16x32_bf16 v[64:67], v[124:127], v[164:167], v[64:67]
	v_mfma_f32_16x16x32_bf16 v[64:67], v[128:131], v[168:171], v[64:67]
	v_mfma_f32_16x16x32_bf16 v[48:51], v[128:131], v[176:179], v[48:51]
	v_mfma_f32_16x16x32_bf16 v[48:51], v[124:127], v[172:175], v[48:51]
	v_mfma_f32_16x16x32_bf16 v[32:35], v[124:127], v[180:183], v[32:35]
	v_mfma_f32_16x16x32_bf16 v[32:35], v[128:131], v[184:187], v[32:35]
	v_mfma_f32_16x16x32_bf16 v[16:19], v[128:131], v[214:217], v[16:19]
	v_mfma_f32_16x16x32_bf16 v[16:19], v[124:127], v[188:191], v[16:19]
	v_mfma_f32_16x16x32_bf16 v[12:15], v[132:135], v[188:191], v[12:15]
	v_mfma_f32_16x16x32_bf16 v[12:15], v[144:147], v[214:217], v[12:15]
	v_mfma_f32_16x16x32_bf16 v[28:31], v[144:147], v[184:187], v[28:31]
	v_mfma_f32_16x16x32_bf16 v[28:31], v[132:135], v[180:183], v[28:31]
	v_mfma_f32_16x16x32_bf16 v[44:47], v[132:135], v[172:175], v[44:47]
	v_mfma_f32_16x16x32_bf16 v[44:47], v[144:147], v[176:179], v[44:47]
	v_mfma_f32_16x16x32_bf16 v[60:63], v[144:147], v[168:171], v[60:63]
	v_mfma_f32_16x16x32_bf16 v[60:63], v[132:135], v[164:167], v[60:63]
	v_mfma_f32_16x16x32_bf16 v[56:59], v[148:151], v[164:167], v[56:59]
	v_mfma_f32_16x16x32_bf16 v[56:59], v[152:155], v[168:171], v[56:59]
	v_mfma_f32_16x16x32_bf16 v[40:43], v[152:155], v[176:179], v[40:43]
	v_mfma_f32_16x16x32_bf16 v[40:43], v[148:151], v[172:175], v[40:43]
	v_mfma_f32_16x16x32_bf16 v[24:27], v[148:151], v[180:183], v[24:27]
	v_mfma_f32_16x16x32_bf16 v[24:27], v[152:155], v[184:187], v[24:27]
	v_mfma_f32_16x16x32_bf16 v[8:11], v[152:155], v[214:217], v[8:11]
	v_mfma_f32_16x16x32_bf16 v[8:11], v[148:151], v[188:191], v[8:11]
	v_mfma_f32_16x16x32_bf16 v[4:7], v[156:159], v[188:191], v[4:7]
	v_mfma_f32_16x16x32_bf16 v[4:7], v[160:163], v[214:217], v[4:7]
	v_mfma_f32_16x16x32_bf16 v[20:23], v[160:163], v[184:187], v[20:23]
	v_mfma_f32_16x16x32_bf16 v[20:23], v[156:159], v[180:183], v[20:23]
	v_mfma_f32_16x16x32_bf16 v[36:39], v[156:159], v[172:175], v[36:39]
	v_mfma_f32_16x16x32_bf16 v[36:39], v[160:163], v[176:179], v[36:39]
	v_mfma_f32_16x16x32_bf16 v[52:55], v[160:163], v[168:171], v[52:55]
	v_mfma_f32_16x16x32_bf16 v[52:55], v[156:159], v[164:167], v[52:55]
	s_setprio 0
	s_barrier
	s_mov_b32 m0, s41
	s_nop 0
	global_load_lds_dwordx4 v[222:223], off
	s_mov_b32 m0, s42
	s_nop 0
	global_load_lds_dwordx4 v[224:225], off
	s_add_i32 s56, 0, 0x18000
	s_add_i32 s57, 0, 0x1c000
	v_add_u32_e32 v144, s56, v240
	v_add_u32_e32 v160, s57, v240
	ds_read_b128 v[124:127], v144
	ds_read_b128 v[128:131], v144 offset:1024
	ds_read_b128 v[132:135], v144 offset:2048
	ds_read_b128 v[144:147], v144 offset:3072
	ds_read_b128 v[148:151], v160
	ds_read_b128 v[152:155], v160 offset:1024
	ds_read_b128 v[156:159], v160 offset:2048
	ds_read_b128 v[160:163], v160 offset:3072
	s_add_u32 s36, s36, 0x100000
	s_addc_u32 s37, s37, 0
	s_mov_b32 m0, s43
	ds_read_b128 v[164:167], v242 offset:32768
	ds_read_b128 v[168:171], v242 offset:33792
	ds_read_b128 v[172:175], v242 offset:34816
	ds_read_b128 v[176:179], v242 offset:35840
	ds_read_b128 v[180:183], v242 offset:36864
	ds_read_b128 v[184:187], v242 offset:37888
	ds_read_b128 v[188:191], v242 offset:38912
	ds_read_b128 v[214:217], v242 offset:39936
	global_load_lds_dwordx4 v208, s[36:37]
	s_mov_b32 m0, s44
	s_nop 0
	global_load_lds_dwordx4 v206, s[36:37]
	s_waitcnt vmcnt(8)
	s_waitcnt lgkmcnt(0)
	s_barrier
	s_setprio 1
	s_waitcnt lgkmcnt(0)
	v_mfma_f32_16x16x32_bf16 v[140:143], v[124:127], v[164:167], v[140:143]
	v_mfma_f32_16x16x32_bf16 v[140:143], v[128:131], v[168:171], v[140:143]
	v_mfma_f32_16x16x32_bf16 v[112:115], v[128:131], v[176:179], v[112:115]
	v_mfma_f32_16x16x32_bf16 v[112:115], v[124:127], v[172:175], v[112:115]
	v_mfma_f32_16x16x32_bf16 v[96:99], v[124:127], v[180:183], v[96:99]
	v_mfma_f32_16x16x32_bf16 v[96:99], v[128:131], v[184:187], v[96:99]
	v_mfma_f32_16x16x32_bf16 v[80:83], v[128:131], v[214:217], v[80:83]
	v_mfma_f32_16x16x32_bf16 v[80:83], v[124:127], v[188:191], v[80:83]
	v_mfma_f32_16x16x32_bf16 v[76:79], v[132:135], v[188:191], v[76:79]
	v_mfma_f32_16x16x32_bf16 v[76:79], v[144:147], v[214:217], v[76:79]
	v_mfma_f32_16x16x32_bf16 v[92:95], v[144:147], v[184:187], v[92:95]
	v_mfma_f32_16x16x32_bf16 v[92:95], v[132:135], v[180:183], v[92:95]
	v_mfma_f32_16x16x32_bf16 v[108:111], v[132:135], v[172:175], v[108:111]
	v_mfma_f32_16x16x32_bf16 v[108:111], v[144:147], v[176:179], v[108:111]
	v_mfma_f32_16x16x32_bf16 v[136:139], v[144:147], v[168:171], v[136:139]
	v_mfma_f32_16x16x32_bf16 v[136:139], v[132:135], v[164:167], v[136:139]
	v_mfma_f32_16x16x32_bf16 v[120:123], v[148:151], v[164:167], v[120:123]
	v_mfma_f32_16x16x32_bf16 v[120:123], v[152:155], v[168:171], v[120:123]
	v_mfma_f32_16x16x32_bf16 v[104:107], v[152:155], v[176:179], v[104:107]
	v_mfma_f32_16x16x32_bf16 v[104:107], v[148:151], v[172:175], v[104:107]
	v_mfma_f32_16x16x32_bf16 v[88:91], v[148:151], v[180:183], v[88:91]
	v_mfma_f32_16x16x32_bf16 v[88:91], v[152:155], v[184:187], v[88:91]
	v_mfma_f32_16x16x32_bf16 v[72:75], v[152:155], v[214:217], v[72:75]
	v_mfma_f32_16x16x32_bf16 v[72:75], v[148:151], v[188:191], v[72:75]
	v_mfma_f32_16x16x32_bf16 v[68:71], v[156:159], v[188:191], v[68:71]
	v_mfma_f32_16x16x32_bf16 v[68:71], v[160:163], v[214:217], v[68:71]
	v_mfma_f32_16x16x32_bf16 v[84:87], v[160:163], v[184:187], v[84:87]
	v_mfma_f32_16x16x32_bf16 v[84:87], v[156:159], v[180:183], v[84:87]
	v_mfma_f32_16x16x32_bf16 v[100:103], v[156:159], v[172:175], v[100:103]
	v_mfma_f32_16x16x32_bf16 v[100:103], v[160:163], v[176:179], v[100:103]
	v_mfma_f32_16x16x32_bf16 v[116:119], v[160:163], v[168:171], v[116:119]
	v_mfma_f32_16x16x32_bf16 v[116:119], v[156:159], v[164:167], v[116:119]
	s_setprio 0
	s_barrier
	s_add_i32 s36, s56, s40
	v_lshl_add_u64 v[218:219], v[218:219], 0, s[84:85]
	s_mov_b32 m0, s36
	ds_read_b128 v[164:167], v242 offset:49152
	ds_read_b128 v[168:171], v242 offset:50176
	ds_read_b128 v[172:175], v242 offset:51200
	ds_read_b128 v[176:179], v242 offset:52224
	ds_read_b128 v[180:183], v242 offset:53248
	ds_read_b128 v[184:187], v242 offset:54272
	ds_read_b128 v[188:191], v242 offset:55296
	ds_read_b128 v[214:217], v242 offset:56320
	global_load_lds_dwordx4 v[218:219], off
	s_add_i32 m0, s36, 0x2000
	s_add_u32 s26, s26, 0x100080
	v_lshl_add_u64 v[218:219], v[220:221], 0, s[84:85]
	s_addc_u32 s27, s27, 0
	s_add_i32 s36, s57, s40
	global_load_lds_dwordx4 v[218:219], off
	s_mov_b32 m0, s36
	s_nop 0
	global_load_lds_dwordx4 v2, s[26:27]
	s_add_i32 m0, s36, 0x2000
	s_nop 0
	global_load_lds_dwordx4 v204, s[26:27]
	s_cmp_eq_u32 s55, 60
	s_cbranch_scc0 .Ldefer_1456_body
	v_lshl_add_u64 v[218:219], v[222:223], 0, s[84:85]
	s_mov_b32 m0, s45
	s_nop 0
	global_load_lds_dwordx4 v[218:219], off
	v_lshl_add_u64 v[218:219], v[224:225], 0, s[84:85]
	s_mov_b32 m0, s46
	s_nop 0
	global_load_lds_dwordx4 v[218:219], off

; #define PG8_STAGE(bufoff, gbase, voff) do { _Pragma("unroll") for (int _i = 0; _i < 2; ++_i) \
;         __builtin_amdgcn_global_load_lds((const unsigned*)((const char*)(gbase) + (voff)[_i]), (PG8_LAS unsigned*)(lds + (bufoff) + ldsw + _i * 8192), 16, 0, 0); } while (0)
; #define PG8_LDA(dst, b, h) do { _Pragma("unroll") for (int m = 0; m < 4; ++m) _Pragma("unroll") for (int k = 0; k < 2; ++k) dst[m][k] = *(const PG8_LAS bf16x8*)(lds + PG8_SA(b, h) + aoff + m * 2048 + k * 1024); } while (0)
; #define PG8_LDB(dst, b, h) do { _Pragma("unroll") for (int n = 0; n < 2; ++n) _Pragma("unroll") for (int k = 0; k < 2; ++k) dst[n][k] = *(const PG8_LAS bf16x8*)(lds + PG8_SB(b, h) + boff + n * 2048 + k * 1024); } while (0)
; #define PG8_WAIT_V(n) asm volatile("s_waitcnt vmcnt(" #n ")" ::: "memory")
; #define PG8_WAIT_L(n) asm volatile("s_waitcnt lgkmcnt(" #n ")" ::: "memory")
; #define PG8_BAR __builtin_amdgcn_s_barrier()
; #define PG8_SCHED __builtin_amdgcn_sched_barrier(0)
; template <class Epi, class Sched, bool ALIGN_EPI = false, bool SP2 = false, bool I8 = false>
; __device__ __forceinline__ void gemm_phase(PG8_LAS unsigned char* lds, const Gemm g, const Sched& S, const Epi& E) {
;     ...
;         const bool has_next = S.next(ui + 1, nxt);
;         const char* nA = has_next ? (const char*)g.A + (size_t)nxt.pm * tstep : cA; const char* nB = has_next ? (const char*)g.Bt + (size_t)nxt.pn * tstep : cB;
;         for (int t = 0; t < nt; t += 2) {
;             const bool last = (t == nt - 2);
;             const char* a1 = cA + (size_t)(t + 1) * kstep;
;             const char* a2 = last ? nA : cA + (size_t)(t + 2) * kstep; const char* b2 = last ? nB : cB + (size_t)(t + 2) * kstep;
;             const char* a3 = a2 + kstep; const char* b3 = b2 + kstep;
;             if (last && has_next) S.a_ready(nxt);
;             if constexpr (SP2) {
;             PG8_LDB(B0, 0, 0); PG8_LDB(B1, 0, 1); PG8_SCHED; PG8_LDA(At, 0, 0); PG8_STAGE(PG8_SA(1, 1), a1 + hstep, voffA);
;             PG8_WAIT_V(8); PG8_WAIT_L(0); PG8_BAR; PG8_MMA(0, 0, At, B0); PG8_MMA(0, 1, At, B1); PG8_BAR; PG8_SCHED;
;             PG8_LDA(At, 0, 1); PG8_STAGE(PG8_SB(0, 0), b2, voffB); PG8_STAGE(PG8_SB(0, 1), b2 + hstep, voffB); PG8_STAGE(PG8_SA(0, 0), a2, voffA);
;             PG8_WAIT_V(8); PG8_WAIT_L(0); PG8_BAR; PG8_MMA(1, 0, At, B0); PG8_MMA(1, 1, At, B1); PG8_BAR; PG8_SCHED;
.LBB0_1590:
	s_ashr_i32 s25, s24, 31
	s_lshl_b64 s[26:27], s[24:25], 20
	s_add_u32 s26, s28, s26
	s_addc_u32 s27, s42, s27
	s_and_b64 s[36:37], s[10:11], exec
	s_cselect_b32 s25, s27, s41
	s_cselect_b32 s57, s26, s40
	s_ashr_i32 s23, s22, 31
	s_lshl_b64 s[36:37], s[22:23], 20
	s_add_u32 s36, s43, s36
	s_addc_u32 s37, s46, s37
	s_and_b64 s[48:49], s[10:11], exec
	s_cselect_b32 s23, s37, s45
	s_cselect_b32 s58, s36, s44
	s_add_u32 s40, s40, 0x80080
	s_addc_u32 s41, s41, 0
	s_add_u32 s59, s44, 0x100
	s_addc_u32 s60, s45, 0
	s_mov_b32 s61, -2
	s_add_u32 s44, s40, 0xfff80080
	s_addc_u32 s45, s41, -1
	s_add_i32 s64, 0, 0x10000
	s_cmp_eq_u32 s61, 28
	s_cselect_b32 s49, s25, s45
	s_cselect_b32 s48, s57, s44
	s_cselect_b32 s45, s23, s60
	s_cselect_b32 s44, s58, s59
	s_add_i32 s67, 0, 0x14000
	v_add_u32_e32 v144, s64, v167
	v_add_u32_e32 v158, s67, v167
	ds_read_b128 v[36:39], v144
	ds_read_b128 v[44:47], v144 offset:1024
	ds_read_b128 v[140:143], v144 offset:2048
	ds_read_b128 v[144:147], v144 offset:3072
	ds_read_b128 v[160:163], v158
	ds_read_b128 v[172:175], v158 offset:1024
	ds_read_b128 v[176:179], v158 offset:2048
	ds_read_b128 v[180:183], v158 offset:3072
	s_add_i32 m0, s50, 0xc000
	ds_read_b128 v[184:187], v171
	ds_read_b128 v[188:191], v171 offset:1024
	ds_read_b128 v[204:207], v171 offset:2048
	ds_read_b128 v[208:211], v171 offset:3072
	ds_read_b128 v[212:215], v171 offset:4096
	ds_read_b128 v[216:219], v171 offset:5120
	ds_read_b128 v[220:223], v171 offset:6144
	ds_read_b128 v[224:227], v171 offset:7168
	global_load_lds_dwordx4 v154, s[40:41]
	s_add_i32 m0, s50, 0xe000
	s_nop 0
	global_load_lds_dwordx4 v156, s[40:41]
	s_waitcnt vmcnt(8)
	s_waitcnt lgkmcnt(0)
	s_barrier
	s_setprio 1
	s_waitcnt lgkmcnt(0)
	v_mfma_i32_16x16x64_i8 v[136:139], v[36:39], v[184:187], 0
	v_mfma_i32_16x16x64_i8 v[136:139], v[44:47], v[188:191], v[136:139]
	v_mfma_i32_16x16x64_i8 v[120:123], v[44:47], v[208:211], 0
	v_mfma_i32_16x16x64_i8 v[120:123], v[36:39], v[204:207], v[120:123]
	v_mfma_i32_16x16x64_i8 v[104:107], v[36:39], v[212:215], 0
	v_mfma_i32_16x16x64_i8 v[104:107], v[44:47], v[216:219], v[104:107]
	v_mfma_i32_16x16x64_i8 v[88:91], v[44:47], v[224:227], 0
	v_mfma_i32_16x16x64_i8 v[88:91], v[36:39], v[220:223], v[88:91]
	v_mfma_i32_16x16x64_i8 v[80:83], v[140:143], v[220:223], 0
	v_mfma_i32_16x16x64_i8 v[80:83], v[144:147], v[224:227], v[80:83]
	v_mfma_i32_16x16x64_i8 v[96:99], v[144:147], v[216:219], 0
	v_mfma_i32_16x16x64_i8 v[96:99], v[140:143], v[212:215], v[96:99]
	v_mfma_i32_16x16x64_i8 v[112:115], v[140:143], v[204:207], 0
	v_mfma_i32_16x16x64_i8 v[112:115], v[144:147], v[208:211], v[112:115]
	v_mfma_i32_16x16x64_i8 v[128:131], v[144:147], v[188:191], 0
	v_mfma_i32_16x16x64_i8 v[128:131], v[140:143], v[184:187], v[128:131]
	v_mfma_i32_16x16x64_i8 v[132:135], v[160:163], v[184:187], 0
	v_mfma_i32_16x16x64_i8 v[132:135], v[172:175], v[188:191], v[132:135]
	v_mfma_i32_16x16x64_i8 v[116:119], v[172:175], v[208:211], 0
	v_mfma_i32_16x16x64_i8 v[116:119], v[160:163], v[204:207], v[116:119]
	v_mfma_i32_16x16x64_i8 v[100:103], v[160:163], v[212:215], 0
	v_mfma_i32_16x16x64_i8 v[100:103], v[172:175], v[216:219], v[100:103]
	v_mfma_i32_16x16x64_i8 v[84:87], v[172:175], v[224:227], 0
	v_mfma_i32_16x16x64_i8 v[84:87], v[160:163], v[220:223], v[84:87]
	v_mfma_i32_16x16x64_i8 v[76:79], v[176:179], v[220:223], 0
	v_mfma_i32_16x16x64_i8 v[76:79], v[180:183], v[224:227], v[76:79]
	v_mfma_i32_16x16x64_i8 v[92:95], v[180:183], v[216:219], 0
	v_mfma_i32_16x16x64_i8 v[92:95], v[176:179], v[212:215], v[92:95]
	v_mfma_i32_16x16x64_i8 v[108:111], v[176:179], v[204:207], 0
	v_mfma_i32_16x16x64_i8 v[108:111], v[180:183], v[208:211], v[108:111]
	v_mfma_i32_16x16x64_i8 v[124:127], v[180:183], v[188:191], 0
	v_mfma_i32_16x16x64_i8 v[124:127], v[176:179], v[184:187], v[124:127]
	s_setprio 0
	s_barrier
	s_add_i32 s64, s64, s47
	v_lshl_add_u64 v[164:165], s[44:45], 0, v[2:3]
	s_mov_b32 m0, s64
	ds_read_b128 v[184:187], v171 offset:16384
	ds_read_b128 v[188:191], v171 offset:17408
	ds_read_b128 v[204:207], v171 offset:18432
	ds_read_b128 v[208:211], v171 offset:19456
	ds_read_b128 v[212:215], v171 offset:20480
	ds_read_b128 v[216:219], v171 offset:21504
	ds_read_b128 v[220:223], v171 offset:22528
	ds_read_b128 v[224:227], v171 offset:23552
	global_load_lds_dwordx4 v[164:165], off
	s_add_i32 m0, s64, 0x2000
	s_add_u32 s64, s44, 0x80000
	v_lshl_add_u64 v[228:229], s[44:45], 0, v[148:149]
	s_addc_u32 s65, s45, 0
	s_add_i32 s67, s67, s47
	global_load_lds_dwordx4 v[228:229], off
	s_mov_b32 m0, s67
	v_lshl_add_u64 v[242:243], s[48:49], 0, v[150:151]
	global_load_lds_dwordx4 v2, s[64:65]
	s_add_i32 m0, s67, 0x2000
	s_nop 0
	global_load_lds_dwordx4 v148, s[64:65]
	v_lshl_add_u64 v[240:241], s[48:49], 0, v[152:153]
	s_waitcnt vmcnt(6)
	s_waitcnt lgkmcnt(0)
	s_barrier
; #define PG8_STAGE(bufoff, gbase, voff) do { _Pragma("unroll") for (int _i = 0; _i < 2; ++_i) \
;         __builtin_amdgcn_global_load_lds((const unsigned*)((const char*)(gbase) + (voff)[_i]), (PG8_LAS unsigned*)(lds + (bufoff) + ldsw + _i * 8192), 16, 0, 0); } while (0)
; #define PG8_LDA(dst, b, h) do { _Pragma("unroll") for (int m = 0; m < 4; ++m) _Pragma("unroll") for (int k = 0; k < 2; ++k) dst[m][k] = *(const PG8_LAS bf16x8*)(lds + PG8_SA(b, h) + aoff + m * 2048 + k * 1024); } while (0)
; #define PG8_LDB(dst, b, h) do { _Pragma("unroll") for (int n = 0; n < 2; ++n) _Pragma("unroll") for (int k = 0; k < 2; ++k) dst[n][k] = *(const PG8_LAS bf16x8*)(lds + PG8_SB(b, h) + boff + n * 2048 + k * 1024); } while (0)
; #define PG8_WAIT_V(n) asm volatile("s_waitcnt vmcnt(" #n ")" ::: "memory")
; #define PG8_WAIT_L(n) asm volatile("s_waitcnt lgkmcnt(" #n ")" ::: "memory")
; #define PG8_BAR __builtin_amdgcn_s_barrier()
; #define PG8_SCHED __builtin_amdgcn_sched_barrier(0)
; template <class Epi, class Sched, bool ALIGN_EPI = false, bool SP2 = false, bool I8 = false>
; __device__ __forceinline__ void gemm_phase(PG8_LAS unsigned char* lds, const Gemm g, const Sched& S, const Epi& E) {
;     ...
;             PG8_WAIT_V(8); PG8_WAIT_L(0); PG8_BAR; PG8_MMA(1, 0, At, B0); PG8_MMA(1, 1, At, B1); PG8_BAR; PG8_SCHED;
;             PG8_LDB(B0, 1, 0); PG8_LDB(B1, 1, 1); PG8_SCHED; PG8_LDA(At, 1, 0); PG8_STAGE(PG8_SA(0, 1), a2 + hstep, voffA);
;             PG8_WAIT_V(8); PG8_WAIT_L(0); PG8_BAR; PG8_MMA(0, 0, At, B0); PG8_MMA(0, 1, At, B1); PG8_BAR; PG8_SCHED;
;             PG8_LDA(At, 1, 1); PG8_STAGE(PG8_SB(1, 0), b3, voffB); PG8_STAGE(PG8_SB(1, 1), b3 + hstep, voffB); PG8_STAGE(PG8_SA(1, 0), a3, voffA);
;             PG8_WAIT_V(8); PG8_WAIT_L(0); PG8_BAR; PG8_MMA(1, 0, At, B0); PG8_MMA(1, 1, At, B1); PG8_BAR; PG8_SCHED;
	s_setprio 1
	s_waitcnt lgkmcnt(0)
	v_mfma_i32_16x16x64_i8 v[72:75], v[36:39], v[184:187], 0
	v_mfma_i32_16x16x64_i8 v[72:75], v[44:47], v[188:191], v[72:75]
	v_mfma_i32_16x16x64_i8 v[56:59], v[44:47], v[208:211], 0
	v_mfma_i32_16x16x64_i8 v[56:59], v[36:39], v[204:207], v[56:59]
	v_mfma_i32_16x16x64_i8 v[32:35], v[36:39], v[212:215], 0
	v_mfma_i32_16x16x64_i8 v[32:35], v[44:47], v[216:219], v[32:35]
	v_mfma_i32_16x16x64_i8 v[16:19], v[44:47], v[224:227], 0
	v_mfma_i32_16x16x64_i8 v[16:19], v[36:39], v[220:223], v[16:19]
	v_mfma_i32_16x16x64_i8 v[8:11], v[140:143], v[220:223], 0
	v_mfma_i32_16x16x64_i8 v[8:11], v[144:147], v[224:227], v[8:11]
	v_mfma_i32_16x16x64_i8 v[24:27], v[144:147], v[216:219], 0
	v_mfma_i32_16x16x64_i8 v[24:27], v[140:143], v[212:215], v[24:27]
	v_mfma_i32_16x16x64_i8 v[48:51], v[140:143], v[204:207], 0
	v_mfma_i32_16x16x64_i8 v[48:51], v[144:147], v[208:211], v[48:51]
	v_mfma_i32_16x16x64_i8 v[64:67], v[144:147], v[188:191], 0
	v_mfma_i32_16x16x64_i8 v[64:67], v[140:143], v[184:187], v[64:67]
	v_mfma_i32_16x16x64_i8 v[36:39], v[160:163], v[184:187], 0
	v_mfma_i32_16x16x64_i8 v[36:39], v[172:175], v[188:191], v[36:39]
	v_mfma_i32_16x16x64_i8 v[52:55], v[172:175], v[208:211], 0
	v_mfma_i32_16x16x64_i8 v[52:55], v[160:163], v[204:207], v[52:55]
	v_mfma_i32_16x16x64_i8 v[28:31], v[160:163], v[212:215], 0
	v_mfma_i32_16x16x64_i8 v[28:31], v[172:175], v[216:219], v[28:31]
	v_mfma_i32_16x16x64_i8 v[12:15], v[172:175], v[224:227], 0
	v_mfma_i32_16x16x64_i8 v[12:15], v[160:163], v[220:223], v[12:15]
	v_mfma_i32_16x16x64_i8 v[4:7], v[176:179], v[220:223], 0
	v_mfma_i32_16x16x64_i8 v[4:7], v[180:183], v[224:227], v[4:7]
	v_mfma_i32_16x16x64_i8 v[20:23], v[180:183], v[216:219], 0
	v_mfma_i32_16x16x64_i8 v[20:23], v[176:179], v[212:215], v[20:23]
	v_mfma_i32_16x16x64_i8 v[40:43], v[176:179], v[204:207], 0
	v_mfma_i32_16x16x64_i8 v[40:43], v[180:183], v[208:211], v[40:43]
	v_mfma_i32_16x16x64_i8 v[44:47], v[180:183], v[188:191], 0
	v_mfma_i32_16x16x64_i8 v[44:47], v[176:179], v[184:187], v[44:47]
	s_setprio 0
	s_barrier
	s_mov_b32 m0, s50
	s_nop 0
	global_load_lds_dwordx4 v[240:241], off
	s_mov_b32 m0, s51
	s_nop 0
	global_load_lds_dwordx4 v[242:243], off
	s_add_i32 s64, 0, 0x18000
	s_add_i32 s65, 0, 0x1c000
	v_add_u32_e32 v144, s64, v167
	v_add_u32_e32 v158, s65, v167
	ds_read_b128 v[60:63], v144
	ds_read_b128 v[68:71], v144 offset:1024
	ds_read_b128 v[140:143], v144 offset:2048
	ds_read_b128 v[144:147], v144 offset:3072
	ds_read_b128 v[160:163], v158
	ds_read_b128 v[172:175], v158 offset:1024
	ds_read_b128 v[176:179], v158 offset:2048
	ds_read_b128 v[180:183], v158 offset:3072
	s_add_u32 s48, s48, 0x80000
	s_addc_u32 s49, s49, 0
	s_mov_b32 m0, s52
	ds_read_b128 v[184:187], v171 offset:32768
	ds_read_b128 v[188:191], v171 offset:33792
	ds_read_b128 v[204:207], v171 offset:34816
	ds_read_b128 v[208:211], v171 offset:35840
	ds_read_b128 v[212:215], v171 offset:36864
	ds_read_b128 v[216:219], v171 offset:37888
	ds_read_b128 v[220:223], v171 offset:38912
	ds_read_b128 v[224:227], v171 offset:39936
	global_load_lds_dwordx4 v152, s[48:49]
	s_mov_b32 m0, s53
	s_nop 0
	global_load_lds_dwordx4 v150, s[48:49]
	s_waitcnt vmcnt(8)
	s_waitcnt lgkmcnt(0)
	s_barrier
	s_setprio 1
	s_waitcnt lgkmcnt(0)
	v_mfma_i32_16x16x64_i8 v[136:139], v[60:63], v[184:187], v[136:139]
	v_mfma_i32_16x16x64_i8 v[136:139], v[68:71], v[188:191], v[136:139]
	v_mfma_i32_16x16x64_i8 v[120:123], v[68:71], v[208:211], v[120:123]
	v_mfma_i32_16x16x64_i8 v[120:123], v[60:63], v[204:207], v[120:123]
	v_mfma_i32_16x16x64_i8 v[104:107], v[60:63], v[212:215], v[104:107]
	v_mfma_i32_16x16x64_i8 v[104:107], v[68:71], v[216:219], v[104:107]
	v_mfma_i32_16x16x64_i8 v[88:91], v[68:71], v[224:227], v[88:91]
	v_mfma_i32_16x16x64_i8 v[88:91], v[60:63], v[220:223], v[88:91]
	v_mfma_i32_16x16x64_i8 v[80:83], v[140:143], v[220:223], v[80:83]
	v_mfma_i32_16x16x64_i8 v[80:83], v[144:147], v[224:227], v[80:83]
	v_mfma_i32_16x16x64_i8 v[96:99], v[144:147], v[216:219], v[96:99]
	v_mfma_i32_16x16x64_i8 v[96:99], v[140:143], v[212:215], v[96:99]
	v_mfma_i32_16x16x64_i8 v[112:115], v[140:143], v[204:207], v[112:115]
	v_mfma_i32_16x16x64_i8 v[112:115], v[144:147], v[208:211], v[112:115]
	v_mfma_i32_16x16x64_i8 v[128:131], v[144:147], v[188:191], v[128:131]
	v_mfma_i32_16x16x64_i8 v[128:131], v[140:143], v[184:187], v[128:131]
	v_mfma_i32_16x16x64_i8 v[132:135], v[160:163], v[184:187], v[132:135]
	v_mfma_i32_16x16x64_i8 v[132:135], v[172:175], v[188:191], v[132:135]
	v_mfma_i32_16x16x64_i8 v[116:119], v[172:175], v[208:211], v[116:119]
	v_mfma_i32_16x16x64_i8 v[116:119], v[160:163], v[204:207], v[116:119]
	v_mfma_i32_16x16x64_i8 v[100:103], v[160:163], v[212:215], v[100:103]
	v_mfma_i32_16x16x64_i8 v[100:103], v[172:175], v[216:219], v[100:103]
	v_mfma_i32_16x16x64_i8 v[84:87], v[172:175], v[224:227], v[84:87]
	v_mfma_i32_16x16x64_i8 v[84:87], v[160:163], v[220:223], v[84:87]
	v_mfma_i32_16x16x64_i8 v[76:79], v[176:179], v[220:223], v[76:79]
	v_mfma_i32_16x16x64_i8 v[76:79], v[180:183], v[224:227], v[76:79]
	v_mfma_i32_16x16x64_i8 v[92:95], v[180:183], v[216:219], v[92:95]
	v_mfma_i32_16x16x64_i8 v[92:95], v[176:179], v[212:215], v[92:95]
	v_mfma_i32_16x16x64_i8 v[108:111], v[176:179], v[204:207], v[108:111]
	v_mfma_i32_16x16x64_i8 v[108:111], v[180:183], v[208:211], v[108:111]
	v_mfma_i32_16x16x64_i8 v[124:127], v[180:183], v[188:191], v[124:127]
	v_mfma_i32_16x16x64_i8 v[124:127], v[176:179], v[184:187], v[124:127]
	s_setprio 0
	s_barrier
	s_add_i32 s48, s64, s47
	v_lshl_add_u64 v[164:165], v[164:165], 0, s[84:85]
	s_mov_b32 m0, s48
	ds_read_b128 v[184:187], v171 offset:49152
	ds_read_b128 v[188:191], v171 offset:50176
	ds_read_b128 v[204:207], v171 offset:51200
	ds_read_b128 v[208:211], v171 offset:52224
	ds_read_b128 v[212:215], v171 offset:53248
	ds_read_b128 v[216:219], v171 offset:54272
	ds_read_b128 v[220:223], v171 offset:55296
	ds_read_b128 v[224:227], v171 offset:56320
	global_load_lds_dwordx4 v[164:165], off
	s_add_i32 m0, s48, 0x2000
	s_add_u32 s44, s44, 0x80080
	v_lshl_add_u64 v[164:165], v[228:229], 0, s[84:85]
	s_addc_u32 s45, s45, 0
	s_add_i32 s48, s65, s47
	global_load_lds_dwordx4 v[164:165], off
	s_mov_b32 m0, s48
	s_nop 0
	global_load_lds_dwordx4 v2, s[44:45]
	s_add_i32 m0, s48, 0x2000
	s_nop 0
	global_load_lds_dwordx4 v148, s[44:45]
	s_cmp_eq_u32 s61, 28
	s_cbranch_scc0 .Ldefer_1591_peel
	v_lshl_add_u64 v[164:165], v[240:241], 0, s[84:85]
	s_mov_b32 m0, s54
	s_nop 0
	global_load_lds_dwordx4 v[164:165], off
	v_lshl_add_u64 v[164:165], v[242:243], 0, s[84:85]
	s_mov_b32 m0, s55
	s_nop 0
	global_load_lds_dwordx4 v[164:165], off

; #define PG8_STAGE(bufoff, gbase, voff) do { _Pragma("unroll") for (int _i = 0; _i < 2; ++_i) \
;         __builtin_amdgcn_global_load_lds((const unsigned*)((const char*)(gbase) + (voff)[_i]), (PG8_LAS unsigned*)(lds + (bufoff) + ldsw + _i * 8192), 16, 0, 0); } while (0)
; #define PG8_LDA(dst, b, h) do { _Pragma("unroll") for (int m = 0; m < 4; ++m) _Pragma("unroll") for (int k = 0; k < 2; ++k) dst[m][k] = *(const PG8_LAS bf16x8*)(lds + PG8_SA(b, h) + aoff + m * 2048 + k * 1024); } while (0)
; #define PG8_LDB(dst, b, h) do { _Pragma("unroll") for (int n = 0; n < 2; ++n) _Pragma("unroll") for (int k = 0; k < 2; ++k) dst[n][k] = *(const PG8_LAS bf16x8*)(lds + PG8_SB(b, h) + boff + n * 2048 + k * 1024); } while (0)
; #define PG8_WAIT_V(n) asm volatile("s_waitcnt vmcnt(" #n ")" ::: "memory")
; #define PG8_WAIT_L(n) asm volatile("s_waitcnt lgkmcnt(" #n ")" ::: "memory")
; #define PG8_BAR __builtin_amdgcn_s_barrier()
; #define PG8_SCHED __builtin_amdgcn_sched_barrier(0)
; template <class Epi, class Sched, bool ALIGN_EPI = false, bool SP2 = false, bool I8 = false>
; __device__ __forceinline__ void gemm_phase(PG8_LAS unsigned char* lds, const Gemm g, const Sched& S, const Epi& E) {
;     ...
;             const bool last = (t == nt - 2);
;             const char* a1 = cA + (size_t)(t + 1) * kstep;
;             const char* a2 = last ? nA : cA + (size_t)(t + 2) * kstep; const char* b2 = last ? nB : cB + (size_t)(t + 2) * kstep;
;             const char* a3 = a2 + kstep; const char* b3 = b2 + kstep;
;             if (last && has_next) S.a_ready(nxt);
;             if constexpr (SP2) {
;             PG8_LDB(B0, 0, 0); PG8_LDB(B1, 0, 1); PG8_SCHED; PG8_LDA(At, 0, 0); PG8_STAGE(PG8_SA(1, 1), a1 + hstep, voffA);
;             PG8_WAIT_V(8); PG8_WAIT_L(0); PG8_BAR; PG8_MMA(0, 0, At, B0); PG8_MMA(0, 1, At, B1); PG8_BAR; PG8_SCHED;
;             PG8_LDA(At, 0, 1); PG8_STAGE(PG8_SB(0, 0), b2, voffB); PG8_STAGE(PG8_SB(0, 1), b2 + hstep, voffB); PG8_STAGE(PG8_SA(0, 0), a2, voffA);
;             PG8_WAIT_V(8); PG8_WAIT_L(0); PG8_BAR; PG8_MMA(1, 0, At, B0); PG8_MMA(1, 1, At, B1); PG8_BAR; PG8_SCHED;
.LBB0_1591:
	s_add_u32 s44, s40, 0xfff80080
	s_addc_u32 s45, s41, -1
	s_add_i32 s64, 0, 0x10000
	s_cmp_eq_u32 s61, 28
	s_cselect_b32 s49, s25, s45
	s_cselect_b32 s48, s57, s44
	s_cselect_b32 s45, s23, s60
	s_cselect_b32 s44, s58, s59
	s_add_i32 s67, 0, 0x14000
	v_add_u32_e32 v144, s64, v167
	v_add_u32_e32 v158, s67, v167
	ds_read_b128 v[36:39], v144
	ds_read_b128 v[44:47], v144 offset:1024
	ds_read_b128 v[140:143], v144 offset:2048
	ds_read_b128 v[144:147], v144 offset:3072
	ds_read_b128 v[160:163], v158
	ds_read_b128 v[172:175], v158 offset:1024
	ds_read_b128 v[176:179], v158 offset:2048
	ds_read_b128 v[180:183], v158 offset:3072
	v_lshl_add_u64 v[164:165], v[240:241], 0, s[84:85]
	s_mov_b32 m0, s54
	s_nop 0
	global_load_lds_dwordx4 v[164:165], off
	v_lshl_add_u64 v[164:165], v[242:243], 0, s[84:85]
	s_mov_b32 m0, s55
	s_nop 0
	global_load_lds_dwordx4 v[164:165], off
	s_add_i32 m0, s50, 0xc000
	ds_read_b128 v[184:187], v171
	ds_read_b128 v[188:191], v171 offset:1024
	ds_read_b128 v[204:207], v171 offset:2048
	ds_read_b128 v[208:211], v171 offset:3072
	ds_read_b128 v[212:215], v171 offset:4096
	ds_read_b128 v[216:219], v171 offset:5120
	ds_read_b128 v[220:223], v171 offset:6144
	ds_read_b128 v[224:227], v171 offset:7168
	global_load_lds_dwordx4 v154, s[40:41]
	s_add_i32 m0, s50, 0xe000
	s_nop 0
	global_load_lds_dwordx4 v156, s[40:41]
	s_waitcnt vmcnt(8)
	s_waitcnt lgkmcnt(0)
	s_barrier
	s_setprio 1
	s_waitcnt lgkmcnt(0)
	v_mfma_i32_16x16x64_i8 v[136:139], v[36:39], v[184:187], v[136:139]
	v_mfma_i32_16x16x64_i8 v[136:139], v[44:47], v[188:191], v[136:139]
	v_mfma_i32_16x16x64_i8 v[120:123], v[44:47], v[208:211], v[120:123]
	v_mfma_i32_16x16x64_i8 v[120:123], v[36:39], v[204:207], v[120:123]
	v_mfma_i32_16x16x64_i8 v[104:107], v[36:39], v[212:215], v[104:107]
	v_mfma_i32_16x16x64_i8 v[104:107], v[44:47], v[216:219], v[104:107]
	v_mfma_i32_16x16x64_i8 v[88:91], v[44:47], v[224:227], v[88:91]
	v_mfma_i32_16x16x64_i8 v[88:91], v[36:39], v[220:223], v[88:91]
	v_mfma_i32_16x16x64_i8 v[80:83], v[140:143], v[220:223], v[80:83]
	v_mfma_i32_16x16x64_i8 v[80:83], v[144:147], v[224:227], v[80:83]
	v_mfma_i32_16x16x64_i8 v[96:99], v[144:147], v[216:219], v[96:99]
	v_mfma_i32_16x16x64_i8 v[96:99], v[140:143], v[212:215], v[96:99]
	v_mfma_i32_16x16x64_i8 v[112:115], v[140:143], v[204:207], v[112:115]
	v_mfma_i32_16x16x64_i8 v[112:115], v[144:147], v[208:211], v[112:115]
	v_mfma_i32_16x16x64_i8 v[128:131], v[144:147], v[188:191], v[128:131]
	v_mfma_i32_16x16x64_i8 v[128:131], v[140:143], v[184:187], v[128:131]
	v_mfma_i32_16x16x64_i8 v[132:135], v[160:163], v[184:187], v[132:135]
	v_mfma_i32_16x16x64_i8 v[132:135], v[172:175], v[188:191], v[132:135]
	v_mfma_i32_16x16x64_i8 v[116:119], v[172:175], v[208:211], v[116:119]
	v_mfma_i32_16x16x64_i8 v[116:119], v[160:163], v[204:207], v[116:119]
	v_mfma_i32_16x16x64_i8 v[100:103], v[160:163], v[212:215], v[100:103]
	v_mfma_i32_16x16x64_i8 v[100:103], v[172:175], v[216:219], v[100:103]
	v_mfma_i32_16x16x64_i8 v[84:87], v[172:175], v[224:227], v[84:87]
	v_mfma_i32_16x16x64_i8 v[84:87], v[160:163], v[220:223], v[84:87]
	v_mfma_i32_16x16x64_i8 v[76:79], v[176:179], v[220:223], v[76:79]
	v_mfma_i32_16x16x64_i8 v[76:79], v[180:183], v[224:227], v[76:79]
	v_mfma_i32_16x16x64_i8 v[92:95], v[180:183], v[216:219], v[92:95]
	v_mfma_i32_16x16x64_i8 v[92:95], v[176:179], v[212:215], v[92:95]
	v_mfma_i32_16x16x64_i8 v[108:111], v[176:179], v[204:207], v[108:111]
	v_mfma_i32_16x16x64_i8 v[108:111], v[180:183], v[208:211], v[108:111]
	v_mfma_i32_16x16x64_i8 v[124:127], v[180:183], v[188:191], v[124:127]
	v_mfma_i32_16x16x64_i8 v[124:127], v[176:179], v[184:187], v[124:127]
	s_setprio 0
	s_barrier
	s_add_i32 s64, s64, s47
	v_lshl_add_u64 v[164:165], s[44:45], 0, v[2:3]
	s_mov_b32 m0, s64
	ds_read_b128 v[184:187], v171 offset:16384
	ds_read_b128 v[188:191], v171 offset:17408
	ds_read_b128 v[204:207], v171 offset:18432
	ds_read_b128 v[208:211], v171 offset:19456
	ds_read_b128 v[212:215], v171 offset:20480
	ds_read_b128 v[216:219], v171 offset:21504
	ds_read_b128 v[220:223], v171 offset:22528
	ds_read_b128 v[224:227], v171 offset:23552
	global_load_lds_dwordx4 v[164:165], off
	s_add_i32 m0, s64, 0x2000
	s_add_u32 s64, s44, 0x80000
	v_lshl_add_u64 v[228:229], s[44:45], 0, v[148:149]
	s_addc_u32 s65, s45, 0
	s_add_i32 s67, s67, s47
	global_load_lds_dwordx4 v[228:229], off
	s_mov_b32 m0, s67
	v_lshl_add_u64 v[242:243], s[48:49], 0, v[150:151]
	global_load_lds_dwordx4 v2, s[64:65]
	s_add_i32 m0, s67, 0x2000
	s_nop 0
	global_load_lds_dwordx4 v148, s[64:65]
	v_lshl_add_u64 v[240:241], s[48:49], 0, v[152:153]
	s_waitcnt vmcnt(6)
	s_waitcnt lgkmcnt(0)
	s_barrier
; #define PG8_STAGE(bufoff, gbase, voff) do { _Pragma("unroll") for (int _i = 0; _i < 2; ++_i) \
;         __builtin_amdgcn_global_load_lds((const unsigned*)((const char*)(gbase) + (voff)[_i]), (PG8_LAS unsigned*)(lds + (bufoff) + ldsw + _i * 8192), 16, 0, 0); } while (0)
; #define PG8_LDA(dst, b, h) do { _Pragma("unroll") for (int m = 0; m < 4; ++m) _Pragma("unroll") for (int k = 0; k < 2; ++k) dst[m][k] = *(const PG8_LAS bf16x8*)(lds + PG8_SA(b, h) + aoff + m * 2048 + k * 1024); } while (0)
; #define PG8_LDB(dst, b, h) do { _Pragma("unroll") for (int n = 0; n < 2; ++n) _Pragma("unroll") for (int k = 0; k < 2; ++k) dst[n][k] = *(const PG8_LAS bf16x8*)(lds + PG8_SB(b, h) + boff + n * 2048 + k * 1024); } while (0)
; #define PG8_WAIT_V(n) asm volatile("s_waitcnt vmcnt(" #n ")" ::: "memory")
; #define PG8_WAIT_L(n) asm volatile("s_waitcnt lgkmcnt(" #n ")" ::: "memory")
; #define PG8_BAR __builtin_amdgcn_s_barrier()
; #define PG8_SCHED __builtin_amdgcn_sched_barrier(0)
; template <class Epi, class Sched, bool ALIGN_EPI = false, bool SP2 = false, bool I8 = false>
; __device__ __forceinline__ void gemm_phase(PG8_LAS unsigned char* lds, const Gemm g, const Sched& S, const Epi& E) {
;     ...
;             PG8_WAIT_V(8); PG8_WAIT_L(0); PG8_BAR; PG8_MMA(1, 0, At, B0); PG8_MMA(1, 1, At, B1); PG8_BAR; PG8_SCHED;
;             PG8_LDB(B0, 1, 0); PG8_LDB(B1, 1, 1); PG8_SCHED; PG8_LDA(At, 1, 0); PG8_STAGE(PG8_SA(0, 1), a2 + hstep, voffA);
;             PG8_WAIT_V(8); PG8_WAIT_L(0); PG8_BAR; PG8_MMA(0, 0, At, B0); PG8_MMA(0, 1, At, B1); PG8_BAR; PG8_SCHED;
;             PG8_LDA(At, 1, 1); PG8_STAGE(PG8_SB(1, 0), b3, voffB); PG8_STAGE(PG8_SB(1, 1), b3 + hstep, voffB); PG8_STAGE(PG8_SA(1, 0), a3, voffA);
;             PG8_WAIT_V(8); PG8_WAIT_L(0); PG8_BAR; PG8_MMA(1, 0, At, B0); PG8_MMA(1, 1, At, B1); PG8_BAR; PG8_SCHED;
	s_setprio 1
	s_waitcnt lgkmcnt(0)
	v_mfma_i32_16x16x64_i8 v[72:75], v[36:39], v[184:187], v[72:75]
	v_mfma_i32_16x16x64_i8 v[72:75], v[44:47], v[188:191], v[72:75]
	v_mfma_i32_16x16x64_i8 v[56:59], v[44:47], v[208:211], v[56:59]
	v_mfma_i32_16x16x64_i8 v[56:59], v[36:39], v[204:207], v[56:59]
	v_mfma_i32_16x16x64_i8 v[32:35], v[36:39], v[212:215], v[32:35]
	v_mfma_i32_16x16x64_i8 v[32:35], v[44:47], v[216:219], v[32:35]
	v_mfma_i32_16x16x64_i8 v[16:19], v[44:47], v[224:227], v[16:19]
	v_mfma_i32_16x16x64_i8 v[16:19], v[36:39], v[220:223], v[16:19]
	v_mfma_i32_16x16x64_i8 v[8:11], v[140:143], v[220:223], v[8:11]
	v_mfma_i32_16x16x64_i8 v[8:11], v[144:147], v[224:227], v[8:11]
	v_mfma_i32_16x16x64_i8 v[24:27], v[144:147], v[216:219], v[24:27]
	v_mfma_i32_16x16x64_i8 v[24:27], v[140:143], v[212:215], v[24:27]
	v_mfma_i32_16x16x64_i8 v[48:51], v[140:143], v[204:207], v[48:51]
	v_mfma_i32_16x16x64_i8 v[48:51], v[144:147], v[208:211], v[48:51]
	v_mfma_i32_16x16x64_i8 v[64:67], v[144:147], v[188:191], v[64:67]
	v_mfma_i32_16x16x64_i8 v[64:67], v[140:143], v[184:187], v[64:67]
	v_mfma_i32_16x16x64_i8 v[36:39], v[160:163], v[184:187], v[68:71]
	v_mfma_i32_16x16x64_i8 v[36:39], v[172:175], v[188:191], v[36:39]
	v_mfma_i32_16x16x64_i8 v[52:55], v[172:175], v[208:211], v[52:55]
	v_mfma_i32_16x16x64_i8 v[52:55], v[160:163], v[204:207], v[52:55]
	v_mfma_i32_16x16x64_i8 v[28:31], v[160:163], v[212:215], v[28:31]
	v_mfma_i32_16x16x64_i8 v[28:31], v[172:175], v[216:219], v[28:31]
	v_mfma_i32_16x16x64_i8 v[12:15], v[172:175], v[224:227], v[12:15]
	v_mfma_i32_16x16x64_i8 v[12:15], v[160:163], v[220:223], v[12:15]
	v_mfma_i32_16x16x64_i8 v[4:7], v[176:179], v[220:223], v[4:7]
	v_mfma_i32_16x16x64_i8 v[4:7], v[180:183], v[224:227], v[4:7]
	v_mfma_i32_16x16x64_i8 v[20:23], v[180:183], v[216:219], v[20:23]
	v_mfma_i32_16x16x64_i8 v[20:23], v[176:179], v[212:215], v[20:23]
	v_mfma_i32_16x16x64_i8 v[40:43], v[176:179], v[204:207], v[40:43]
	v_mfma_i32_16x16x64_i8 v[40:43], v[180:183], v[208:211], v[40:43]
	v_mfma_i32_16x16x64_i8 v[44:47], v[180:183], v[188:191], v[60:63]
	v_mfma_i32_16x16x64_i8 v[44:47], v[176:179], v[184:187], v[44:47]
	s_setprio 0
	s_barrier
	s_mov_b32 m0, s50
	s_nop 0
	global_load_lds_dwordx4 v[240:241], off
	s_mov_b32 m0, s51
	s_nop 0
	global_load_lds_dwordx4 v[242:243], off
	s_add_i32 s64, 0, 0x18000
	s_add_i32 s65, 0, 0x1c000
	v_add_u32_e32 v144, s64, v167
	v_add_u32_e32 v158, s65, v167
	ds_read_b128 v[60:63], v144
	ds_read_b128 v[68:71], v144 offset:1024
	ds_read_b128 v[140:143], v144 offset:2048
	ds_read_b128 v[144:147], v144 offset:3072
	ds_read_b128 v[160:163], v158
	ds_read_b128 v[172:175], v158 offset:1024
	ds_read_b128 v[176:179], v158 offset:2048
	ds_read_b128 v[180:183], v158 offset:3072
	s_add_u32 s48, s48, 0x80000
	s_addc_u32 s49, s49, 0
	s_mov_b32 m0, s52
	ds_read_b128 v[184:187], v171 offset:32768
	ds_read_b128 v[188:191], v171 offset:33792
	ds_read_b128 v[204:207], v171 offset:34816
	ds_read_b128 v[208:211], v171 offset:35840
	ds_read_b128 v[212:215], v171 offset:36864
	ds_read_b128 v[216:219], v171 offset:37888
	ds_read_b128 v[220:223], v171 offset:38912
	ds_read_b128 v[224:227], v171 offset:39936
	global_load_lds_dwordx4 v152, s[48:49]
	s_mov_b32 m0, s53
	s_nop 0
	global_load_lds_dwordx4 v150, s[48:49]
	s_waitcnt vmcnt(8)
	s_waitcnt lgkmcnt(0)
	s_barrier
	s_setprio 1
	s_waitcnt lgkmcnt(0)
	v_mfma_i32_16x16x64_i8 v[136:139], v[60:63], v[184:187], v[136:139]
	v_mfma_i32_16x16x64_i8 v[136:139], v[68:71], v[188:191], v[136:139]
	v_mfma_i32_16x16x64_i8 v[120:123], v[68:71], v[208:211], v[120:123]
	v_mfma_i32_16x16x64_i8 v[120:123], v[60:63], v[204:207], v[120:123]
	v_mfma_i32_16x16x64_i8 v[104:107], v[60:63], v[212:215], v[104:107]
	v_mfma_i32_16x16x64_i8 v[104:107], v[68:71], v[216:219], v[104:107]
	v_mfma_i32_16x16x64_i8 v[88:91], v[68:71], v[224:227], v[88:91]
	v_mfma_i32_16x16x64_i8 v[88:91], v[60:63], v[220:223], v[88:91]
	v_mfma_i32_16x16x64_i8 v[80:83], v[140:143], v[220:223], v[80:83]
	v_mfma_i32_16x16x64_i8 v[80:83], v[144:147], v[224:227], v[80:83]
	v_mfma_i32_16x16x64_i8 v[96:99], v[144:147], v[216:219], v[96:99]
	v_mfma_i32_16x16x64_i8 v[96:99], v[140:143], v[212:215], v[96:99]
	v_mfma_i32_16x16x64_i8 v[112:115], v[140:143], v[204:207], v[112:115]
	v_mfma_i32_16x16x64_i8 v[112:115], v[144:147], v[208:211], v[112:115]
	v_mfma_i32_16x16x64_i8 v[128:131], v[144:147], v[188:191], v[128:131]
	v_mfma_i32_16x16x64_i8 v[128:131], v[140:143], v[184:187], v[128:131]
	v_mfma_i32_16x16x64_i8 v[132:135], v[160:163], v[184:187], v[132:135]
	v_mfma_i32_16x16x64_i8 v[132:135], v[172:175], v[188:191], v[132:135]
	v_mfma_i32_16x16x64_i8 v[116:119], v[172:175], v[208:211], v[116:119]
	v_mfma_i32_16x16x64_i8 v[116:119], v[160:163], v[204:207], v[116:119]
	v_mfma_i32_16x16x64_i8 v[100:103], v[160:163], v[212:215], v[100:103]
	v_mfma_i32_16x16x64_i8 v[100:103], v[172:175], v[216:219], v[100:103]
	v_mfma_i32_16x16x64_i8 v[84:87], v[172:175], v[224:227], v[84:87]
	v_mfma_i32_16x16x64_i8 v[84:87], v[160:163], v[220:223], v[84:87]
	v_mfma_i32_16x16x64_i8 v[76:79], v[176:179], v[220:223], v[76:79]
	v_mfma_i32_16x16x64_i8 v[76:79], v[180:183], v[224:227], v[76:79]
	v_mfma_i32_16x16x64_i8 v[92:95], v[180:183], v[216:219], v[92:95]
	v_mfma_i32_16x16x64_i8 v[92:95], v[176:179], v[212:215], v[92:95]
	v_mfma_i32_16x16x64_i8 v[108:111], v[176:179], v[204:207], v[108:111]
	v_mfma_i32_16x16x64_i8 v[108:111], v[180:183], v[208:211], v[108:111]
	v_mfma_i32_16x16x64_i8 v[124:127], v[180:183], v[188:191], v[124:127]
	v_mfma_i32_16x16x64_i8 v[124:127], v[176:179], v[184:187], v[124:127]
	s_setprio 0
	s_barrier
	s_add_i32 s48, s64, s47
	v_lshl_add_u64 v[164:165], v[164:165], 0, s[84:85]
	s_mov_b32 m0, s48
	ds_read_b128 v[184:187], v171 offset:49152
	ds_read_b128 v[188:191], v171 offset:50176
	ds_read_b128 v[204:207], v171 offset:51200
	ds_read_b128 v[208:211], v171 offset:52224
	ds_read_b128 v[212:215], v171 offset:53248
	ds_read_b128 v[216:219], v171 offset:54272
	ds_read_b128 v[220:223], v171 offset:55296
	ds_read_b128 v[224:227], v171 offset:56320
	global_load_lds_dwordx4 v[164:165], off
	s_add_i32 m0, s48, 0x2000
	s_add_u32 s44, s44, 0x80080
	v_lshl_add_u64 v[164:165], v[228:229], 0, s[84:85]
	s_addc_u32 s45, s45, 0
	s_add_i32 s48, s65, s47
	global_load_lds_dwordx4 v[164:165], off
	s_mov_b32 m0, s48
	s_nop 0
	global_load_lds_dwordx4 v2, s[44:45]
	s_add_i32 m0, s48, 0x2000
	s_nop 0
	global_load_lds_dwordx4 v148, s[44:45]
	s_cmp_eq_u32 s61, 28
	s_cbranch_scc0 .Ldefer_1591_body
	v_lshl_add_u64 v[164:165], v[240:241], 0, s[84:85]
	s_mov_b32 m0, s54
	s_nop 0
	global_load_lds_dwordx4 v[164:165], off
	v_lshl_add_u64 v[164:165], v[242:243], 0, s[84:85]
	s_mov_b32 m0, s55
	s_nop 0
	global_load_lds_dwordx4 v[164:165], off

; #define PG8_STAGE(bufoff, gbase, voff) do { _Pragma("unroll") for (int _i = 0; _i < 2; ++_i) \
;         __builtin_amdgcn_global_load_lds((const unsigned*)((const char*)(gbase) + (voff)[_i]), (PG8_LAS unsigned*)(lds + (bufoff) + ldsw + _i * 8192), 16, 0, 0); } while (0)
; #define PG8_LDA(dst, b, h) do { _Pragma("unroll") for (int m = 0; m < 4; ++m) _Pragma("unroll") for (int k = 0; k < 2; ++k) dst[m][k] = *(const PG8_LAS bf16x8*)(lds + PG8_SA(b, h) + aoff + m * 2048 + k * 1024); } while (0)
; #define PG8_LDB(dst, b, h) do { _Pragma("unroll") for (int n = 0; n < 2; ++n) _Pragma("unroll") for (int k = 0; k < 2; ++k) dst[n][k] = *(const PG8_LAS bf16x8*)(lds + PG8_SB(b, h) + boff + n * 2048 + k * 1024); } while (0)
; #define PG8_WAIT_V(n) asm volatile("s_waitcnt vmcnt(" #n ")" ::: "memory")
; #define PG8_WAIT_L(n) asm volatile("s_waitcnt lgkmcnt(" #n ")" ::: "memory")
; #define PG8_BAR __builtin_amdgcn_s_barrier()
; #define PG8_SCHED __builtin_amdgcn_sched_barrier(0)
; template <class Epi, class Sched, bool ALIGN_EPI = false, bool SP2 = false, bool I8 = false>
; __device__ __forceinline__ void gemm_phase(PG8_LAS unsigned char* lds, const Gemm g, const Sched& S, const Epi& E) {
;     ...
;         for (int t = 0; t < nt; t += 2) {
;             const bool last = (t == nt - 2);
;             const char* a1 = cA + (size_t)(t + 1) * kstep;
;             const char* a2 = last ? nA : cA + (size_t)(t + 2) * kstep; const char* b2 = last ? nB : cB + (size_t)(t + 2) * kstep;
;             const char* a3 = a2 + kstep; const char* b3 = b2 + kstep;
;             if (last && has_next) S.a_ready(nxt);
;             if constexpr (SP2) {
;             PG8_LDB(B0, 0, 0); PG8_LDB(B1, 0, 1); PG8_SCHED; PG8_LDA(At, 0, 0); PG8_STAGE(PG8_SA(1, 1), a1 + hstep, voffA);
;             PG8_WAIT_V(8); PG8_WAIT_L(0); PG8_BAR; PG8_MMA(0, 0, At, B0); PG8_MMA(0, 1, At, B1); PG8_BAR; PG8_SCHED;
;     ...
; #pragma unroll
;         for (int a = 0; a < 2; ++a)
; #pragma unroll
;             for (int b = 0; b < 2; ++b)
; #pragma unroll
;                 for (int m = 0; m < 4; ++m)
; #pragma unroll
;                     for (int n = 0; n < 2; ++n) acc[a][b][m][n] = (acc_t){0, 0, 0, 0};
;         cur = nxt; cA = nA; cB = nB; ++ui;
.LBB0_1621:
	v_mov_b32_e32 v127, 0
	s_andn2_b64 vcc, exec, s[26:27]
	v_mov_b32_e32 v126, v127
	v_mov_b32_e32 v125, v127
	v_mov_b32_e32 v124, v127
	v_mov_b32_e32 v131, v127
	v_mov_b32_e32 v130, v127
	v_mov_b32_e32 v129, v127
	v_mov_b32_e32 v128, v127
	v_mov_b32_e32 v115, v127
	v_mov_b32_e32 v114, v127
	v_mov_b32_e32 v113, v127
	v_mov_b32_e32 v112, v127
	v_mov_b32_e32 v111, v127
	v_mov_b32_e32 v110, v127
	v_mov_b32_e32 v109, v127
	v_mov_b32_e32 v108, v127
	v_mov_b32_e32 v99, v127
	v_mov_b32_e32 v98, v127
	v_mov_b32_e32 v97, v127
	v_mov_b32_e32 v96, v127
	v_mov_b32_e32 v95, v127
	v_mov_b32_e32 v94, v127
	v_mov_b32_e32 v93, v127
	v_mov_b32_e32 v92, v127
	v_mov_b32_e32 v83, v127
	v_mov_b32_e32 v82, v127
	v_mov_b32_e32 v81, v127
	v_mov_b32_e32 v80, v127
	v_mov_b32_e32 v79, v127
	v_mov_b32_e32 v78, v127
	v_mov_b32_e32 v77, v127
	v_mov_b32_e32 v76, v127
	v_mov_b32_e32 v123, v127
	v_mov_b32_e32 v122, v127
	v_mov_b32_e32 v121, v127
	v_mov_b32_e32 v120, v127
	v_mov_b32_e32 v119, v127
	v_mov_b32_e32 v118, v127
	v_mov_b32_e32 v117, v127
	v_mov_b32_e32 v116, v127
	v_mov_b32_e32 v107, v127
	v_mov_b32_e32 v106, v127
	v_mov_b32_e32 v105, v127
	v_mov_b32_e32 v104, v127
	v_mov_b32_e32 v103, v127
	v_mov_b32_e32 v102, v127
	v_mov_b32_e32 v101, v127
	v_mov_b32_e32 v100, v127
	v_mov_b32_e32 v91, v127
	v_mov_b32_e32 v90, v127
	v_mov_b32_e32 v89, v127
	v_mov_b32_e32 v88, v127
	v_mov_b32_e32 v87, v127
	v_mov_b32_e32 v86, v127
	v_mov_b32_e32 v85, v127
	v_mov_b32_e32 v84, v127
	v_mov_b32_e32 v75, v127
	v_mov_b32_e32 v74, v127
	v_mov_b32_e32 v73, v127
	v_mov_b32_e32 v72, v127
	v_mov_b32_e32 v71, v127
	v_mov_b32_e32 v70, v127
	v_mov_b32_e32 v69, v127
	v_mov_b32_e32 v68, v127
	v_mov_b32_e32 v67, v127
	v_mov_b32_e32 v66, v127
	v_mov_b32_e32 v65, v127
	v_mov_b32_e32 v64, v127
	v_mov_b32_e32 v63, v127
	v_mov_b32_e32 v62, v127
	v_mov_b32_e32 v61, v127
	v_mov_b32_e32 v60, v127
	v_mov_b32_e32 v51, v127
	v_mov_b32_e32 v50, v127
	v_mov_b32_e32 v49, v127
	v_mov_b32_e32 v48, v127
	v_mov_b32_e32 v47, v127
	v_mov_b32_e32 v46, v127
	v_mov_b32_e32 v45, v127
	v_mov_b32_e32 v44, v127
	v_mov_b32_e32 v35, v127
	v_mov_b32_e32 v34, v127
	v_mov_b32_e32 v33, v127
	v_mov_b32_e32 v32, v127
	v_mov_b32_e32 v31, v127
	v_mov_b32_e32 v30, v127
	v_mov_b32_e32 v29, v127
	v_mov_b32_e32 v28, v127
	v_mov_b32_e32 v19, v127
	v_mov_b32_e32 v18, v127
	v_mov_b32_e32 v17, v127
	v_mov_b32_e32 v16, v127
	v_mov_b32_e32 v15, v127
	v_mov_b32_e32 v14, v127
	v_mov_b32_e32 v13, v127
	v_mov_b32_e32 v12, v127
	v_mov_b32_e32 v59, v127
	v_mov_b32_e32 v58, v127
	v_mov_b32_e32 v57, v127
	v_mov_b32_e32 v56, v127
	v_mov_b32_e32 v55, v127
	v_mov_b32_e32 v54, v127
	v_mov_b32_e32 v53, v127
	v_mov_b32_e32 v52, v127
	v_mov_b32_e32 v43, v127
	v_mov_b32_e32 v42, v127
	v_mov_b32_e32 v41, v127
	v_mov_b32_e32 v40, v127
	v_mov_b32_e32 v39, v127
	v_mov_b32_e32 v38, v127
	v_mov_b32_e32 v37, v127
	v_mov_b32_e32 v36, v127
	v_mov_b32_e32 v27, v127
	v_mov_b32_e32 v26, v127
	v_mov_b32_e32 v25, v127
	v_mov_b32_e32 v24, v127
	v_mov_b32_e32 v23, v127
	v_mov_b32_e32 v22, v127
	v_mov_b32_e32 v21, v127
	v_mov_b32_e32 v20, v127
	v_mov_b32_e32 v11, v127
	v_mov_b32_e32 v10, v127
	v_mov_b32_e32 v9, v127
	v_mov_b32_e32 v8, v127
	v_mov_b32_e32 v7, v127
	v_mov_b32_e32 v6, v127
	v_mov_b32_e32 v5, v127
	v_mov_b32_e32 v4, v127
	s_cbranch_vccnz .LBB0_1625
	s_add_u32 s44, s44, 0x80
	s_addc_u32 s45, s45, 0
	s_add_u32 s65, s48, 0x100
	s_addc_u32 s67, s49, 0
	s_mov_b32 s48, 0
	s_add_i32 s72, s48, 2
	s_add_u32 s73, s44, 0x80
	s_addc_u32 s49, s45, 0
	s_add_i32 s86, 0, 0x10000
	s_cmp_eq_u32 s57, s48
	s_cselect_b32 s49, s13, s49
	s_cselect_b32 s48, s12, s73
	s_cselect_b32 s77, s41, s67
	s_cselect_b32 s76, s40, s65
	s_add_i32 s73, 0, 0x14000
	v_add_u32_e32 v158, s86, v143
	v_add_u32_e32 v174, s73, v143
	ds_read_b128 v[146:149], v158
	ds_read_b128 v[150:153], v158 offset:1024
	ds_read_b128 v[154:157], v158 offset:2048
	ds_read_b128 v[158:161], v158 offset:3072
	ds_read_b128 v[162:165], v174
	ds_read_b128 v[166:169], v174 offset:1024
	ds_read_b128 v[170:173], v174 offset:2048
	ds_read_b128 v[174:177], v174 offset:3072
	v_lshl_add_u64 v[190:191], s[44:45], 0, v[138:139]
	s_add_i32 m0, s47, 0xc000
	ds_read_b128 v[178:181], v145
	ds_read_b128 v[182:185], v145 offset:1024
	ds_read_b128 v[186:189], v145 offset:2048
	ds_read_b128 v[204:207], v145 offset:3072
	ds_read_b128 v[208:211], v145 offset:4096
	ds_read_b128 v[212:215], v145 offset:5120
	ds_read_b128 v[216:219], v145 offset:6144
	ds_read_b128 v[220:223], v145 offset:7168
	global_load_lds_dwordx4 v[190:191], off
	v_lshl_add_u64 v[190:191], s[44:45], 0, v[140:141]
	s_add_i32 m0, s47, 0xe000
	s_nop 0
	global_load_lds_dwordx4 v[190:191], off
	s_waitcnt vmcnt(8)
	s_waitcnt lgkmcnt(0)
	s_barrier
; #define PG8_STAGE(bufoff, gbase, voff) do { _Pragma("unroll") for (int _i = 0; _i < 2; ++_i) \
;         __builtin_amdgcn_global_load_lds((const unsigned*)((const char*)(gbase) + (voff)[_i]), (PG8_LAS unsigned*)(lds + (bufoff) + ldsw + _i * 8192), 16, 0, 0); } while (0)
; #define PG8_LDA(dst, b, h) do { _Pragma("unroll") for (int m = 0; m < 4; ++m) _Pragma("unroll") for (int k = 0; k < 2; ++k) dst[m][k] = *(const PG8_LAS bf16x8*)(lds + PG8_SA(b, h) + aoff + m * 2048 + k * 1024); } while (0)
; #define PG8_WAIT_V(n) asm volatile("s_waitcnt vmcnt(" #n ")" ::: "memory")
; #define PG8_WAIT_L(n) asm volatile("s_waitcnt lgkmcnt(" #n ")" ::: "memory")
; #define PG8_BAR __builtin_amdgcn_s_barrier()
; #define PG8_SCHED __builtin_amdgcn_sched_barrier(0)
; template <class Epi, class Sched, bool ALIGN_EPI = false, bool SP2 = false, bool I8 = false>
; __device__ __forceinline__ void gemm_phase(PG8_LAS unsigned char* lds, const Gemm g, const Sched& S, const Epi& E) {
;     ...
;             PG8_WAIT_V(8); PG8_WAIT_L(0); PG8_BAR; PG8_MMA(0, 0, At, B0); PG8_MMA(0, 1, At, B1); PG8_BAR; PG8_SCHED;
;             PG8_LDA(At, 0, 1); PG8_STAGE(PG8_SB(0, 0), b2, voffB); PG8_STAGE(PG8_SB(0, 1), b2 + hstep, voffB); PG8_STAGE(PG8_SA(0, 0), a2, voffA);
;             PG8_WAIT_V(8); PG8_WAIT_L(0); PG8_BAR; PG8_MMA(1, 0, At, B0); PG8_MMA(1, 1, At, B1); PG8_BAR; PG8_SCHED;
	s_setprio 1
	s_waitcnt lgkmcnt(0)
	v_mfma_f32_16x16x32_bf16 v[124:127], v[146:149], v[178:181], 0
	v_mfma_f32_16x16x32_bf16 v[124:127], v[150:153], v[182:185], v[124:127]
	v_mfma_f32_16x16x32_bf16 v[112:115], v[150:153], v[204:207], 0
	v_mfma_f32_16x16x32_bf16 v[112:115], v[146:149], v[186:189], v[112:115]
	v_mfma_f32_16x16x32_bf16 v[96:99], v[146:149], v[208:211], 0
	v_mfma_f32_16x16x32_bf16 v[96:99], v[150:153], v[212:215], v[96:99]
	v_mfma_f32_16x16x32_bf16 v[80:83], v[150:153], v[220:223], 0
	v_mfma_f32_16x16x32_bf16 v[80:83], v[146:149], v[216:219], v[80:83]
	v_mfma_f32_16x16x32_bf16 v[76:79], v[154:157], v[216:219], 0
	v_mfma_f32_16x16x32_bf16 v[76:79], v[158:161], v[220:223], v[76:79]
	v_mfma_f32_16x16x32_bf16 v[92:95], v[158:161], v[212:215], 0
	v_mfma_f32_16x16x32_bf16 v[92:95], v[154:157], v[208:211], v[92:95]
	v_mfma_f32_16x16x32_bf16 v[108:111], v[154:157], v[186:189], 0
	v_mfma_f32_16x16x32_bf16 v[108:111], v[158:161], v[204:207], v[108:111]
	v_mfma_f32_16x16x32_bf16 v[128:131], v[158:161], v[182:185], 0
	v_mfma_f32_16x16x32_bf16 v[128:131], v[154:157], v[178:181], v[128:131]
	v_mfma_f32_16x16x32_bf16 v[120:123], v[162:165], v[178:181], 0
	v_mfma_f32_16x16x32_bf16 v[120:123], v[166:169], v[182:185], v[120:123]
	v_mfma_f32_16x16x32_bf16 v[104:107], v[166:169], v[204:207], 0
	v_mfma_f32_16x16x32_bf16 v[104:107], v[162:165], v[186:189], v[104:107]
	v_mfma_f32_16x16x32_bf16 v[88:91], v[162:165], v[208:211], 0
	v_mfma_f32_16x16x32_bf16 v[88:91], v[166:169], v[212:215], v[88:91]
	v_mfma_f32_16x16x32_bf16 v[72:75], v[166:169], v[220:223], 0
	v_mfma_f32_16x16x32_bf16 v[72:75], v[162:165], v[216:219], v[72:75]
	v_mfma_f32_16x16x32_bf16 v[68:71], v[170:173], v[216:219], 0
	v_mfma_f32_16x16x32_bf16 v[68:71], v[174:177], v[220:223], v[68:71]
	v_mfma_f32_16x16x32_bf16 v[84:87], v[174:177], v[212:215], 0
	v_mfma_f32_16x16x32_bf16 v[84:87], v[170:173], v[208:211], v[84:87]
	v_mfma_f32_16x16x32_bf16 v[100:103], v[170:173], v[186:189], 0
	v_mfma_f32_16x16x32_bf16 v[100:103], v[174:177], v[204:207], v[100:103]
	v_mfma_f32_16x16x32_bf16 v[116:119], v[174:177], v[182:185], 0
	v_mfma_f32_16x16x32_bf16 v[116:119], v[170:173], v[178:181], v[116:119]
	s_setprio 0
	s_barrier
	s_add_i32 s86, s86, s28
	v_lshl_add_u64 v[190:191], s[76:77], 0, v[2:3]
	s_mov_b32 m0, s86
	ds_read_b128 v[178:181], v145 offset:16384
	ds_read_b128 v[182:185], v145 offset:17408
	ds_read_b128 v[186:189], v145 offset:18432
	ds_read_b128 v[204:207], v145 offset:19456
	ds_read_b128 v[208:211], v145 offset:20480
	ds_read_b128 v[212:215], v145 offset:21504
	ds_read_b128 v[216:219], v145 offset:22528
	ds_read_b128 v[220:223], v145 offset:23552
	global_load_lds_dwordx4 v[190:191], off
	s_add_i32 m0, s86, 0x2000
	v_lshl_add_u64 v[224:225], s[76:77], 0, v[136:137]
	s_add_u32 s76, s76, s18
	s_addc_u32 s77, s77, s19
	s_add_i32 s73, s73, s28
	global_load_lds_dwordx4 v[224:225], off
	v_lshl_add_u64 v[226:227], s[76:77], 0, v[2:3]
	s_mov_b32 m0, s73
	v_lshl_add_u64 v[228:229], s[76:77], 0, v[136:137]
	global_load_lds_dwordx4 v[226:227], off
	s_add_i32 m0, s73, 0x2000
	v_lshl_add_u64 v[240:241], s[48:49], 0, v[132:133]
	global_load_lds_dwordx4 v[228:229], off
	v_lshl_add_u64 v[242:243], s[48:49], 0, v[134:135]
	s_waitcnt vmcnt(6)
	s_waitcnt lgkmcnt(0)
	s_barrier
	s_setprio 1
	s_waitcnt lgkmcnt(0)
	v_mfma_f32_16x16x32_bf16 v[64:67], v[146:149], v[178:181], 0
	v_mfma_f32_16x16x32_bf16 v[64:67], v[150:153], v[182:185], v[64:67]
	v_mfma_f32_16x16x32_bf16 v[48:51], v[150:153], v[204:207], 0
	v_mfma_f32_16x16x32_bf16 v[48:51], v[146:149], v[186:189], v[48:51]
	v_mfma_f32_16x16x32_bf16 v[32:35], v[146:149], v[208:211], 0
	v_mfma_f32_16x16x32_bf16 v[32:35], v[150:153], v[212:215], v[32:35]
	v_mfma_f32_16x16x32_bf16 v[16:19], v[150:153], v[220:223], 0
	v_mfma_f32_16x16x32_bf16 v[16:19], v[146:149], v[216:219], v[16:19]
	v_mfma_f32_16x16x32_bf16 v[12:15], v[154:157], v[216:219], 0
	v_mfma_f32_16x16x32_bf16 v[12:15], v[158:161], v[220:223], v[12:15]
	v_mfma_f32_16x16x32_bf16 v[28:31], v[158:161], v[212:215], 0
	v_mfma_f32_16x16x32_bf16 v[28:31], v[154:157], v[208:211], v[28:31]
	v_mfma_f32_16x16x32_bf16 v[44:47], v[154:157], v[186:189], 0
	v_mfma_f32_16x16x32_bf16 v[44:47], v[158:161], v[204:207], v[44:47]
	v_mfma_f32_16x16x32_bf16 v[60:63], v[158:161], v[182:185], 0
	v_mfma_f32_16x16x32_bf16 v[60:63], v[154:157], v[178:181], v[60:63]
	v_mfma_f32_16x16x32_bf16 v[56:59], v[162:165], v[178:181], 0
	v_mfma_f32_16x16x32_bf16 v[56:59], v[166:169], v[182:185], v[56:59]
	v_mfma_f32_16x16x32_bf16 v[40:43], v[166:169], v[204:207], 0
	v_mfma_f32_16x16x32_bf16 v[40:43], v[162:165], v[186:189], v[40:43]
	v_mfma_f32_16x16x32_bf16 v[24:27], v[162:165], v[208:211], 0
	v_mfma_f32_16x16x32_bf16 v[24:27], v[166:169], v[212:215], v[24:27]
	v_mfma_f32_16x16x32_bf16 v[8:11], v[166:169], v[220:223], 0
	v_mfma_f32_16x16x32_bf16 v[8:11], v[162:165], v[216:219], v[8:11]
	v_mfma_f32_16x16x32_bf16 v[4:7], v[170:173], v[216:219], 0
	v_mfma_f32_16x16x32_bf16 v[4:7], v[174:177], v[220:223], v[4:7]
	v_mfma_f32_16x16x32_bf16 v[20:23], v[174:177], v[212:215], 0
	v_mfma_f32_16x16x32_bf16 v[20:23], v[170:173], v[208:211], v[20:23]
	v_mfma_f32_16x16x32_bf16 v[36:39], v[170:173], v[186:189], 0
	v_mfma_f32_16x16x32_bf16 v[36:39], v[174:177], v[204:207], v[36:39]
	v_mfma_f32_16x16x32_bf16 v[52:55], v[174:177], v[182:185], 0
	v_mfma_f32_16x16x32_bf16 v[52:55], v[170:173], v[178:181], v[52:55]
	s_setprio 0
	s_barrier
; #define PG8_STAGE(bufoff, gbase, voff) do { _Pragma("unroll") for (int _i = 0; _i < 2; ++_i) \
;         __builtin_amdgcn_global_load_lds((const unsigned*)((const char*)(gbase) + (voff)[_i]), (PG8_LAS unsigned*)(lds + (bufoff) + ldsw + _i * 8192), 16, 0, 0); } while (0)
; #define PG8_LDA(dst, b, h) do { _Pragma("unroll") for (int m = 0; m < 4; ++m) _Pragma("unroll") for (int k = 0; k < 2; ++k) dst[m][k] = *(const PG8_LAS bf16x8*)(lds + PG8_SA(b, h) + aoff + m * 2048 + k * 1024); } while (0)
; #define PG8_LDB(dst, b, h) do { _Pragma("unroll") for (int n = 0; n < 2; ++n) _Pragma("unroll") for (int k = 0; k < 2; ++k) dst[n][k] = *(const PG8_LAS bf16x8*)(lds + PG8_SB(b, h) + boff + n * 2048 + k * 1024); } while (0)
; #define PG8_WAIT_V(n) asm volatile("s_waitcnt vmcnt(" #n ")" ::: "memory")
; #define PG8_WAIT_L(n) asm volatile("s_waitcnt lgkmcnt(" #n ")" ::: "memory")
; #define PG8_BAR __builtin_amdgcn_s_barrier()
; #define PG8_SCHED __builtin_amdgcn_sched_barrier(0)
; template <class Epi, class Sched, bool ALIGN_EPI = false, bool SP2 = false, bool I8 = false>
; __device__ __forceinline__ void gemm_phase(PG8_LAS unsigned char* lds, const Gemm g, const Sched& S, const Epi& E) {
;     ...
;             PG8_LDB(B0, 1, 0); PG8_LDB(B1, 1, 1); PG8_SCHED; PG8_LDA(At, 1, 0); PG8_STAGE(PG8_SA(0, 1), a2 + hstep, voffA);
;             PG8_WAIT_V(8); PG8_WAIT_L(0); PG8_BAR; PG8_MMA(0, 0, At, B0); PG8_MMA(0, 1, At, B1); PG8_BAR; PG8_SCHED;
;             PG8_LDA(At, 1, 1); PG8_STAGE(PG8_SB(1, 0), b3, voffB); PG8_STAGE(PG8_SB(1, 1), b3 + hstep, voffB); PG8_STAGE(PG8_SA(1, 0), a3, voffA);
;             PG8_WAIT_V(8); PG8_WAIT_L(0); PG8_BAR; PG8_MMA(1, 0, At, B0); PG8_MMA(1, 1, At, B1); PG8_BAR; PG8_SCHED;
	s_mov_b32 m0, s47
	s_nop 0
	global_load_lds_dwordx4 v[240:241], off
	s_mov_b32 m0, s50
	s_nop 0
	global_load_lds_dwordx4 v[242:243], off
	s_add_i32 s73, 0, 0x18000
	s_add_i32 s76, 0, 0x1c000
	v_add_u32_e32 v158, s73, v143
	v_add_u32_e32 v174, s76, v143
	ds_read_b128 v[146:149], v158
	ds_read_b128 v[150:153], v158 offset:1024
	ds_read_b128 v[154:157], v158 offset:2048
	ds_read_b128 v[158:161], v158 offset:3072
	ds_read_b128 v[162:165], v174
	ds_read_b128 v[166:169], v174 offset:1024
	ds_read_b128 v[170:173], v174 offset:2048
	ds_read_b128 v[174:177], v174 offset:3072
	s_add_u32 s48, s48, s18
	s_addc_u32 s49, s49, s19
	s_mov_b32 m0, s51
	ds_read_b128 v[178:181], v145 offset:32768
	ds_read_b128 v[182:185], v145 offset:33792
	ds_read_b128 v[186:189], v145 offset:34816
	ds_read_b128 v[204:207], v145 offset:35840
	ds_read_b128 v[208:211], v145 offset:36864
	ds_read_b128 v[212:215], v145 offset:37888
	ds_read_b128 v[216:219], v145 offset:38912
	ds_read_b128 v[220:223], v145 offset:39936
	global_load_lds_dwordx4 v132, s[48:49]
	s_mov_b32 m0, s52
	s_nop 0
	global_load_lds_dwordx4 v134, s[48:49]
	s_waitcnt vmcnt(8)
	s_waitcnt lgkmcnt(0)
	s_barrier
	s_setprio 1
	s_waitcnt lgkmcnt(0)
	v_mfma_f32_16x16x32_bf16 v[124:127], v[146:149], v[178:181], v[124:127]
	v_mfma_f32_16x16x32_bf16 v[124:127], v[150:153], v[182:185], v[124:127]
	v_mfma_f32_16x16x32_bf16 v[112:115], v[150:153], v[204:207], v[112:115]
	v_mfma_f32_16x16x32_bf16 v[112:115], v[146:149], v[186:189], v[112:115]
	v_mfma_f32_16x16x32_bf16 v[96:99], v[146:149], v[208:211], v[96:99]
	v_mfma_f32_16x16x32_bf16 v[96:99], v[150:153], v[212:215], v[96:99]
	v_mfma_f32_16x16x32_bf16 v[80:83], v[150:153], v[220:223], v[80:83]
	v_mfma_f32_16x16x32_bf16 v[80:83], v[146:149], v[216:219], v[80:83]
	v_mfma_f32_16x16x32_bf16 v[76:79], v[154:157], v[216:219], v[76:79]
	v_mfma_f32_16x16x32_bf16 v[76:79], v[158:161], v[220:223], v[76:79]
	v_mfma_f32_16x16x32_bf16 v[92:95], v[158:161], v[212:215], v[92:95]
	v_mfma_f32_16x16x32_bf16 v[92:95], v[154:157], v[208:211], v[92:95]
	v_mfma_f32_16x16x32_bf16 v[108:111], v[154:157], v[186:189], v[108:111]
	v_mfma_f32_16x16x32_bf16 v[108:111], v[158:161], v[204:207], v[108:111]
	v_mfma_f32_16x16x32_bf16 v[128:131], v[158:161], v[182:185], v[128:131]
	v_mfma_f32_16x16x32_bf16 v[128:131], v[154:157], v[178:181], v[128:131]
	v_mfma_f32_16x16x32_bf16 v[120:123], v[162:165], v[178:181], v[120:123]
	v_mfma_f32_16x16x32_bf16 v[120:123], v[166:169], v[182:185], v[120:123]
	v_mfma_f32_16x16x32_bf16 v[104:107], v[166:169], v[204:207], v[104:107]
	v_mfma_f32_16x16x32_bf16 v[104:107], v[162:165], v[186:189], v[104:107]
	v_mfma_f32_16x16x32_bf16 v[88:91], v[162:165], v[208:211], v[88:91]
	v_mfma_f32_16x16x32_bf16 v[88:91], v[166:169], v[212:215], v[88:91]
	v_mfma_f32_16x16x32_bf16 v[72:75], v[166:169], v[220:223], v[72:75]
	v_mfma_f32_16x16x32_bf16 v[72:75], v[162:165], v[216:219], v[72:75]
	v_mfma_f32_16x16x32_bf16 v[68:71], v[170:173], v[216:219], v[68:71]
	v_mfma_f32_16x16x32_bf16 v[68:71], v[174:177], v[220:223], v[68:71]
	v_mfma_f32_16x16x32_bf16 v[84:87], v[174:177], v[212:215], v[84:87]
	v_mfma_f32_16x16x32_bf16 v[84:87], v[170:173], v[208:211], v[84:87]
	v_mfma_f32_16x16x32_bf16 v[100:103], v[170:173], v[186:189], v[100:103]
	v_mfma_f32_16x16x32_bf16 v[100:103], v[174:177], v[204:207], v[100:103]
	v_mfma_f32_16x16x32_bf16 v[116:119], v[174:177], v[182:185], v[116:119]
	v_mfma_f32_16x16x32_bf16 v[116:119], v[170:173], v[178:181], v[116:119]
	s_setprio 0
	s_barrier
	s_add_i32 s48, s73, s28
	v_lshl_add_u64 v[190:191], v[190:191], 0, s[84:85]
	s_mov_b32 m0, s48
	ds_read_b128 v[178:181], v145 offset:49152
	ds_read_b128 v[182:185], v145 offset:50176
	ds_read_b128 v[186:189], v145 offset:51200
	ds_read_b128 v[204:207], v145 offset:52224
	ds_read_b128 v[208:211], v145 offset:53248
	ds_read_b128 v[212:215], v145 offset:54272
	ds_read_b128 v[216:219], v145 offset:55296
	ds_read_b128 v[220:223], v145 offset:56320
	global_load_lds_dwordx4 v[190:191], off
	v_lshl_add_u64 v[190:191], v[224:225], 0, s[84:85]
	s_add_i32 m0, s48, 0x2000
	s_add_i32 s48, s76, s28
	global_load_lds_dwordx4 v[190:191], off
	v_lshl_add_u64 v[190:191], v[226:227], 0, s[84:85]
	s_mov_b32 m0, s48
	s_nop 0
	global_load_lds_dwordx4 v[190:191], off
	v_lshl_add_u64 v[190:191], v[228:229], 0, s[84:85]
	s_add_i32 m0, s48, 0x2000
	s_nop 0
	global_load_lds_dwordx4 v[190:191], off
	v_lshl_add_u64 v[190:191], v[240:241], 0, s[84:85]
	s_mov_b32 m0, s55
	s_nop 0
	global_load_lds_dwordx4 v[190:191], off
	v_lshl_add_u64 v[190:191], v[242:243], 0, s[84:85]
	s_mov_b32 m0, s56
	s_nop 0
	global_load_lds_dwordx4 v[190:191], off
	s_waitcnt vmcnt(8)
	s_waitcnt lgkmcnt(0)
	s_barrier
; #define PG8_STAGE(bufoff, gbase, voff) do { _Pragma("unroll") for (int _i = 0; _i < 2; ++_i) \
;         __builtin_amdgcn_global_load_lds((const unsigned*)((const char*)(gbase) + (voff)[_i]), (PG8_LAS unsigned*)(lds + (bufoff) + ldsw + _i * 8192), 16, 0, 0); } while (0)
; #define PG8_LDA(dst, b, h) do { _Pragma("unroll") for (int m = 0; m < 4; ++m) _Pragma("unroll") for (int k = 0; k < 2; ++k) dst[m][k] = *(const PG8_LAS bf16x8*)(lds + PG8_SA(b, h) + aoff + m * 2048 + k * 1024); } while (0)
; #define PG8_LDB(dst, b, h) do { _Pragma("unroll") for (int n = 0; n < 2; ++n) _Pragma("unroll") for (int k = 0; k < 2; ++k) dst[n][k] = *(const PG8_LAS bf16x8*)(lds + PG8_SB(b, h) + boff + n * 2048 + k * 1024); } while (0)
; #define PG8_WAIT_V(n) asm volatile("s_waitcnt vmcnt(" #n ")" ::: "memory")
; #define PG8_WAIT_L(n) asm volatile("s_waitcnt lgkmcnt(" #n ")" ::: "memory")
; #define PG8_BAR __builtin_amdgcn_s_barrier()
; #define PG8_SCHED __builtin_amdgcn_sched_barrier(0)
; template <class Epi, class Sched, bool ALIGN_EPI = false, bool SP2 = false, bool I8 = false>
; __device__ __forceinline__ void gemm_phase(PG8_LAS unsigned char* lds, const Gemm g, const Sched& S, const Epi& E) {
;     ...
;         for (int t = 0; t < nt; t += 2) {
;             const bool last = (t == nt - 2);
;             const char* a1 = cA + (size_t)(t + 1) * kstep;
;             const char* a2 = last ? nA : cA + (size_t)(t + 2) * kstep; const char* b2 = last ? nB : cB + (size_t)(t + 2) * kstep;
;             const char* a3 = a2 + kstep; const char* b3 = b2 + kstep;
;             if (last && has_next) S.a_ready(nxt);
;             if constexpr (SP2) {
;             PG8_LDB(B0, 0, 0); PG8_LDB(B1, 0, 1); PG8_SCHED; PG8_LDA(At, 0, 0); PG8_STAGE(PG8_SA(1, 1), a1 + hstep, voffA);
;             PG8_WAIT_V(8); PG8_WAIT_L(0); PG8_BAR; PG8_MMA(0, 0, At, B0); PG8_MMA(0, 1, At, B1); PG8_BAR; PG8_SCHED;
;     ...
;             PG8_WAIT_V(8); PG8_WAIT_L(0); PG8_BAR; PG8_MMA(1, 0, At, B0); PG8_MMA(1, 1, At, B1); PG8_BAR; PG8_SCHED;
	s_setprio 1
	s_waitcnt lgkmcnt(0)
	v_mfma_f32_16x16x32_bf16 v[64:67], v[146:149], v[178:181], v[64:67]
	v_mfma_f32_16x16x32_bf16 v[64:67], v[150:153], v[182:185], v[64:67]
	v_mfma_f32_16x16x32_bf16 v[48:51], v[150:153], v[204:207], v[48:51]
	v_mfma_f32_16x16x32_bf16 v[48:51], v[146:149], v[186:189], v[48:51]
	v_mfma_f32_16x16x32_bf16 v[32:35], v[146:149], v[208:211], v[32:35]
	v_mfma_f32_16x16x32_bf16 v[32:35], v[150:153], v[212:215], v[32:35]
	v_mfma_f32_16x16x32_bf16 v[16:19], v[150:153], v[220:223], v[16:19]
	v_mfma_f32_16x16x32_bf16 v[16:19], v[146:149], v[216:219], v[16:19]
	v_mfma_f32_16x16x32_bf16 v[12:15], v[154:157], v[216:219], v[12:15]
	v_mfma_f32_16x16x32_bf16 v[12:15], v[158:161], v[220:223], v[12:15]
	v_mfma_f32_16x16x32_bf16 v[28:31], v[158:161], v[212:215], v[28:31]
	v_mfma_f32_16x16x32_bf16 v[28:31], v[154:157], v[208:211], v[28:31]
	v_mfma_f32_16x16x32_bf16 v[44:47], v[154:157], v[186:189], v[44:47]
	v_mfma_f32_16x16x32_bf16 v[44:47], v[158:161], v[204:207], v[44:47]
	v_mfma_f32_16x16x32_bf16 v[60:63], v[158:161], v[182:185], v[60:63]
	v_mfma_f32_16x16x32_bf16 v[60:63], v[154:157], v[178:181], v[60:63]
	v_mfma_f32_16x16x32_bf16 v[56:59], v[162:165], v[178:181], v[56:59]
	v_mfma_f32_16x16x32_bf16 v[56:59], v[166:169], v[182:185], v[56:59]
	v_mfma_f32_16x16x32_bf16 v[40:43], v[166:169], v[204:207], v[40:43]
	v_mfma_f32_16x16x32_bf16 v[40:43], v[162:165], v[186:189], v[40:43]
	v_mfma_f32_16x16x32_bf16 v[24:27], v[162:165], v[208:211], v[24:27]
	v_mfma_f32_16x16x32_bf16 v[24:27], v[166:169], v[212:215], v[24:27]
	v_mfma_f32_16x16x32_bf16 v[8:11], v[166:169], v[220:223], v[8:11]
	v_mfma_f32_16x16x32_bf16 v[8:11], v[162:165], v[216:219], v[8:11]
	v_mfma_f32_16x16x32_bf16 v[4:7], v[170:173], v[216:219], v[4:7]
	v_mfma_f32_16x16x32_bf16 v[4:7], v[174:177], v[220:223], v[4:7]
	v_mfma_f32_16x16x32_bf16 v[20:23], v[174:177], v[212:215], v[20:23]
	v_mfma_f32_16x16x32_bf16 v[20:23], v[170:173], v[208:211], v[20:23]
	v_mfma_f32_16x16x32_bf16 v[36:39], v[170:173], v[186:189], v[36:39]
	v_mfma_f32_16x16x32_bf16 v[36:39], v[174:177], v[204:207], v[36:39]
	v_mfma_f32_16x16x32_bf16 v[52:55], v[174:177], v[182:185], v[52:55]
	v_mfma_f32_16x16x32_bf16 v[52:55], v[170:173], v[178:181], v[52:55]
	s_setprio 0
	s_barrier
	s_add_u32 s44, s44, 0x100
	s_addc_u32 s45, s45, 0
	s_add_u32 s65, s65, 0x100
	s_addc_u32 s67, s67, 0
	s_cmp_ge_i32 s72, s53
	s_mov_b32 s48, s72
	s_cbranch_scc1 .Lkloop_exit_4
.LBB0_1623:
	s_add_i32 s72, s48, 2
	s_add_u32 s73, s44, 0x80
	s_addc_u32 s49, s45, 0
	s_add_i32 s86, 0, 0x10000
	s_cmp_eq_u32 s57, s48
	s_cselect_b32 s49, s13, s49
	s_cselect_b32 s48, s12, s73
	s_cselect_b32 s77, s41, s67
	s_cselect_b32 s76, s40, s65
	s_add_i32 s73, 0, 0x14000
	v_add_u32_e32 v158, s86, v143
	v_add_u32_e32 v174, s73, v143
	ds_read_b128 v[146:149], v158
	ds_read_b128 v[150:153], v158 offset:1024
	ds_read_b128 v[154:157], v158 offset:2048
	ds_read_b128 v[158:161], v158 offset:3072
	ds_read_b128 v[162:165], v174
	ds_read_b128 v[166:169], v174 offset:1024
	ds_read_b128 v[170:173], v174 offset:2048
	ds_read_b128 v[174:177], v174 offset:3072
	v_lshl_add_u64 v[190:191], s[44:45], 0, v[138:139]
	s_add_i32 m0, s47, 0xc000
	ds_read_b128 v[178:181], v145
	ds_read_b128 v[182:185], v145 offset:1024
	ds_read_b128 v[186:189], v145 offset:2048
	ds_read_b128 v[204:207], v145 offset:3072
	ds_read_b128 v[208:211], v145 offset:4096
	ds_read_b128 v[212:215], v145 offset:5120
	ds_read_b128 v[216:219], v145 offset:6144
	ds_read_b128 v[220:223], v145 offset:7168
	global_load_lds_dwordx4 v[190:191], off
	v_lshl_add_u64 v[190:191], s[44:45], 0, v[140:141]
	s_add_i32 m0, s47, 0xe000
	s_nop 0
	global_load_lds_dwordx4 v[190:191], off
	s_waitcnt vmcnt(8)
	s_waitcnt lgkmcnt(0)
	s_barrier
	s_setprio 1
	s_waitcnt lgkmcnt(0)
	v_mfma_f32_16x16x32_bf16 v[124:127], v[146:149], v[178:181], v[124:127]
	v_mfma_f32_16x16x32_bf16 v[124:127], v[150:153], v[182:185], v[124:127]
	v_mfma_f32_16x16x32_bf16 v[112:115], v[150:153], v[204:207], v[112:115]
	v_mfma_f32_16x16x32_bf16 v[112:115], v[146:149], v[186:189], v[112:115]
	v_mfma_f32_16x16x32_bf16 v[96:99], v[146:149], v[208:211], v[96:99]
	v_mfma_f32_16x16x32_bf16 v[96:99], v[150:153], v[212:215], v[96:99]
	v_mfma_f32_16x16x32_bf16 v[80:83], v[150:153], v[220:223], v[80:83]
	v_mfma_f32_16x16x32_bf16 v[80:83], v[146:149], v[216:219], v[80:83]
	v_mfma_f32_16x16x32_bf16 v[76:79], v[154:157], v[216:219], v[76:79]
	v_mfma_f32_16x16x32_bf16 v[76:79], v[158:161], v[220:223], v[76:79]
	v_mfma_f32_16x16x32_bf16 v[92:95], v[158:161], v[212:215], v[92:95]
	v_mfma_f32_16x16x32_bf16 v[92:95], v[154:157], v[208:211], v[92:95]
	v_mfma_f32_16x16x32_bf16 v[108:111], v[154:157], v[186:189], v[108:111]
	v_mfma_f32_16x16x32_bf16 v[108:111], v[158:161], v[204:207], v[108:111]
	v_mfma_f32_16x16x32_bf16 v[128:131], v[158:161], v[182:185], v[128:131]
	v_mfma_f32_16x16x32_bf16 v[128:131], v[154:157], v[178:181], v[128:131]
	v_mfma_f32_16x16x32_bf16 v[120:123], v[162:165], v[178:181], v[120:123]
	v_mfma_f32_16x16x32_bf16 v[120:123], v[166:169], v[182:185], v[120:123]
	v_mfma_f32_16x16x32_bf16 v[104:107], v[166:169], v[204:207], v[104:107]
	v_mfma_f32_16x16x32_bf16 v[104:107], v[162:165], v[186:189], v[104:107]
	v_mfma_f32_16x16x32_bf16 v[88:91], v[162:165], v[208:211], v[88:91]
	v_mfma_f32_16x16x32_bf16 v[88:91], v[166:169], v[212:215], v[88:91]
	v_mfma_f32_16x16x32_bf16 v[72:75], v[166:169], v[220:223], v[72:75]
	v_mfma_f32_16x16x32_bf16 v[72:75], v[162:165], v[216:219], v[72:75]
	v_mfma_f32_16x16x32_bf16 v[68:71], v[170:173], v[216:219], v[68:71]
	v_mfma_f32_16x16x32_bf16 v[68:71], v[174:177], v[220:223], v[68:71]
	v_mfma_f32_16x16x32_bf16 v[84:87], v[174:177], v[212:215], v[84:87]
	v_mfma_f32_16x16x32_bf16 v[84:87], v[170:173], v[208:211], v[84:87]
	v_mfma_f32_16x16x32_bf16 v[100:103], v[170:173], v[186:189], v[100:103]
	v_mfma_f32_16x16x32_bf16 v[100:103], v[174:177], v[204:207], v[100:103]
	v_mfma_f32_16x16x32_bf16 v[116:119], v[174:177], v[182:185], v[116:119]
	v_mfma_f32_16x16x32_bf16 v[116:119], v[170:173], v[178:181], v[116:119]
	s_setprio 0
	s_barrier
; #define PG8_STAGE(bufoff, gbase, voff) do { _Pragma("unroll") for (int _i = 0; _i < 2; ++_i) \
;         __builtin_amdgcn_global_load_lds((const unsigned*)((const char*)(gbase) + (voff)[_i]), (PG8_LAS unsigned*)(lds + (bufoff) + ldsw + _i * 8192), 16, 0, 0); } while (0)
; #define PG8_LDA(dst, b, h) do { _Pragma("unroll") for (int m = 0; m < 4; ++m) _Pragma("unroll") for (int k = 0; k < 2; ++k) dst[m][k] = *(const PG8_LAS bf16x8*)(lds + PG8_SA(b, h) + aoff + m * 2048 + k * 1024); } while (0)
; #define PG8_LDB(dst, b, h) do { _Pragma("unroll") for (int n = 0; n < 2; ++n) _Pragma("unroll") for (int k = 0; k < 2; ++k) dst[n][k] = *(const PG8_LAS bf16x8*)(lds + PG8_SB(b, h) + boff + n * 2048 + k * 1024); } while (0)
; #define PG8_WAIT_V(n) asm volatile("s_waitcnt vmcnt(" #n ")" ::: "memory")
; #define PG8_WAIT_L(n) asm volatile("s_waitcnt lgkmcnt(" #n ")" ::: "memory")
; #define PG8_BAR __builtin_amdgcn_s_barrier()
; #define PG8_SCHED __builtin_amdgcn_sched_barrier(0)
; template <class Epi, class Sched, bool ALIGN_EPI = false, bool SP2 = false, bool I8 = false>
; __device__ __forceinline__ void gemm_phase(PG8_LAS unsigned char* lds, const Gemm g, const Sched& S, const Epi& E) {
;     ...
;             PG8_LDA(At, 0, 1); PG8_STAGE(PG8_SB(0, 0), b2, voffB); PG8_STAGE(PG8_SB(0, 1), b2 + hstep, voffB); PG8_STAGE(PG8_SA(0, 0), a2, voffA);
;             PG8_WAIT_V(8); PG8_WAIT_L(0); PG8_BAR; PG8_MMA(1, 0, At, B0); PG8_MMA(1, 1, At, B1); PG8_BAR; PG8_SCHED;
;             PG8_LDB(B0, 1, 0); PG8_LDB(B1, 1, 1); PG8_SCHED; PG8_LDA(At, 1, 0); PG8_STAGE(PG8_SA(0, 1), a2 + hstep, voffA);
;             PG8_WAIT_V(8); PG8_WAIT_L(0); PG8_BAR; PG8_MMA(0, 0, At, B0); PG8_MMA(0, 1, At, B1); PG8_BAR; PG8_SCHED;
;             PG8_LDA(At, 1, 1); PG8_STAGE(PG8_SB(1, 0), b3, voffB); PG8_STAGE(PG8_SB(1, 1), b3 + hstep, voffB); PG8_STAGE(PG8_SA(1, 0), a3, voffA);
	s_add_i32 s86, s86, s28
	v_lshl_add_u64 v[190:191], s[76:77], 0, v[2:3]
	s_mov_b32 m0, s86
	ds_read_b128 v[178:181], v145 offset:16384
	ds_read_b128 v[182:185], v145 offset:17408
	ds_read_b128 v[186:189], v145 offset:18432
	ds_read_b128 v[204:207], v145 offset:19456
	ds_read_b128 v[208:211], v145 offset:20480
	ds_read_b128 v[212:215], v145 offset:21504
	ds_read_b128 v[216:219], v145 offset:22528
	ds_read_b128 v[220:223], v145 offset:23552
	global_load_lds_dwordx4 v[190:191], off
	s_add_i32 m0, s86, 0x2000
	v_lshl_add_u64 v[224:225], s[76:77], 0, v[136:137]
	s_add_u32 s76, s76, s18
	s_addc_u32 s77, s77, s19
	s_add_i32 s73, s73, s28
	global_load_lds_dwordx4 v[224:225], off
	v_lshl_add_u64 v[226:227], s[76:77], 0, v[2:3]
	s_mov_b32 m0, s73
	v_lshl_add_u64 v[228:229], s[76:77], 0, v[136:137]
	global_load_lds_dwordx4 v[226:227], off
	s_add_i32 m0, s73, 0x2000
	v_lshl_add_u64 v[240:241], s[48:49], 0, v[132:133]
	global_load_lds_dwordx4 v[228:229], off
	v_lshl_add_u64 v[242:243], s[48:49], 0, v[134:135]
	s_waitcnt vmcnt(6)
	s_waitcnt lgkmcnt(0)
	s_barrier
	s_setprio 1
	s_waitcnt lgkmcnt(0)
	v_mfma_f32_16x16x32_bf16 v[64:67], v[146:149], v[178:181], v[64:67]
	v_mfma_f32_16x16x32_bf16 v[64:67], v[150:153], v[182:185], v[64:67]
	v_mfma_f32_16x16x32_bf16 v[48:51], v[150:153], v[204:207], v[48:51]
	v_mfma_f32_16x16x32_bf16 v[48:51], v[146:149], v[186:189], v[48:51]
	v_mfma_f32_16x16x32_bf16 v[32:35], v[146:149], v[208:211], v[32:35]
	v_mfma_f32_16x16x32_bf16 v[32:35], v[150:153], v[212:215], v[32:35]
	v_mfma_f32_16x16x32_bf16 v[16:19], v[150:153], v[220:223], v[16:19]
	v_mfma_f32_16x16x32_bf16 v[16:19], v[146:149], v[216:219], v[16:19]
	v_mfma_f32_16x16x32_bf16 v[12:15], v[154:157], v[216:219], v[12:15]
	v_mfma_f32_16x16x32_bf16 v[12:15], v[158:161], v[220:223], v[12:15]
	v_mfma_f32_16x16x32_bf16 v[28:31], v[158:161], v[212:215], v[28:31]
	v_mfma_f32_16x16x32_bf16 v[28:31], v[154:157], v[208:211], v[28:31]
	v_mfma_f32_16x16x32_bf16 v[44:47], v[154:157], v[186:189], v[44:47]
	v_mfma_f32_16x16x32_bf16 v[44:47], v[158:161], v[204:207], v[44:47]
	v_mfma_f32_16x16x32_bf16 v[60:63], v[158:161], v[182:185], v[60:63]
	v_mfma_f32_16x16x32_bf16 v[60:63], v[154:157], v[178:181], v[60:63]
	v_mfma_f32_16x16x32_bf16 v[56:59], v[162:165], v[178:181], v[56:59]
	v_mfma_f32_16x16x32_bf16 v[56:59], v[166:169], v[182:185], v[56:59]
	v_mfma_f32_16x16x32_bf16 v[40:43], v[166:169], v[204:207], v[40:43]
	v_mfma_f32_16x16x32_bf16 v[40:43], v[162:165], v[186:189], v[40:43]
	v_mfma_f32_16x16x32_bf16 v[24:27], v[162:165], v[208:211], v[24:27]
	v_mfma_f32_16x16x32_bf16 v[24:27], v[166:169], v[212:215], v[24:27]
	v_mfma_f32_16x16x32_bf16 v[8:11], v[166:169], v[220:223], v[8:11]
	v_mfma_f32_16x16x32_bf16 v[8:11], v[162:165], v[216:219], v[8:11]
	v_mfma_f32_16x16x32_bf16 v[4:7], v[170:173], v[216:219], v[4:7]
	v_mfma_f32_16x16x32_bf16 v[4:7], v[174:177], v[220:223], v[4:7]
	v_mfma_f32_16x16x32_bf16 v[20:23], v[174:177], v[212:215], v[20:23]
	v_mfma_f32_16x16x32_bf16 v[20:23], v[170:173], v[208:211], v[20:23]
	v_mfma_f32_16x16x32_bf16 v[36:39], v[170:173], v[186:189], v[36:39]
	v_mfma_f32_16x16x32_bf16 v[36:39], v[174:177], v[204:207], v[36:39]
	v_mfma_f32_16x16x32_bf16 v[52:55], v[174:177], v[182:185], v[52:55]
	v_mfma_f32_16x16x32_bf16 v[52:55], v[170:173], v[178:181], v[52:55]
	s_setprio 0
	s_barrier
	s_mov_b32 m0, s47
	s_nop 0
	global_load_lds_dwordx4 v[240:241], off
	s_mov_b32 m0, s50
	s_nop 0
	global_load_lds_dwordx4 v[242:243], off
	s_add_i32 s73, 0, 0x18000
	s_add_i32 s76, 0, 0x1c000
	v_add_u32_e32 v158, s73, v143
	v_add_u32_e32 v174, s76, v143
	ds_read_b128 v[146:149], v158
	ds_read_b128 v[150:153], v158 offset:1024
	ds_read_b128 v[154:157], v158 offset:2048
	ds_read_b128 v[158:161], v158 offset:3072
	ds_read_b128 v[162:165], v174
	ds_read_b128 v[166:169], v174 offset:1024
	ds_read_b128 v[170:173], v174 offset:2048
	ds_read_b128 v[174:177], v174 offset:3072
	s_add_u32 s48, s48, s18
	s_addc_u32 s49, s49, s19
	s_mov_b32 m0, s51
	ds_read_b128 v[178:181], v145 offset:32768
	ds_read_b128 v[182:185], v145 offset:33792
	ds_read_b128 v[186:189], v145 offset:34816
	ds_read_b128 v[204:207], v145 offset:35840
	ds_read_b128 v[208:211], v145 offset:36864
	ds_read_b128 v[212:215], v145 offset:37888
	ds_read_b128 v[216:219], v145 offset:38912
	ds_read_b128 v[220:223], v145 offset:39936
	global_load_lds_dwordx4 v132, s[48:49]
	s_mov_b32 m0, s52
	s_nop 0
	global_load_lds_dwordx4 v134, s[48:49]
	s_waitcnt vmcnt(8)
	s_waitcnt lgkmcnt(0)
	s_barrier
; #define PG8_STAGE(bufoff, gbase, voff) do { _Pragma("unroll") for (int _i = 0; _i < 2; ++_i) \
;         __builtin_amdgcn_global_load_lds((const unsigned*)((const char*)(gbase) + (voff)[_i]), (PG8_LAS unsigned*)(lds + (bufoff) + ldsw + _i * 8192), 16, 0, 0); } while (0)
; #define PG8_LDA(dst, b, h) do { _Pragma("unroll") for (int m = 0; m < 4; ++m) _Pragma("unroll") for (int k = 0; k < 2; ++k) dst[m][k] = *(const PG8_LAS bf16x8*)(lds + PG8_SA(b, h) + aoff + m * 2048 + k * 1024); } while (0)
; #define PG8_WAIT_V(n) asm volatile("s_waitcnt vmcnt(" #n ")" ::: "memory")
; #define PG8_WAIT_L(n) asm volatile("s_waitcnt lgkmcnt(" #n ")" ::: "memory")
; #define PG8_BAR __builtin_amdgcn_s_barrier()
; #define PG8_SCHED __builtin_amdgcn_sched_barrier(0)
; template <class Epi, class Sched, bool ALIGN_EPI = false, bool SP2 = false, bool I8 = false>
; __device__ __forceinline__ void gemm_phase(PG8_LAS unsigned char* lds, const Gemm g, const Sched& S, const Epi& E) {
;     ...
;             PG8_WAIT_V(8); PG8_WAIT_L(0); PG8_BAR; PG8_MMA(0, 0, At, B0); PG8_MMA(0, 1, At, B1); PG8_BAR; PG8_SCHED;
;             PG8_LDA(At, 1, 1); PG8_STAGE(PG8_SB(1, 0), b3, voffB); PG8_STAGE(PG8_SB(1, 1), b3 + hstep, voffB); PG8_STAGE(PG8_SA(1, 0), a3, voffA);
;             PG8_WAIT_V(8); PG8_WAIT_L(0); PG8_BAR; PG8_MMA(1, 0, At, B0); PG8_MMA(1, 1, At, B1); PG8_BAR; PG8_SCHED;
	s_setprio 1
	s_waitcnt lgkmcnt(0)
	v_mfma_f32_16x16x32_bf16 v[124:127], v[146:149], v[178:181], v[124:127]
	v_mfma_f32_16x16x32_bf16 v[124:127], v[150:153], v[182:185], v[124:127]
	v_mfma_f32_16x16x32_bf16 v[112:115], v[150:153], v[204:207], v[112:115]
	v_mfma_f32_16x16x32_bf16 v[112:115], v[146:149], v[186:189], v[112:115]
	v_mfma_f32_16x16x32_bf16 v[96:99], v[146:149], v[208:211], v[96:99]
	v_mfma_f32_16x16x32_bf16 v[96:99], v[150:153], v[212:215], v[96:99]
	v_mfma_f32_16x16x32_bf16 v[80:83], v[150:153], v[220:223], v[80:83]
	v_mfma_f32_16x16x32_bf16 v[80:83], v[146:149], v[216:219], v[80:83]
	v_mfma_f32_16x16x32_bf16 v[76:79], v[154:157], v[216:219], v[76:79]
	v_mfma_f32_16x16x32_bf16 v[76:79], v[158:161], v[220:223], v[76:79]
	v_mfma_f32_16x16x32_bf16 v[92:95], v[158:161], v[212:215], v[92:95]
	v_mfma_f32_16x16x32_bf16 v[92:95], v[154:157], v[208:211], v[92:95]
	v_mfma_f32_16x16x32_bf16 v[108:111], v[154:157], v[186:189], v[108:111]
	v_mfma_f32_16x16x32_bf16 v[108:111], v[158:161], v[204:207], v[108:111]
	v_mfma_f32_16x16x32_bf16 v[128:131], v[158:161], v[182:185], v[128:131]
	v_mfma_f32_16x16x32_bf16 v[128:131], v[154:157], v[178:181], v[128:131]
	v_mfma_f32_16x16x32_bf16 v[120:123], v[162:165], v[178:181], v[120:123]
	v_mfma_f32_16x16x32_bf16 v[120:123], v[166:169], v[182:185], v[120:123]
	v_mfma_f32_16x16x32_bf16 v[104:107], v[166:169], v[204:207], v[104:107]
	v_mfma_f32_16x16x32_bf16 v[104:107], v[162:165], v[186:189], v[104:107]
	v_mfma_f32_16x16x32_bf16 v[88:91], v[162:165], v[208:211], v[88:91]
	v_mfma_f32_16x16x32_bf16 v[88:91], v[166:169], v[212:215], v[88:91]
	v_mfma_f32_16x16x32_bf16 v[72:75], v[166:169], v[220:223], v[72:75]
	v_mfma_f32_16x16x32_bf16 v[72:75], v[162:165], v[216:219], v[72:75]
	v_mfma_f32_16x16x32_bf16 v[68:71], v[170:173], v[216:219], v[68:71]
	v_mfma_f32_16x16x32_bf16 v[68:71], v[174:177], v[220:223], v[68:71]
	v_mfma_f32_16x16x32_bf16 v[84:87], v[174:177], v[212:215], v[84:87]
	v_mfma_f32_16x16x32_bf16 v[84:87], v[170:173], v[208:211], v[84:87]
	v_mfma_f32_16x16x32_bf16 v[100:103], v[170:173], v[186:189], v[100:103]
	v_mfma_f32_16x16x32_bf16 v[100:103], v[174:177], v[204:207], v[100:103]
	v_mfma_f32_16x16x32_bf16 v[116:119], v[174:177], v[182:185], v[116:119]
	v_mfma_f32_16x16x32_bf16 v[116:119], v[170:173], v[178:181], v[116:119]
	s_setprio 0
	s_barrier
	s_add_i32 s48, s73, s28
	v_lshl_add_u64 v[190:191], v[190:191], 0, s[84:85]
	s_mov_b32 m0, s48
	ds_read_b128 v[178:181], v145 offset:49152
	ds_read_b128 v[182:185], v145 offset:50176
	ds_read_b128 v[186:189], v145 offset:51200
	ds_read_b128 v[204:207], v145 offset:52224
	ds_read_b128 v[208:211], v145 offset:53248
	ds_read_b128 v[212:215], v145 offset:54272
	ds_read_b128 v[216:219], v145 offset:55296
	ds_read_b128 v[220:223], v145 offset:56320
	global_load_lds_dwordx4 v[190:191], off
	v_lshl_add_u64 v[190:191], v[224:225], 0, s[84:85]
	s_add_i32 m0, s48, 0x2000
	s_add_i32 s48, s76, s28
	global_load_lds_dwordx4 v[190:191], off
	v_lshl_add_u64 v[190:191], v[226:227], 0, s[84:85]
	s_mov_b32 m0, s48
	s_nop 0
	global_load_lds_dwordx4 v[190:191], off
	v_lshl_add_u64 v[190:191], v[228:229], 0, s[84:85]
	s_add_i32 m0, s48, 0x2000
	s_nop 0
	global_load_lds_dwordx4 v[190:191], off
	v_lshl_add_u64 v[190:191], v[240:241], 0, s[84:85]
	s_mov_b32 m0, s55
	s_nop 0
	global_load_lds_dwordx4 v[190:191], off
	v_lshl_add_u64 v[190:191], v[242:243], 0, s[84:85]
	s_mov_b32 m0, s56
	s_nop 0
	global_load_lds_dwordx4 v[190:191], off
	s_waitcnt vmcnt(8)
	s_waitcnt lgkmcnt(0)
	s_barrier
	s_setprio 1
	s_waitcnt lgkmcnt(0)
	v_mfma_f32_16x16x32_bf16 v[64:67], v[146:149], v[178:181], v[64:67]
	v_mfma_f32_16x16x32_bf16 v[64:67], v[150:153], v[182:185], v[64:67]
	v_mfma_f32_16x16x32_bf16 v[48:51], v[150:153], v[204:207], v[48:51]
	v_mfma_f32_16x16x32_bf16 v[48:51], v[146:149], v[186:189], v[48:51]
	v_mfma_f32_16x16x32_bf16 v[32:35], v[146:149], v[208:211], v[32:35]
	v_mfma_f32_16x16x32_bf16 v[32:35], v[150:153], v[212:215], v[32:35]
	v_mfma_f32_16x16x32_bf16 v[16:19], v[150:153], v[220:223], v[16:19]
	v_mfma_f32_16x16x32_bf16 v[16:19], v[146:149], v[216:219], v[16:19]
	v_mfma_f32_16x16x32_bf16 v[12:15], v[154:157], v[216:219], v[12:15]
	v_mfma_f32_16x16x32_bf16 v[12:15], v[158:161], v[220:223], v[12:15]
	v_mfma_f32_16x16x32_bf16 v[28:31], v[158:161], v[212:215], v[28:31]
	v_mfma_f32_16x16x32_bf16 v[28:31], v[154:157], v[208:211], v[28:31]
	v_mfma_f32_16x16x32_bf16 v[44:47], v[154:157], v[186:189], v[44:47]
	v_mfma_f32_16x16x32_bf16 v[44:47], v[158:161], v[204:207], v[44:47]
	v_mfma_f32_16x16x32_bf16 v[60:63], v[158:161], v[182:185], v[60:63]
	v_mfma_f32_16x16x32_bf16 v[60:63], v[154:157], v[178:181], v[60:63]
	v_mfma_f32_16x16x32_bf16 v[56:59], v[162:165], v[178:181], v[56:59]
	v_mfma_f32_16x16x32_bf16 v[56:59], v[166:169], v[182:185], v[56:59]
	v_mfma_f32_16x16x32_bf16 v[40:43], v[166:169], v[204:207], v[40:43]
	v_mfma_f32_16x16x32_bf16 v[40:43], v[162:165], v[186:189], v[40:43]
	v_mfma_f32_16x16x32_bf16 v[24:27], v[162:165], v[208:211], v[24:27]
	v_mfma_f32_16x16x32_bf16 v[24:27], v[166:169], v[212:215], v[24:27]
	v_mfma_f32_16x16x32_bf16 v[8:11], v[166:169], v[220:223], v[8:11]
	v_mfma_f32_16x16x32_bf16 v[8:11], v[162:165], v[216:219], v[8:11]
	v_mfma_f32_16x16x32_bf16 v[4:7], v[170:173], v[216:219], v[4:7]
	v_mfma_f32_16x16x32_bf16 v[4:7], v[174:177], v[220:223], v[4:7]
	v_mfma_f32_16x16x32_bf16 v[20:23], v[174:177], v[212:215], v[20:23]
	v_mfma_f32_16x16x32_bf16 v[20:23], v[170:173], v[208:211], v[20:23]
	v_mfma_f32_16x16x32_bf16 v[36:39], v[170:173], v[186:189], v[36:39]
	v_mfma_f32_16x16x32_bf16 v[36:39], v[174:177], v[204:207], v[36:39]
	v_mfma_f32_16x16x32_bf16 v[52:55], v[174:177], v[182:185], v[52:55]
	v_mfma_f32_16x16x32_bf16 v[52:55], v[170:173], v[178:181], v[52:55]
	s_setprio 0
	s_barrier
	s_add_u32 s44, s44, 0x100
	s_addc_u32 s45, s45, 0
	s_add_u32 s65, s65, 0x100
	s_addc_u32 s67, s67, 0
	s_cmp_ge_i32 s72, s53
	s_mov_b32 s48, s72
	s_cbranch_scc0 .LBB0_1623

; #define PG8_STAGE(bufoff, gbase, voff) do { _Pragma("unroll") for (int _i = 0; _i < 2; ++_i) \
;         __builtin_amdgcn_global_load_lds((const unsigned*)((const char*)(gbase) + (voff)[_i]), (PG8_LAS unsigned*)(lds + (bufoff) + ldsw + _i * 8192), 16, 0, 0); } while (0)
; #define PG8_LDA(dst, b, h) do { _Pragma("unroll") for (int m = 0; m < 4; ++m) _Pragma("unroll") for (int k = 0; k < 2; ++k) dst[m][k] = *(const PG8_LAS bf16x8*)(lds + PG8_SA(b, h) + aoff + m * 2048 + k * 1024); } while (0)
; #define PG8_LDB(dst, b, h) do { _Pragma("unroll") for (int n = 0; n < 2; ++n) _Pragma("unroll") for (int k = 0; k < 2; ++k) dst[n][k] = *(const PG8_LAS bf16x8*)(lds + PG8_SB(b, h) + boff + n * 2048 + k * 1024); } while (0)
; #define PG8_WAIT_V(n) asm volatile("s_waitcnt vmcnt(" #n ")" ::: "memory")
; #define PG8_WAIT_L(n) asm volatile("s_waitcnt lgkmcnt(" #n ")" ::: "memory")
; #define PG8_BAR __builtin_amdgcn_s_barrier()
; #define PG8_SCHED __builtin_amdgcn_sched_barrier(0)
; template <class Epi, class Sched, bool ALIGN_EPI = false, bool SP2 = false, bool I8 = false>
; __device__ __forceinline__ void gemm_phase(PG8_LAS unsigned char* lds, const Gemm g, const Sched& S, const Epi& E) {
;     ...
;         for (int t = 0; t < nt; t += 2) {
;             const bool last = (t == nt - 2);
;             const char* a1 = cA + (size_t)(t + 1) * kstep;
;             const char* a2 = last ? nA : cA + (size_t)(t + 2) * kstep; const char* b2 = last ? nB : cB + (size_t)(t + 2) * kstep;
;             const char* a3 = a2 + kstep; const char* b3 = b2 + kstep;
;             if (last && has_next) S.a_ready(nxt);
;             if constexpr (SP2) {
;             PG8_LDB(B0, 0, 0); PG8_LDB(B1, 0, 1); PG8_SCHED; PG8_LDA(At, 0, 0); PG8_STAGE(PG8_SA(1, 1), a1 + hstep, voffA);
;             PG8_WAIT_V(8); PG8_WAIT_L(0); PG8_BAR; PG8_MMA(0, 0, At, B0); PG8_MMA(0, 1, At, B1); PG8_BAR; PG8_SCHED;
;             PG8_LDA(At, 0, 1); PG8_STAGE(PG8_SB(0, 0), b2, voffB); PG8_STAGE(PG8_SB(0, 1), b2 + hstep, voffB); PG8_STAGE(PG8_SA(0, 0), a2, voffA);
;             PG8_WAIT_V(8); PG8_WAIT_L(0); PG8_BAR; PG8_MMA(1, 0, At, B0); PG8_MMA(1, 1, At, B1); PG8_BAR; PG8_SCHED;
.LBB0_1699:
	s_add_u32 s53, s24, 0x100
	s_addc_u32 s54, s25, 0
	s_mov_b32 s55, -2
	s_add_u32 s24, s22, 0x100
	s_addc_u32 s25, s23, 0
	s_add_i32 s56, 0, 0x10000
	s_cmpk_eq_i32 s55, 0xa8
	s_cselect_b32 s37, s13, s25
	s_cselect_b32 s36, s12, s24
	s_cselect_b32 s27, s21, s54
	s_cselect_b32 s26, s20, s53
	s_add_i32 s57, 0, 0x14000
	v_add_u32_e32 v144, s56, v240
	v_add_u32_e32 v160, s57, v240
	ds_read_b128 v[124:127], v144
	ds_read_b128 v[128:131], v144 offset:1024
	ds_read_b128 v[132:135], v144 offset:2048
	ds_read_b128 v[144:147], v144 offset:3072
	ds_read_b128 v[148:151], v160
	ds_read_b128 v[152:155], v160 offset:1024
	ds_read_b128 v[156:159], v160 offset:2048
	ds_read_b128 v[160:163], v160 offset:3072
	v_lshl_add_u64 v[218:219], s[22:23], 0, v[210:211]
	s_add_i32 m0, s42, 0xc000
	ds_read_b128 v[164:167], v242
	ds_read_b128 v[168:171], v242 offset:1024
	ds_read_b128 v[172:175], v242 offset:2048
	ds_read_b128 v[176:179], v242 offset:3072
	ds_read_b128 v[180:183], v242 offset:4096
	ds_read_b128 v[184:187], v242 offset:5120
	ds_read_b128 v[188:191], v242 offset:6144
	ds_read_b128 v[214:217], v242 offset:7168
	global_load_lds_dwordx4 v[218:219], off
	v_lshl_add_u64 v[218:219], s[22:23], 0, v[212:213]
	s_add_i32 m0, s42, 0xe000
	s_nop 0
	global_load_lds_dwordx4 v[218:219], off
	s_waitcnt vmcnt(8)
	s_waitcnt lgkmcnt(0)
	s_barrier
	s_setprio 1
	s_waitcnt lgkmcnt(0)
	v_mfma_f32_16x16x32_bf16 v[140:143], v[124:127], v[164:167], 0
	v_mfma_f32_16x16x32_bf16 v[140:143], v[128:131], v[168:171], v[140:143]
	v_mfma_f32_16x16x32_bf16 v[112:115], v[128:131], v[176:179], 0
	v_mfma_f32_16x16x32_bf16 v[112:115], v[124:127], v[172:175], v[112:115]
	v_mfma_f32_16x16x32_bf16 v[96:99], v[124:127], v[180:183], 0
	v_mfma_f32_16x16x32_bf16 v[96:99], v[128:131], v[184:187], v[96:99]
	v_mfma_f32_16x16x32_bf16 v[80:83], v[128:131], v[214:217], 0
	v_mfma_f32_16x16x32_bf16 v[80:83], v[124:127], v[188:191], v[80:83]
	v_mfma_f32_16x16x32_bf16 v[76:79], v[132:135], v[188:191], 0
	v_mfma_f32_16x16x32_bf16 v[76:79], v[144:147], v[214:217], v[76:79]
	v_mfma_f32_16x16x32_bf16 v[92:95], v[144:147], v[184:187], 0
	v_mfma_f32_16x16x32_bf16 v[92:95], v[132:135], v[180:183], v[92:95]
	v_mfma_f32_16x16x32_bf16 v[108:111], v[132:135], v[172:175], 0
	v_mfma_f32_16x16x32_bf16 v[108:111], v[144:147], v[176:179], v[108:111]
	v_mfma_f32_16x16x32_bf16 v[136:139], v[144:147], v[168:171], 0
	v_mfma_f32_16x16x32_bf16 v[136:139], v[132:135], v[164:167], v[136:139]
	v_mfma_f32_16x16x32_bf16 v[120:123], v[148:151], v[164:167], 0
	v_mfma_f32_16x16x32_bf16 v[120:123], v[152:155], v[168:171], v[120:123]
	v_mfma_f32_16x16x32_bf16 v[104:107], v[152:155], v[176:179], 0
	v_mfma_f32_16x16x32_bf16 v[104:107], v[148:151], v[172:175], v[104:107]
	v_mfma_f32_16x16x32_bf16 v[88:91], v[148:151], v[180:183], 0
	v_mfma_f32_16x16x32_bf16 v[88:91], v[152:155], v[184:187], v[88:91]
	v_mfma_f32_16x16x32_bf16 v[72:75], v[152:155], v[214:217], 0
	v_mfma_f32_16x16x32_bf16 v[72:75], v[148:151], v[188:191], v[72:75]
	v_mfma_f32_16x16x32_bf16 v[68:71], v[156:159], v[188:191], 0
	v_mfma_f32_16x16x32_bf16 v[68:71], v[160:163], v[214:217], v[68:71]
	v_mfma_f32_16x16x32_bf16 v[84:87], v[160:163], v[184:187], 0
	v_mfma_f32_16x16x32_bf16 v[84:87], v[156:159], v[180:183], v[84:87]
	v_mfma_f32_16x16x32_bf16 v[100:103], v[156:159], v[172:175], 0
	v_mfma_f32_16x16x32_bf16 v[100:103], v[160:163], v[176:179], v[100:103]
	v_mfma_f32_16x16x32_bf16 v[116:119], v[160:163], v[168:171], 0
	v_mfma_f32_16x16x32_bf16 v[116:119], v[156:159], v[164:167], v[116:119]
	s_setprio 0
	s_barrier
	s_add_i32 s22, s56, s41
	v_lshl_add_u64 v[218:219], s[26:27], 0, v[2:3]
	s_mov_b32 m0, s22
	ds_read_b128 v[164:167], v242 offset:16384
	ds_read_b128 v[168:171], v242 offset:17408
	ds_read_b128 v[172:175], v242 offset:18432
	ds_read_b128 v[176:179], v242 offset:19456
	ds_read_b128 v[180:183], v242 offset:20480
	ds_read_b128 v[184:187], v242 offset:21504
	ds_read_b128 v[188:191], v242 offset:22528
	ds_read_b128 v[214:217], v242 offset:23552
	global_load_lds_dwordx4 v[218:219], off
	s_add_i32 m0, s22, 0x2000
	s_add_u32 s22, s26, 0x2b0000
	v_lshl_add_u64 v[220:221], s[26:27], 0, v[204:205]
	s_addc_u32 s23, s27, 0
	s_add_i32 s56, s57, s41
	global_load_lds_dwordx4 v[220:221], off
	s_mov_b32 m0, s56
	v_lshl_add_u64 v[224:225], s[36:37], 0, v[206:207]
	global_load_lds_dwordx4 v2, s[22:23]
	s_add_i32 m0, s56, 0x2000
	s_nop 0
	global_load_lds_dwordx4 v204, s[22:23]
	v_lshl_add_u64 v[222:223], s[36:37], 0, v[208:209]
	s_waitcnt vmcnt(6)
	s_waitcnt lgkmcnt(0)
	s_barrier
	s_setprio 1
	s_waitcnt lgkmcnt(0)
	v_mfma_f32_16x16x32_bf16 v[64:67], v[124:127], v[164:167], 0
	v_mfma_f32_16x16x32_bf16 v[64:67], v[128:131], v[168:171], v[64:67]
	v_mfma_f32_16x16x32_bf16 v[48:51], v[128:131], v[176:179], 0
	v_mfma_f32_16x16x32_bf16 v[48:51], v[124:127], v[172:175], v[48:51]
	v_mfma_f32_16x16x32_bf16 v[32:35], v[124:127], v[180:183], 0
	v_mfma_f32_16x16x32_bf16 v[32:35], v[128:131], v[184:187], v[32:35]
	v_mfma_f32_16x16x32_bf16 v[16:19], v[128:131], v[214:217], 0
	v_mfma_f32_16x16x32_bf16 v[16:19], v[124:127], v[188:191], v[16:19]
	v_mfma_f32_16x16x32_bf16 v[12:15], v[132:135], v[188:191], 0
	v_mfma_f32_16x16x32_bf16 v[12:15], v[144:147], v[214:217], v[12:15]
	v_mfma_f32_16x16x32_bf16 v[28:31], v[144:147], v[184:187], 0
	v_mfma_f32_16x16x32_bf16 v[28:31], v[132:135], v[180:183], v[28:31]
	v_mfma_f32_16x16x32_bf16 v[44:47], v[132:135], v[172:175], 0
	v_mfma_f32_16x16x32_bf16 v[44:47], v[144:147], v[176:179], v[44:47]
	v_mfma_f32_16x16x32_bf16 v[60:63], v[144:147], v[168:171], 0
	v_mfma_f32_16x16x32_bf16 v[60:63], v[132:135], v[164:167], v[60:63]
	v_mfma_f32_16x16x32_bf16 v[56:59], v[148:151], v[164:167], 0
	v_mfma_f32_16x16x32_bf16 v[56:59], v[152:155], v[168:171], v[56:59]
	v_mfma_f32_16x16x32_bf16 v[40:43], v[152:155], v[176:179], 0
	v_mfma_f32_16x16x32_bf16 v[40:43], v[148:151], v[172:175], v[40:43]
	v_mfma_f32_16x16x32_bf16 v[24:27], v[148:151], v[180:183], 0
	v_mfma_f32_16x16x32_bf16 v[24:27], v[152:155], v[184:187], v[24:27]
	v_mfma_f32_16x16x32_bf16 v[8:11], v[152:155], v[214:217], 0
	v_mfma_f32_16x16x32_bf16 v[8:11], v[148:151], v[188:191], v[8:11]
	v_mfma_f32_16x16x32_bf16 v[4:7], v[156:159], v[188:191], 0
	v_mfma_f32_16x16x32_bf16 v[4:7], v[160:163], v[214:217], v[4:7]
	v_mfma_f32_16x16x32_bf16 v[20:23], v[160:163], v[184:187], 0
	v_mfma_f32_16x16x32_bf16 v[20:23], v[156:159], v[180:183], v[20:23]
	v_mfma_f32_16x16x32_bf16 v[36:39], v[156:159], v[172:175], 0
	v_mfma_f32_16x16x32_bf16 v[36:39], v[160:163], v[176:179], v[36:39]
	v_mfma_f32_16x16x32_bf16 v[52:55], v[160:163], v[168:171], 0
	v_mfma_f32_16x16x32_bf16 v[52:55], v[156:159], v[164:167], v[52:55]
	s_setprio 0
	s_barrier
; #define PG8_STAGE(bufoff, gbase, voff) do { _Pragma("unroll") for (int _i = 0; _i < 2; ++_i) \
;         __builtin_amdgcn_global_load_lds((const unsigned*)((const char*)(gbase) + (voff)[_i]), (PG8_LAS unsigned*)(lds + (bufoff) + ldsw + _i * 8192), 16, 0, 0); } while (0)
; #define PG8_LDA(dst, b, h) do { _Pragma("unroll") for (int m = 0; m < 4; ++m) _Pragma("unroll") for (int k = 0; k < 2; ++k) dst[m][k] = *(const PG8_LAS bf16x8*)(lds + PG8_SA(b, h) + aoff + m * 2048 + k * 1024); } while (0)
; #define PG8_LDB(dst, b, h) do { _Pragma("unroll") for (int n = 0; n < 2; ++n) _Pragma("unroll") for (int k = 0; k < 2; ++k) dst[n][k] = *(const PG8_LAS bf16x8*)(lds + PG8_SB(b, h) + boff + n * 2048 + k * 1024); } while (0)
; #define PG8_WAIT_V(n) asm volatile("s_waitcnt vmcnt(" #n ")" ::: "memory")
; #define PG8_WAIT_L(n) asm volatile("s_waitcnt lgkmcnt(" #n ")" ::: "memory")
; #define PG8_BAR __builtin_amdgcn_s_barrier()
; #define PG8_SCHED __builtin_amdgcn_sched_barrier(0)
; template <class Epi, class Sched, bool ALIGN_EPI = false, bool SP2 = false, bool I8 = false>
; __device__ __forceinline__ void gemm_phase(PG8_LAS unsigned char* lds, const Gemm g, const Sched& S, const Epi& E) {
;     ...
;             PG8_WAIT_V(8); PG8_WAIT_L(0); PG8_BAR; PG8_MMA(1, 0, At, B0); PG8_MMA(1, 1, At, B1); PG8_BAR; PG8_SCHED;
;             PG8_LDB(B0, 1, 0); PG8_LDB(B1, 1, 1); PG8_SCHED; PG8_LDA(At, 1, 0); PG8_STAGE(PG8_SA(0, 1), a2 + hstep, voffA);
;             PG8_WAIT_V(8); PG8_WAIT_L(0); PG8_BAR; PG8_MMA(0, 0, At, B0); PG8_MMA(0, 1, At, B1); PG8_BAR; PG8_SCHED;
;             PG8_LDA(At, 1, 1); PG8_STAGE(PG8_SB(1, 0), b3, voffB); PG8_STAGE(PG8_SB(1, 1), b3 + hstep, voffB); PG8_STAGE(PG8_SA(1, 0), a3, voffA);
;             PG8_WAIT_V(8); PG8_WAIT_L(0); PG8_BAR; PG8_MMA(1, 0, At, B0); PG8_MMA(1, 1, At, B1); PG8_BAR; PG8_SCHED;
	s_mov_b32 m0, s42
	s_nop 0
	global_load_lds_dwordx4 v[222:223], off
	s_mov_b32 m0, s43
	s_nop 0
	global_load_lds_dwordx4 v[224:225], off
	s_add_i32 s56, 0, 0x18000
	s_add_i32 s57, 0, 0x1c000
	v_add_u32_e32 v144, s56, v240
	v_add_u32_e32 v160, s57, v240
	ds_read_b128 v[124:127], v144
	ds_read_b128 v[128:131], v144 offset:1024
	ds_read_b128 v[132:135], v144 offset:2048
	ds_read_b128 v[144:147], v144 offset:3072
	ds_read_b128 v[148:151], v160
	ds_read_b128 v[152:155], v160 offset:1024
	ds_read_b128 v[156:159], v160 offset:2048
	ds_read_b128 v[160:163], v160 offset:3072
	s_add_u32 s22, s36, 0x2b0000
	s_addc_u32 s23, s37, 0
	s_mov_b32 m0, s44
	ds_read_b128 v[164:167], v242 offset:32768
	ds_read_b128 v[168:171], v242 offset:33792
	ds_read_b128 v[172:175], v242 offset:34816
	ds_read_b128 v[176:179], v242 offset:35840
	ds_read_b128 v[180:183], v242 offset:36864
	ds_read_b128 v[184:187], v242 offset:37888
	ds_read_b128 v[188:191], v242 offset:38912
	ds_read_b128 v[214:217], v242 offset:39936
	global_load_lds_dwordx4 v208, s[22:23]
	s_mov_b32 m0, s45
	s_nop 0
	global_load_lds_dwordx4 v206, s[22:23]
	s_waitcnt vmcnt(8)
	s_waitcnt lgkmcnt(0)
	s_barrier
	s_setprio 1
	s_waitcnt lgkmcnt(0)
	v_mfma_f32_16x16x32_bf16 v[140:143], v[124:127], v[164:167], v[140:143]
	v_mfma_f32_16x16x32_bf16 v[140:143], v[128:131], v[168:171], v[140:143]
	v_mfma_f32_16x16x32_bf16 v[112:115], v[128:131], v[176:179], v[112:115]
	v_mfma_f32_16x16x32_bf16 v[112:115], v[124:127], v[172:175], v[112:115]
	v_mfma_f32_16x16x32_bf16 v[96:99], v[124:127], v[180:183], v[96:99]
	v_mfma_f32_16x16x32_bf16 v[96:99], v[128:131], v[184:187], v[96:99]
	v_mfma_f32_16x16x32_bf16 v[80:83], v[128:131], v[214:217], v[80:83]
	v_mfma_f32_16x16x32_bf16 v[80:83], v[124:127], v[188:191], v[80:83]
	v_mfma_f32_16x16x32_bf16 v[76:79], v[132:135], v[188:191], v[76:79]
	v_mfma_f32_16x16x32_bf16 v[76:79], v[144:147], v[214:217], v[76:79]
	v_mfma_f32_16x16x32_bf16 v[92:95], v[144:147], v[184:187], v[92:95]
	v_mfma_f32_16x16x32_bf16 v[92:95], v[132:135], v[180:183], v[92:95]
	v_mfma_f32_16x16x32_bf16 v[108:111], v[132:135], v[172:175], v[108:111]
	v_mfma_f32_16x16x32_bf16 v[108:111], v[144:147], v[176:179], v[108:111]
	v_mfma_f32_16x16x32_bf16 v[136:139], v[144:147], v[168:171], v[136:139]
	v_mfma_f32_16x16x32_bf16 v[136:139], v[132:135], v[164:167], v[136:139]
	v_mfma_f32_16x16x32_bf16 v[120:123], v[148:151], v[164:167], v[120:123]
	v_mfma_f32_16x16x32_bf16 v[120:123], v[152:155], v[168:171], v[120:123]
	v_mfma_f32_16x16x32_bf16 v[104:107], v[152:155], v[176:179], v[104:107]
	v_mfma_f32_16x16x32_bf16 v[104:107], v[148:151], v[172:175], v[104:107]
	v_mfma_f32_16x16x32_bf16 v[88:91], v[148:151], v[180:183], v[88:91]
	v_mfma_f32_16x16x32_bf16 v[88:91], v[152:155], v[184:187], v[88:91]
	v_mfma_f32_16x16x32_bf16 v[72:75], v[152:155], v[214:217], v[72:75]
	v_mfma_f32_16x16x32_bf16 v[72:75], v[148:151], v[188:191], v[72:75]
	v_mfma_f32_16x16x32_bf16 v[68:71], v[156:159], v[188:191], v[68:71]
	v_mfma_f32_16x16x32_bf16 v[68:71], v[160:163], v[214:217], v[68:71]
	v_mfma_f32_16x16x32_bf16 v[84:87], v[160:163], v[184:187], v[84:87]
	v_mfma_f32_16x16x32_bf16 v[84:87], v[156:159], v[180:183], v[84:87]
	v_mfma_f32_16x16x32_bf16 v[100:103], v[156:159], v[172:175], v[100:103]
	v_mfma_f32_16x16x32_bf16 v[100:103], v[160:163], v[176:179], v[100:103]
	v_mfma_f32_16x16x32_bf16 v[116:119], v[160:163], v[168:171], v[116:119]
	v_mfma_f32_16x16x32_bf16 v[116:119], v[156:159], v[164:167], v[116:119]
	s_setprio 0
	s_barrier
	s_add_i32 s22, s56, s41
	v_lshl_add_u64 v[218:219], v[218:219], 0, s[84:85]
	s_mov_b32 m0, s22
	ds_read_b128 v[164:167], v242 offset:49152
	ds_read_b128 v[168:171], v242 offset:50176
	ds_read_b128 v[172:175], v242 offset:51200
	ds_read_b128 v[176:179], v242 offset:52224
	ds_read_b128 v[180:183], v242 offset:53248
	ds_read_b128 v[184:187], v242 offset:54272
	ds_read_b128 v[188:191], v242 offset:55296
	ds_read_b128 v[214:217], v242 offset:56320
	global_load_lds_dwordx4 v[218:219], off
	s_add_i32 m0, s22, 0x2000
	s_add_u32 s22, s26, 0x2b0080
	v_lshl_add_u64 v[218:219], v[220:221], 0, s[84:85]
	s_addc_u32 s23, s27, 0
	s_add_i32 s26, s57, s41
	global_load_lds_dwordx4 v[218:219], off
	s_mov_b32 m0, s26
	s_nop 0
	global_load_lds_dwordx4 v2, s[22:23]
	s_add_i32 m0, s26, 0x2000
	s_nop 0
	global_load_lds_dwordx4 v204, s[22:23]
	s_cmpk_eq_i32 s55, 0xa8
	s_cbranch_scc0 .Ldefer_1700_peel
	v_lshl_add_u64 v[218:219], v[222:223], 0, s[84:85]
	s_mov_b32 m0, s46
	s_nop 0
	global_load_lds_dwordx4 v[218:219], off
	v_lshl_add_u64 v[218:219], v[224:225], 0, s[84:85]
	s_mov_b32 m0, s47
	s_nop 0
	global_load_lds_dwordx4 v[218:219], off

; #define PG8_STAGE(bufoff, gbase, voff) do { _Pragma("unroll") for (int _i = 0; _i < 2; ++_i) \
;         __builtin_amdgcn_global_load_lds((const unsigned*)((const char*)(gbase) + (voff)[_i]), (PG8_LAS unsigned*)(lds + (bufoff) + ldsw + _i * 8192), 16, 0, 0); } while (0)
; #define PG8_LDA(dst, b, h) do { _Pragma("unroll") for (int m = 0; m < 4; ++m) _Pragma("unroll") for (int k = 0; k < 2; ++k) dst[m][k] = *(const PG8_LAS bf16x8*)(lds + PG8_SA(b, h) + aoff + m * 2048 + k * 1024); } while (0)
; #define PG8_LDB(dst, b, h) do { _Pragma("unroll") for (int n = 0; n < 2; ++n) _Pragma("unroll") for (int k = 0; k < 2; ++k) dst[n][k] = *(const PG8_LAS bf16x8*)(lds + PG8_SB(b, h) + boff + n * 2048 + k * 1024); } while (0)
; #define PG8_WAIT_V(n) asm volatile("s_waitcnt vmcnt(" #n ")" ::: "memory")
; #define PG8_WAIT_L(n) asm volatile("s_waitcnt lgkmcnt(" #n ")" ::: "memory")
; #define PG8_BAR __builtin_amdgcn_s_barrier()
; #define PG8_SCHED __builtin_amdgcn_sched_barrier(0)
; template <class Epi, class Sched, bool ALIGN_EPI = false, bool SP2 = false, bool I8 = false>
; __device__ __forceinline__ void gemm_phase(PG8_LAS unsigned char* lds, const Gemm g, const Sched& S, const Epi& E) {
;     ...
;         for (int t = 0; t < nt; t += 2) {
;             const bool last = (t == nt - 2);
;             const char* a1 = cA + (size_t)(t + 1) * kstep;
;             const char* a2 = last ? nA : cA + (size_t)(t + 2) * kstep; const char* b2 = last ? nB : cB + (size_t)(t + 2) * kstep;
;             const char* a3 = a2 + kstep; const char* b3 = b2 + kstep;
;             if (last && has_next) S.a_ready(nxt);
;             if constexpr (SP2) {
;             PG8_LDB(B0, 0, 0); PG8_LDB(B1, 0, 1); PG8_SCHED; PG8_LDA(At, 0, 0); PG8_STAGE(PG8_SA(1, 1), a1 + hstep, voffA);
;             PG8_WAIT_V(8); PG8_WAIT_L(0); PG8_BAR; PG8_MMA(0, 0, At, B0); PG8_MMA(0, 1, At, B1); PG8_BAR; PG8_SCHED;
;             PG8_LDA(At, 0, 1); PG8_STAGE(PG8_SB(0, 0), b2, voffB); PG8_STAGE(PG8_SB(0, 1), b2 + hstep, voffB); PG8_STAGE(PG8_SA(0, 0), a2, voffA);
;             PG8_WAIT_V(8); PG8_WAIT_L(0); PG8_BAR; PG8_MMA(1, 0, At, B0); PG8_MMA(1, 1, At, B1); PG8_BAR; PG8_SCHED;
.LBB0_1700:
	s_add_u32 s24, s22, 0x100
	s_addc_u32 s25, s23, 0
	s_add_i32 s56, 0, 0x10000
	s_cmpk_eq_i32 s55, 0xa8
	s_cselect_b32 s37, s13, s25
	s_cselect_b32 s36, s12, s24
	s_cselect_b32 s27, s21, s54
	s_cselect_b32 s26, s20, s53
	s_add_i32 s57, 0, 0x14000
	v_add_u32_e32 v144, s56, v240
	v_add_u32_e32 v160, s57, v240
	ds_read_b128 v[124:127], v144
	ds_read_b128 v[128:131], v144 offset:1024
	ds_read_b128 v[132:135], v144 offset:2048
	ds_read_b128 v[144:147], v144 offset:3072
	ds_read_b128 v[148:151], v160
	ds_read_b128 v[152:155], v160 offset:1024
	ds_read_b128 v[156:159], v160 offset:2048
	ds_read_b128 v[160:163], v160 offset:3072
	v_lshl_add_u64 v[218:219], v[222:223], 0, s[84:85]
	s_mov_b32 m0, s46
	s_nop 0
	global_load_lds_dwordx4 v[218:219], off
	v_lshl_add_u64 v[218:219], v[224:225], 0, s[84:85]
	s_mov_b32 m0, s47
	s_nop 0
	global_load_lds_dwordx4 v[218:219], off
	v_lshl_add_u64 v[218:219], s[22:23], 0, v[210:211]
	s_add_i32 m0, s42, 0xc000
	ds_read_b128 v[164:167], v242
	ds_read_b128 v[168:171], v242 offset:1024
	ds_read_b128 v[172:175], v242 offset:2048
	ds_read_b128 v[176:179], v242 offset:3072
	ds_read_b128 v[180:183], v242 offset:4096
	ds_read_b128 v[184:187], v242 offset:5120
	ds_read_b128 v[188:191], v242 offset:6144
	ds_read_b128 v[214:217], v242 offset:7168
	global_load_lds_dwordx4 v[218:219], off
	v_lshl_add_u64 v[218:219], s[22:23], 0, v[212:213]
	s_add_i32 m0, s42, 0xe000
	s_nop 0
	global_load_lds_dwordx4 v[218:219], off
	s_waitcnt vmcnt(8)
	s_waitcnt lgkmcnt(0)
	s_barrier
	s_setprio 1
	s_waitcnt lgkmcnt(0)
	v_mfma_f32_16x16x32_bf16 v[140:143], v[124:127], v[164:167], v[140:143]
	v_mfma_f32_16x16x32_bf16 v[140:143], v[128:131], v[168:171], v[140:143]
	v_mfma_f32_16x16x32_bf16 v[112:115], v[128:131], v[176:179], v[112:115]
	v_mfma_f32_16x16x32_bf16 v[112:115], v[124:127], v[172:175], v[112:115]
	v_mfma_f32_16x16x32_bf16 v[96:99], v[124:127], v[180:183], v[96:99]
	v_mfma_f32_16x16x32_bf16 v[96:99], v[128:131], v[184:187], v[96:99]
	v_mfma_f32_16x16x32_bf16 v[80:83], v[128:131], v[214:217], v[80:83]
	v_mfma_f32_16x16x32_bf16 v[80:83], v[124:127], v[188:191], v[80:83]
	v_mfma_f32_16x16x32_bf16 v[76:79], v[132:135], v[188:191], v[76:79]
	v_mfma_f32_16x16x32_bf16 v[76:79], v[144:147], v[214:217], v[76:79]
	v_mfma_f32_16x16x32_bf16 v[92:95], v[144:147], v[184:187], v[92:95]
	v_mfma_f32_16x16x32_bf16 v[92:95], v[132:135], v[180:183], v[92:95]
	v_mfma_f32_16x16x32_bf16 v[108:111], v[132:135], v[172:175], v[108:111]
	v_mfma_f32_16x16x32_bf16 v[108:111], v[144:147], v[176:179], v[108:111]
	v_mfma_f32_16x16x32_bf16 v[136:139], v[144:147], v[168:171], v[136:139]
	v_mfma_f32_16x16x32_bf16 v[136:139], v[132:135], v[164:167], v[136:139]
	v_mfma_f32_16x16x32_bf16 v[120:123], v[148:151], v[164:167], v[120:123]
	v_mfma_f32_16x16x32_bf16 v[120:123], v[152:155], v[168:171], v[120:123]
	v_mfma_f32_16x16x32_bf16 v[104:107], v[152:155], v[176:179], v[104:107]
	v_mfma_f32_16x16x32_bf16 v[104:107], v[148:151], v[172:175], v[104:107]
	v_mfma_f32_16x16x32_bf16 v[88:91], v[148:151], v[180:183], v[88:91]
	v_mfma_f32_16x16x32_bf16 v[88:91], v[152:155], v[184:187], v[88:91]
	v_mfma_f32_16x16x32_bf16 v[72:75], v[152:155], v[214:217], v[72:75]
	v_mfma_f32_16x16x32_bf16 v[72:75], v[148:151], v[188:191], v[72:75]
	v_mfma_f32_16x16x32_bf16 v[68:71], v[156:159], v[188:191], v[68:71]
	v_mfma_f32_16x16x32_bf16 v[68:71], v[160:163], v[214:217], v[68:71]
	v_mfma_f32_16x16x32_bf16 v[84:87], v[160:163], v[184:187], v[84:87]
	v_mfma_f32_16x16x32_bf16 v[84:87], v[156:159], v[180:183], v[84:87]
	v_mfma_f32_16x16x32_bf16 v[100:103], v[156:159], v[172:175], v[100:103]
	v_mfma_f32_16x16x32_bf16 v[100:103], v[160:163], v[176:179], v[100:103]
	v_mfma_f32_16x16x32_bf16 v[116:119], v[160:163], v[168:171], v[116:119]
	v_mfma_f32_16x16x32_bf16 v[116:119], v[156:159], v[164:167], v[116:119]
	s_setprio 0
	s_barrier
	s_add_i32 s22, s56, s41
	v_lshl_add_u64 v[218:219], s[26:27], 0, v[2:3]
	s_mov_b32 m0, s22
	ds_read_b128 v[164:167], v242 offset:16384
	ds_read_b128 v[168:171], v242 offset:17408
	ds_read_b128 v[172:175], v242 offset:18432
	ds_read_b128 v[176:179], v242 offset:19456
	ds_read_b128 v[180:183], v242 offset:20480
	ds_read_b128 v[184:187], v242 offset:21504
	ds_read_b128 v[188:191], v242 offset:22528
	ds_read_b128 v[214:217], v242 offset:23552
	global_load_lds_dwordx4 v[218:219], off
	s_add_i32 m0, s22, 0x2000
	s_add_u32 s22, s26, 0x2b0000
	v_lshl_add_u64 v[220:221], s[26:27], 0, v[204:205]
	s_addc_u32 s23, s27, 0
	s_add_i32 s56, s57, s41
	global_load_lds_dwordx4 v[220:221], off
	s_mov_b32 m0, s56
	v_lshl_add_u64 v[224:225], s[36:37], 0, v[206:207]
	global_load_lds_dwordx4 v2, s[22:23]
	s_add_i32 m0, s56, 0x2000
	s_nop 0
	global_load_lds_dwordx4 v204, s[22:23]
	v_lshl_add_u64 v[222:223], s[36:37], 0, v[208:209]
	s_waitcnt vmcnt(6)
	s_waitcnt lgkmcnt(0)
	s_barrier
; #define PG8_STAGE(bufoff, gbase, voff) do { _Pragma("unroll") for (int _i = 0; _i < 2; ++_i) \
;         __builtin_amdgcn_global_load_lds((const unsigned*)((const char*)(gbase) + (voff)[_i]), (PG8_LAS unsigned*)(lds + (bufoff) + ldsw + _i * 8192), 16, 0, 0); } while (0)
; #define PG8_LDA(dst, b, h) do { _Pragma("unroll") for (int m = 0; m < 4; ++m) _Pragma("unroll") for (int k = 0; k < 2; ++k) dst[m][k] = *(const PG8_LAS bf16x8*)(lds + PG8_SA(b, h) + aoff + m * 2048 + k * 1024); } while (0)
; #define PG8_LDB(dst, b, h) do { _Pragma("unroll") for (int n = 0; n < 2; ++n) _Pragma("unroll") for (int k = 0; k < 2; ++k) dst[n][k] = *(const PG8_LAS bf16x8*)(lds + PG8_SB(b, h) + boff + n * 2048 + k * 1024); } while (0)
; #define PG8_WAIT_V(n) asm volatile("s_waitcnt vmcnt(" #n ")" ::: "memory")
; #define PG8_WAIT_L(n) asm volatile("s_waitcnt lgkmcnt(" #n ")" ::: "memory")
; #define PG8_BAR __builtin_amdgcn_s_barrier()
; #define PG8_SCHED __builtin_amdgcn_sched_barrier(0)
; template <class Epi, class Sched, bool ALIGN_EPI = false, bool SP2 = false, bool I8 = false>
; __device__ __forceinline__ void gemm_phase(PG8_LAS unsigned char* lds, const Gemm g, const Sched& S, const Epi& E) {
;     ...
;             PG8_WAIT_V(8); PG8_WAIT_L(0); PG8_BAR; PG8_MMA(1, 0, At, B0); PG8_MMA(1, 1, At, B1); PG8_BAR; PG8_SCHED;
;             PG8_LDB(B0, 1, 0); PG8_LDB(B1, 1, 1); PG8_SCHED; PG8_LDA(At, 1, 0); PG8_STAGE(PG8_SA(0, 1), a2 + hstep, voffA);
;             PG8_WAIT_V(8); PG8_WAIT_L(0); PG8_BAR; PG8_MMA(0, 0, At, B0); PG8_MMA(0, 1, At, B1); PG8_BAR; PG8_SCHED;
;             PG8_LDA(At, 1, 1); PG8_STAGE(PG8_SB(1, 0), b3, voffB); PG8_STAGE(PG8_SB(1, 1), b3 + hstep, voffB); PG8_STAGE(PG8_SA(1, 0), a3, voffA);
;             PG8_WAIT_V(8); PG8_WAIT_L(0); PG8_BAR; PG8_MMA(1, 0, At, B0); PG8_MMA(1, 1, At, B1); PG8_BAR; PG8_SCHED;
	s_setprio 1
	s_waitcnt lgkmcnt(0)
	v_mfma_f32_16x16x32_bf16 v[64:67], v[124:127], v[164:167], v[64:67]
	v_mfma_f32_16x16x32_bf16 v[64:67], v[128:131], v[168:171], v[64:67]
	v_mfma_f32_16x16x32_bf16 v[48:51], v[128:131], v[176:179], v[48:51]
	v_mfma_f32_16x16x32_bf16 v[48:51], v[124:127], v[172:175], v[48:51]
	v_mfma_f32_16x16x32_bf16 v[32:35], v[124:127], v[180:183], v[32:35]
	v_mfma_f32_16x16x32_bf16 v[32:35], v[128:131], v[184:187], v[32:35]
	v_mfma_f32_16x16x32_bf16 v[16:19], v[128:131], v[214:217], v[16:19]
	v_mfma_f32_16x16x32_bf16 v[16:19], v[124:127], v[188:191], v[16:19]
	v_mfma_f32_16x16x32_bf16 v[12:15], v[132:135], v[188:191], v[12:15]
	v_mfma_f32_16x16x32_bf16 v[12:15], v[144:147], v[214:217], v[12:15]
	v_mfma_f32_16x16x32_bf16 v[28:31], v[144:147], v[184:187], v[28:31]
	v_mfma_f32_16x16x32_bf16 v[28:31], v[132:135], v[180:183], v[28:31]
	v_mfma_f32_16x16x32_bf16 v[44:47], v[132:135], v[172:175], v[44:47]
	v_mfma_f32_16x16x32_bf16 v[44:47], v[144:147], v[176:179], v[44:47]
	v_mfma_f32_16x16x32_bf16 v[60:63], v[144:147], v[168:171], v[60:63]
	v_mfma_f32_16x16x32_bf16 v[60:63], v[132:135], v[164:167], v[60:63]
	v_mfma_f32_16x16x32_bf16 v[56:59], v[148:151], v[164:167], v[56:59]
	v_mfma_f32_16x16x32_bf16 v[56:59], v[152:155], v[168:171], v[56:59]
	v_mfma_f32_16x16x32_bf16 v[40:43], v[152:155], v[176:179], v[40:43]
	v_mfma_f32_16x16x32_bf16 v[40:43], v[148:151], v[172:175], v[40:43]
	v_mfma_f32_16x16x32_bf16 v[24:27], v[148:151], v[180:183], v[24:27]
	v_mfma_f32_16x16x32_bf16 v[24:27], v[152:155], v[184:187], v[24:27]
	v_mfma_f32_16x16x32_bf16 v[8:11], v[152:155], v[214:217], v[8:11]
	v_mfma_f32_16x16x32_bf16 v[8:11], v[148:151], v[188:191], v[8:11]
	v_mfma_f32_16x16x32_bf16 v[4:7], v[156:159], v[188:191], v[4:7]
	v_mfma_f32_16x16x32_bf16 v[4:7], v[160:163], v[214:217], v[4:7]
	v_mfma_f32_16x16x32_bf16 v[20:23], v[160:163], v[184:187], v[20:23]
	v_mfma_f32_16x16x32_bf16 v[20:23], v[156:159], v[180:183], v[20:23]
	v_mfma_f32_16x16x32_bf16 v[36:39], v[156:159], v[172:175], v[36:39]
	v_mfma_f32_16x16x32_bf16 v[36:39], v[160:163], v[176:179], v[36:39]
	v_mfma_f32_16x16x32_bf16 v[52:55], v[160:163], v[168:171], v[52:55]
	v_mfma_f32_16x16x32_bf16 v[52:55], v[156:159], v[164:167], v[52:55]
	s_setprio 0
	s_barrier
	s_mov_b32 m0, s42
	s_nop 0
	global_load_lds_dwordx4 v[222:223], off
	s_mov_b32 m0, s43
	s_nop 0
	global_load_lds_dwordx4 v[224:225], off
	s_add_i32 s56, 0, 0x18000
	s_add_i32 s57, 0, 0x1c000
	v_add_u32_e32 v144, s56, v240
	v_add_u32_e32 v160, s57, v240
	ds_read_b128 v[124:127], v144
	ds_read_b128 v[128:131], v144 offset:1024
	ds_read_b128 v[132:135], v144 offset:2048
	ds_read_b128 v[144:147], v144 offset:3072
	ds_read_b128 v[148:151], v160
	ds_read_b128 v[152:155], v160 offset:1024
	ds_read_b128 v[156:159], v160 offset:2048
	ds_read_b128 v[160:163], v160 offset:3072
	s_add_u32 s22, s36, 0x2b0000
	s_addc_u32 s23, s37, 0
	s_mov_b32 m0, s44
	ds_read_b128 v[164:167], v242 offset:32768
	ds_read_b128 v[168:171], v242 offset:33792
	ds_read_b128 v[172:175], v242 offset:34816
	ds_read_b128 v[176:179], v242 offset:35840
	ds_read_b128 v[180:183], v242 offset:36864
	ds_read_b128 v[184:187], v242 offset:37888
	ds_read_b128 v[188:191], v242 offset:38912
	ds_read_b128 v[214:217], v242 offset:39936
	global_load_lds_dwordx4 v208, s[22:23]
	s_mov_b32 m0, s45
	s_nop 0
	global_load_lds_dwordx4 v206, s[22:23]
	s_waitcnt vmcnt(8)
	s_waitcnt lgkmcnt(0)
	s_barrier
	s_setprio 1
	s_waitcnt lgkmcnt(0)
	v_mfma_f32_16x16x32_bf16 v[140:143], v[124:127], v[164:167], v[140:143]
	v_mfma_f32_16x16x32_bf16 v[140:143], v[128:131], v[168:171], v[140:143]
	v_mfma_f32_16x16x32_bf16 v[112:115], v[128:131], v[176:179], v[112:115]
	v_mfma_f32_16x16x32_bf16 v[112:115], v[124:127], v[172:175], v[112:115]
	v_mfma_f32_16x16x32_bf16 v[96:99], v[124:127], v[180:183], v[96:99]
	v_mfma_f32_16x16x32_bf16 v[96:99], v[128:131], v[184:187], v[96:99]
	v_mfma_f32_16x16x32_bf16 v[80:83], v[128:131], v[214:217], v[80:83]
	v_mfma_f32_16x16x32_bf16 v[80:83], v[124:127], v[188:191], v[80:83]
	v_mfma_f32_16x16x32_bf16 v[76:79], v[132:135], v[188:191], v[76:79]
	v_mfma_f32_16x16x32_bf16 v[76:79], v[144:147], v[214:217], v[76:79]
	v_mfma_f32_16x16x32_bf16 v[92:95], v[144:147], v[184:187], v[92:95]
	v_mfma_f32_16x16x32_bf16 v[92:95], v[132:135], v[180:183], v[92:95]
	v_mfma_f32_16x16x32_bf16 v[108:111], v[132:135], v[172:175], v[108:111]
	v_mfma_f32_16x16x32_bf16 v[108:111], v[144:147], v[176:179], v[108:111]
	v_mfma_f32_16x16x32_bf16 v[136:139], v[144:147], v[168:171], v[136:139]
	v_mfma_f32_16x16x32_bf16 v[136:139], v[132:135], v[164:167], v[136:139]
	v_mfma_f32_16x16x32_bf16 v[120:123], v[148:151], v[164:167], v[120:123]
	v_mfma_f32_16x16x32_bf16 v[120:123], v[152:155], v[168:171], v[120:123]
	v_mfma_f32_16x16x32_bf16 v[104:107], v[152:155], v[176:179], v[104:107]
	v_mfma_f32_16x16x32_bf16 v[104:107], v[148:151], v[172:175], v[104:107]
	v_mfma_f32_16x16x32_bf16 v[88:91], v[148:151], v[180:183], v[88:91]
	v_mfma_f32_16x16x32_bf16 v[88:91], v[152:155], v[184:187], v[88:91]
	v_mfma_f32_16x16x32_bf16 v[72:75], v[152:155], v[214:217], v[72:75]
	v_mfma_f32_16x16x32_bf16 v[72:75], v[148:151], v[188:191], v[72:75]
	v_mfma_f32_16x16x32_bf16 v[68:71], v[156:159], v[188:191], v[68:71]
	v_mfma_f32_16x16x32_bf16 v[68:71], v[160:163], v[214:217], v[68:71]
	v_mfma_f32_16x16x32_bf16 v[84:87], v[160:163], v[184:187], v[84:87]
	v_mfma_f32_16x16x32_bf16 v[84:87], v[156:159], v[180:183], v[84:87]
	v_mfma_f32_16x16x32_bf16 v[100:103], v[156:159], v[172:175], v[100:103]
	v_mfma_f32_16x16x32_bf16 v[100:103], v[160:163], v[176:179], v[100:103]
	v_mfma_f32_16x16x32_bf16 v[116:119], v[160:163], v[168:171], v[116:119]
	v_mfma_f32_16x16x32_bf16 v[116:119], v[156:159], v[164:167], v[116:119]
	s_setprio 0
	s_barrier
	s_add_i32 s22, s56, s41
	v_lshl_add_u64 v[218:219], v[218:219], 0, s[84:85]
	s_mov_b32 m0, s22
	ds_read_b128 v[164:167], v242 offset:49152
	ds_read_b128 v[168:171], v242 offset:50176
	ds_read_b128 v[172:175], v242 offset:51200
	ds_read_b128 v[176:179], v242 offset:52224
	ds_read_b128 v[180:183], v242 offset:53248
	ds_read_b128 v[184:187], v242 offset:54272
	ds_read_b128 v[188:191], v242 offset:55296
	ds_read_b128 v[214:217], v242 offset:56320
	global_load_lds_dwordx4 v[218:219], off
	s_add_i32 m0, s22, 0x2000
	s_add_u32 s22, s26, 0x2b0080
	v_lshl_add_u64 v[218:219], v[220:221], 0, s[84:85]
	s_addc_u32 s23, s27, 0
	s_add_i32 s26, s57, s41
	global_load_lds_dwordx4 v[218:219], off
	s_mov_b32 m0, s26
	s_nop 0
	global_load_lds_dwordx4 v2, s[22:23]
	s_add_i32 m0, s26, 0x2000
	s_nop 0
	global_load_lds_dwordx4 v204, s[22:23]
	s_cmpk_eq_i32 s55, 0xa8
	s_cbranch_scc0 .Ldefer_1700_body
	v_lshl_add_u64 v[218:219], v[222:223], 0, s[84:85]
	s_mov_b32 m0, s46
	s_nop 0
	global_load_lds_dwordx4 v[218:219], off
	v_lshl_add_u64 v[218:219], v[224:225], 0, s[84:85]
	s_mov_b32 m0, s47
	s_nop 0
	global_load_lds_dwordx4 v[218:219], off

; #define PG8_STAGE(bufoff, gbase, voff) do { _Pragma("unroll") for (int _i = 0; _i < 2; ++_i) \
;         __builtin_amdgcn_global_load_lds((const unsigned*)((const char*)(gbase) + (voff)[_i]), (PG8_LAS unsigned*)(lds + (bufoff) + ldsw + _i * 8192), 16, 0, 0); } while (0)
; #define PG8_LDA(dst, b, h) do { _Pragma("unroll") for (int m = 0; m < 4; ++m) _Pragma("unroll") for (int k = 0; k < 2; ++k) dst[m][k] = *(const PG8_LAS bf16x8*)(lds + PG8_SA(b, h) + aoff + m * 2048 + k * 1024); } while (0)
; #define PG8_LDB(dst, b, h) do { _Pragma("unroll") for (int n = 0; n < 2; ++n) _Pragma("unroll") for (int k = 0; k < 2; ++k) dst[n][k] = *(const PG8_LAS bf16x8*)(lds + PG8_SB(b, h) + boff + n * 2048 + k * 1024); } while (0)
; #define PG8_WAIT_V(n) asm volatile("s_waitcnt vmcnt(" #n ")" ::: "memory")
; #define PG8_WAIT_L(n) asm volatile("s_waitcnt lgkmcnt(" #n ")" ::: "memory")
; #define PG8_BAR __builtin_amdgcn_s_barrier()
; #define PG8_SCHED __builtin_amdgcn_sched_barrier(0)
; template <class Epi, class Sched, bool ALIGN_EPI = false, bool SP2 = false, bool I8 = false>
; __device__ __forceinline__ void gemm_phase(PG8_LAS unsigned char* lds, const Gemm g, const Sched& S, const Epi& E) {
;     ...
;         const bool has_next = S.next(ui + 1, nxt);
;         const char* nA = has_next ? (const char*)g.A + (size_t)nxt.pm * tstep : cA; const char* nB = has_next ? (const char*)g.Bt + (size_t)nxt.pn * tstep : cB;
;         for (int t = 0; t < nt; t += 2) {
;             const bool last = (t == nt - 2);
;             const char* a1 = cA + (size_t)(t + 1) * kstep;
;             const char* a2 = last ? nA : cA + (size_t)(t + 2) * kstep; const char* b2 = last ? nB : cB + (size_t)(t + 2) * kstep;
;             const char* a3 = a2 + kstep; const char* b3 = b2 + kstep;
;             if (last && has_next) S.a_ready(nxt);
;             if constexpr (SP2) {
;             PG8_LDB(B0, 0, 0); PG8_LDB(B1, 0, 1); PG8_SCHED; PG8_LDA(At, 0, 0); PG8_STAGE(PG8_SA(1, 1), a1 + hstep, voffA);
;             PG8_WAIT_V(8); PG8_WAIT_L(0); PG8_BAR; PG8_MMA(0, 0, At, B0); PG8_MMA(0, 1, At, B1); PG8_BAR; PG8_SCHED;
;             PG8_LDA(At, 0, 1); PG8_STAGE(PG8_SB(0, 0), b2, voffB); PG8_STAGE(PG8_SB(0, 1), b2 + hstep, voffB); PG8_STAGE(PG8_SA(0, 0), a2, voffA);
;             PG8_WAIT_V(8); PG8_WAIT_L(0); PG8_BAR; PG8_MMA(1, 0, At, B0); PG8_MMA(1, 1, At, B1); PG8_BAR; PG8_SCHED;
.LBB0_1842:
	s_ashr_i32 s45, s44, 31
	s_lshl_b64 s[34:35], s[44:45], 20
	s_add_u32 s50, s47, s34
	s_addc_u32 s51, s52, s35
	s_and_b64 s[34:35], s[8:9], exec
	s_cselect_b32 s11, s51, s55
	s_cselect_b32 s13, s50, s54
	s_ashr_i32 s49, s48, 31
	s_lshl_b64 s[34:35], s[48:49], 20
	s_add_u32 s56, s53, s34
	s_addc_u32 s57, s64, s35
	s_and_b64 s[34:35], s[8:9], exec
	s_cselect_b32 s34, s57, s59
	s_cselect_b32 s35, s56, s58
	s_add_u32 s54, s54, 0x80080
	s_addc_u32 s55, s55, 0
	s_add_u32 s45, s58, 0x100
	s_addc_u32 s49, s59, 0
	s_mov_b32 s86, -2
	s_waitcnt lgkmcnt(0)
	s_add_u32 s58, s54, 0xfff80080
	s_addc_u32 s59, s55, -1
	s_add_i32 s87, 0, 0x10000
	s_cmp_eq_u32 s86, 28
	s_cselect_b32 s61, s11, s59
	s_cselect_b32 s60, s13, s58
	s_cselect_b32 s59, s34, s49
	s_cselect_b32 s58, s35, s45
	s_add_i32 vcc_lo, 0, 0x14000
	v_add_u32_e32 v40, s87, v217
	v_add_u32_e32 v160, vcc_lo, v217
	ds_read_b128 v[28:31], v40
	ds_read_b128 v[32:35], v40 offset:1024
	ds_read_b128 v[36:39], v40 offset:2048
	ds_read_b128 v[40:43], v40 offset:3072
	ds_read_b128 v[140:143], v160
	ds_read_b128 v[144:147], v160 offset:1024
	ds_read_b128 v[156:159], v160 offset:2048
	ds_read_b128 v[160:163], v160 offset:3072
	s_add_i32 m0, s65, 0xc000
	ds_read_b128 v[164:167], v219
	ds_read_b128 v[168:171], v219 offset:1024
	ds_read_b128 v[172:175], v219 offset:2048
	ds_read_b128 v[176:179], v219 offset:3072
	ds_read_b128 v[204:207], v219 offset:4096
	ds_read_b128 v[208:211], v219 offset:5120
	ds_read_b128 v[212:215], v219 offset:6144
	ds_read_b128 v[220:223], v219 offset:7168
	global_load_lds_dwordx4 v186, s[54:55]
	s_add_i32 m0, s65, 0xe000
	s_nop 0
	global_load_lds_dwordx4 v188, s[54:55]
	s_waitcnt vmcnt(8)
	s_waitcnt lgkmcnt(0)
	s_barrier
	s_setprio 1
	s_waitcnt lgkmcnt(0)
	v_mfma_i32_16x16x64_i8 v[152:155], v[28:31], v[164:167], 0
	v_mfma_i32_16x16x64_i8 v[152:155], v[32:35], v[168:171], v[152:155]
	v_mfma_i32_16x16x64_i8 v[128:131], v[32:35], v[176:179], 0
	v_mfma_i32_16x16x64_i8 v[128:131], v[28:31], v[172:175], v[128:131]
	v_mfma_i32_16x16x64_i8 v[112:115], v[28:31], v[204:207], 0
	v_mfma_i32_16x16x64_i8 v[112:115], v[32:35], v[208:211], v[112:115]
	v_mfma_i32_16x16x64_i8 v[96:99], v[32:35], v[220:223], 0
	v_mfma_i32_16x16x64_i8 v[96:99], v[28:31], v[212:215], v[96:99]
	v_mfma_i32_16x16x64_i8 v[92:95], v[36:39], v[212:215], 0
	v_mfma_i32_16x16x64_i8 v[92:95], v[40:43], v[220:223], v[92:95]
	v_mfma_i32_16x16x64_i8 v[108:111], v[40:43], v[208:211], 0
	v_mfma_i32_16x16x64_i8 v[108:111], v[36:39], v[204:207], v[108:111]
	v_mfma_i32_16x16x64_i8 v[124:127], v[36:39], v[172:175], 0
	v_mfma_i32_16x16x64_i8 v[124:127], v[40:43], v[176:179], v[124:127]
	v_mfma_i32_16x16x64_i8 v[148:151], v[40:43], v[168:171], 0
	v_mfma_i32_16x16x64_i8 v[148:151], v[36:39], v[164:167], v[148:151]
	v_mfma_i32_16x16x64_i8 v[136:139], v[140:143], v[164:167], 0
	v_mfma_i32_16x16x64_i8 v[136:139], v[144:147], v[168:171], v[136:139]
	v_mfma_i32_16x16x64_i8 v[120:123], v[144:147], v[176:179], 0
	v_mfma_i32_16x16x64_i8 v[120:123], v[140:143], v[172:175], v[120:123]
	v_mfma_i32_16x16x64_i8 v[104:107], v[140:143], v[204:207], 0
	v_mfma_i32_16x16x64_i8 v[104:107], v[144:147], v[208:211], v[104:107]
	v_mfma_i32_16x16x64_i8 v[88:91], v[144:147], v[220:223], 0
	v_mfma_i32_16x16x64_i8 v[88:91], v[140:143], v[212:215], v[88:91]
	v_mfma_i32_16x16x64_i8 v[84:87], v[156:159], v[212:215], 0
	v_mfma_i32_16x16x64_i8 v[84:87], v[160:163], v[220:223], v[84:87]
	v_mfma_i32_16x16x64_i8 v[100:103], v[160:163], v[208:211], 0
	v_mfma_i32_16x16x64_i8 v[100:103], v[156:159], v[204:207], v[100:103]
	v_mfma_i32_16x16x64_i8 v[116:119], v[156:159], v[172:175], 0
	v_mfma_i32_16x16x64_i8 v[116:119], v[160:163], v[176:179], v[116:119]
	v_mfma_i32_16x16x64_i8 v[132:135], v[160:163], v[168:171], 0
	v_mfma_i32_16x16x64_i8 v[132:135], v[156:159], v[164:167], v[132:135]
	s_setprio 0
	s_barrier
	s_add_i32 s87, s87, s46
	v_lshl_add_u64 v[190:191], s[58:59], 0, v[2:3]
	s_mov_b32 m0, s87
	ds_read_b128 v[164:167], v219 offset:16384
	ds_read_b128 v[168:171], v219 offset:17408
	ds_read_b128 v[172:175], v219 offset:18432
	ds_read_b128 v[176:179], v219 offset:19456
	ds_read_b128 v[204:207], v219 offset:20480
	ds_read_b128 v[208:211], v219 offset:21504
	ds_read_b128 v[212:215], v219 offset:22528
	ds_read_b128 v[220:223], v219 offset:23552
	global_load_lds_dwordx4 v[190:191], off
	s_add_i32 m0, s87, 0x2000
	s_add_u32 s96, s58, 0x80000
	v_lshl_add_u64 v[224:225], s[58:59], 0, v[184:185]
	s_addc_u32 s97, s59, 0
	s_add_i32 s87, vcc_lo, s46
	global_load_lds_dwordx4 v[224:225], off
	s_mov_b32 m0, s87
	v_lshl_add_u64 v[228:229], s[60:61], 0, v[182:183]
	global_load_lds_dwordx4 v2, s[96:97]
	s_add_i32 m0, s87, 0x2000
	s_nop 0
	global_load_lds_dwordx4 v184, s[96:97]
	v_lshl_add_u64 v[226:227], s[60:61], 0, v[180:181]
	s_waitcnt vmcnt(6)
	s_waitcnt lgkmcnt(0)
	s_barrier
; #define PG8_STAGE(bufoff, gbase, voff) do { _Pragma("unroll") for (int _i = 0; _i < 2; ++_i) \
;         __builtin_amdgcn_global_load_lds((const unsigned*)((const char*)(gbase) + (voff)[_i]), (PG8_LAS unsigned*)(lds + (bufoff) + ldsw + _i * 8192), 16, 0, 0); } while (0)
; #define PG8_LDA(dst, b, h) do { _Pragma("unroll") for (int m = 0; m < 4; ++m) _Pragma("unroll") for (int k = 0; k < 2; ++k) dst[m][k] = *(const PG8_LAS bf16x8*)(lds + PG8_SA(b, h) + aoff + m * 2048 + k * 1024); } while (0)
; #define PG8_LDB(dst, b, h) do { _Pragma("unroll") for (int n = 0; n < 2; ++n) _Pragma("unroll") for (int k = 0; k < 2; ++k) dst[n][k] = *(const PG8_LAS bf16x8*)(lds + PG8_SB(b, h) + boff + n * 2048 + k * 1024); } while (0)
; #define PG8_WAIT_V(n) asm volatile("s_waitcnt vmcnt(" #n ")" ::: "memory")
; #define PG8_WAIT_L(n) asm volatile("s_waitcnt lgkmcnt(" #n ")" ::: "memory")
; #define PG8_BAR __builtin_amdgcn_s_barrier()
; #define PG8_SCHED __builtin_amdgcn_sched_barrier(0)
; template <class Epi, class Sched, bool ALIGN_EPI = false, bool SP2 = false, bool I8 = false>
; __device__ __forceinline__ void gemm_phase(PG8_LAS unsigned char* lds, const Gemm g, const Sched& S, const Epi& E) {
;     ...
;             PG8_WAIT_V(8); PG8_WAIT_L(0); PG8_BAR; PG8_MMA(1, 0, At, B0); PG8_MMA(1, 1, At, B1); PG8_BAR; PG8_SCHED;
;             PG8_LDB(B0, 1, 0); PG8_LDB(B1, 1, 1); PG8_SCHED; PG8_LDA(At, 1, 0); PG8_STAGE(PG8_SA(0, 1), a2 + hstep, voffA);
;             PG8_WAIT_V(8); PG8_WAIT_L(0); PG8_BAR; PG8_MMA(0, 0, At, B0); PG8_MMA(0, 1, At, B1); PG8_BAR; PG8_SCHED;
;             PG8_LDA(At, 1, 1); PG8_STAGE(PG8_SB(1, 0), b3, voffB); PG8_STAGE(PG8_SB(1, 1), b3 + hstep, voffB); PG8_STAGE(PG8_SA(1, 0), a3, voffA);
;             PG8_WAIT_V(8); PG8_WAIT_L(0); PG8_BAR; PG8_MMA(1, 0, At, B0); PG8_MMA(1, 1, At, B1); PG8_BAR; PG8_SCHED;
	s_setprio 1
	s_waitcnt lgkmcnt(0)
	v_mfma_i32_16x16x64_i8 v[80:83], v[28:31], v[164:167], 0
	v_mfma_i32_16x16x64_i8 v[80:83], v[32:35], v[168:171], v[80:83]
	v_mfma_i32_16x16x64_i8 v[64:67], v[32:35], v[176:179], 0
	v_mfma_i32_16x16x64_i8 v[64:67], v[28:31], v[172:175], v[64:67]
	v_mfma_i32_16x16x64_i8 v[48:51], v[28:31], v[204:207], 0
	v_mfma_i32_16x16x64_i8 v[48:51], v[32:35], v[208:211], v[48:51]
	v_mfma_i32_16x16x64_i8 v[16:19], v[32:35], v[220:223], 0
	v_mfma_i32_16x16x64_i8 v[16:19], v[28:31], v[212:215], v[16:19]
	v_mfma_i32_16x16x64_i8 v[12:15], v[36:39], v[212:215], 0
	v_mfma_i32_16x16x64_i8 v[12:15], v[40:43], v[220:223], v[12:15]
	v_mfma_i32_16x16x64_i8 v[44:47], v[40:43], v[208:211], 0
	v_mfma_i32_16x16x64_i8 v[44:47], v[36:39], v[204:207], v[44:47]
	v_mfma_i32_16x16x64_i8 v[60:63], v[36:39], v[172:175], 0
	v_mfma_i32_16x16x64_i8 v[60:63], v[40:43], v[176:179], v[60:63]
	v_mfma_i32_16x16x64_i8 v[76:79], v[40:43], v[168:171], 0
	v_mfma_i32_16x16x64_i8 v[76:79], v[36:39], v[164:167], v[76:79]
	v_mfma_i32_16x16x64_i8 v[28:31], v[140:143], v[164:167], 0
	v_mfma_i32_16x16x64_i8 v[28:31], v[144:147], v[168:171], v[28:31]
	v_mfma_i32_16x16x64_i8 v[36:39], v[144:147], v[176:179], 0
	v_mfma_i32_16x16x64_i8 v[36:39], v[140:143], v[172:175], v[36:39]
	v_mfma_i32_16x16x64_i8 v[24:27], v[140:143], v[204:207], 0
	v_mfma_i32_16x16x64_i8 v[24:27], v[144:147], v[208:211], v[24:27]
	v_mfma_i32_16x16x64_i8 v[8:11], v[144:147], v[220:223], 0
	v_mfma_i32_16x16x64_i8 v[8:11], v[140:143], v[212:215], v[8:11]
	v_mfma_i32_16x16x64_i8 v[4:7], v[156:159], v[212:215], 0
	v_mfma_i32_16x16x64_i8 v[4:7], v[160:163], v[220:223], v[4:7]
	v_mfma_i32_16x16x64_i8 v[20:23], v[160:163], v[208:211], 0
	v_mfma_i32_16x16x64_i8 v[20:23], v[156:159], v[204:207], v[20:23]
	v_mfma_i32_16x16x64_i8 v[40:43], v[156:159], v[172:175], 0
	v_mfma_i32_16x16x64_i8 v[40:43], v[160:163], v[176:179], v[40:43]
	v_mfma_i32_16x16x64_i8 v[32:35], v[160:163], v[168:171], 0
	v_mfma_i32_16x16x64_i8 v[32:35], v[156:159], v[164:167], v[32:35]
	s_setprio 0
	s_barrier
	s_mov_b32 m0, s65
	s_nop 0
	global_load_lds_dwordx4 v[226:227], off
	s_mov_b32 m0, s67
	s_nop 0
	global_load_lds_dwordx4 v[228:229], off
	s_add_i32 s87, 0, 0x18000
	s_add_i32 s96, 0, 0x1c000
	v_add_u32_e32 v72, s87, v217
	v_add_u32_e32 v160, s96, v217
	ds_read_b128 v[52:55], v72
	ds_read_b128 v[56:59], v72 offset:1024
	ds_read_b128 v[68:71], v72 offset:2048
	ds_read_b128 v[72:75], v72 offset:3072
	ds_read_b128 v[140:143], v160
	ds_read_b128 v[144:147], v160 offset:1024
	ds_read_b128 v[156:159], v160 offset:2048
	ds_read_b128 v[160:163], v160 offset:3072
	s_add_u32 s60, s60, 0x80000
	s_addc_u32 s61, s61, 0
	s_mov_b32 m0, s72
	ds_read_b128 v[164:167], v219 offset:32768
	ds_read_b128 v[168:171], v219 offset:33792
	ds_read_b128 v[172:175], v219 offset:34816
	ds_read_b128 v[176:179], v219 offset:35840
	ds_read_b128 v[204:207], v219 offset:36864
	ds_read_b128 v[208:211], v219 offset:37888
	ds_read_b128 v[212:215], v219 offset:38912
	ds_read_b128 v[220:223], v219 offset:39936
	global_load_lds_dwordx4 v180, s[60:61]
	s_mov_b32 m0, s73
	s_nop 0
	global_load_lds_dwordx4 v182, s[60:61]
	s_waitcnt vmcnt(8)
	s_waitcnt lgkmcnt(0)
	s_barrier
	s_setprio 1
	s_waitcnt lgkmcnt(0)
	v_mfma_i32_16x16x64_i8 v[152:155], v[52:55], v[164:167], v[152:155]
	v_mfma_i32_16x16x64_i8 v[152:155], v[56:59], v[168:171], v[152:155]
	v_mfma_i32_16x16x64_i8 v[128:131], v[56:59], v[176:179], v[128:131]
	v_mfma_i32_16x16x64_i8 v[128:131], v[52:55], v[172:175], v[128:131]
	v_mfma_i32_16x16x64_i8 v[112:115], v[52:55], v[204:207], v[112:115]
	v_mfma_i32_16x16x64_i8 v[112:115], v[56:59], v[208:211], v[112:115]
	v_mfma_i32_16x16x64_i8 v[96:99], v[56:59], v[220:223], v[96:99]
	v_mfma_i32_16x16x64_i8 v[96:99], v[52:55], v[212:215], v[96:99]
	v_mfma_i32_16x16x64_i8 v[92:95], v[68:71], v[212:215], v[92:95]
	v_mfma_i32_16x16x64_i8 v[92:95], v[72:75], v[220:223], v[92:95]
	v_mfma_i32_16x16x64_i8 v[108:111], v[72:75], v[208:211], v[108:111]
	v_mfma_i32_16x16x64_i8 v[108:111], v[68:71], v[204:207], v[108:111]
	v_mfma_i32_16x16x64_i8 v[124:127], v[68:71], v[172:175], v[124:127]
	v_mfma_i32_16x16x64_i8 v[124:127], v[72:75], v[176:179], v[124:127]
	v_mfma_i32_16x16x64_i8 v[148:151], v[72:75], v[168:171], v[148:151]
	v_mfma_i32_16x16x64_i8 v[148:151], v[68:71], v[164:167], v[148:151]
	v_mfma_i32_16x16x64_i8 v[136:139], v[140:143], v[164:167], v[136:139]
	v_mfma_i32_16x16x64_i8 v[136:139], v[144:147], v[168:171], v[136:139]
	v_mfma_i32_16x16x64_i8 v[120:123], v[144:147], v[176:179], v[120:123]
	v_mfma_i32_16x16x64_i8 v[120:123], v[140:143], v[172:175], v[120:123]
	v_mfma_i32_16x16x64_i8 v[104:107], v[140:143], v[204:207], v[104:107]
	v_mfma_i32_16x16x64_i8 v[104:107], v[144:147], v[208:211], v[104:107]
	v_mfma_i32_16x16x64_i8 v[88:91], v[144:147], v[220:223], v[88:91]
	v_mfma_i32_16x16x64_i8 v[88:91], v[140:143], v[212:215], v[88:91]
	v_mfma_i32_16x16x64_i8 v[84:87], v[156:159], v[212:215], v[84:87]
	v_mfma_i32_16x16x64_i8 v[84:87], v[160:163], v[220:223], v[84:87]
	v_mfma_i32_16x16x64_i8 v[100:103], v[160:163], v[208:211], v[100:103]
	v_mfma_i32_16x16x64_i8 v[100:103], v[156:159], v[204:207], v[100:103]
	v_mfma_i32_16x16x64_i8 v[116:119], v[156:159], v[172:175], v[116:119]
	v_mfma_i32_16x16x64_i8 v[116:119], v[160:163], v[176:179], v[116:119]
	v_mfma_i32_16x16x64_i8 v[132:135], v[160:163], v[168:171], v[132:135]
	v_mfma_i32_16x16x64_i8 v[132:135], v[156:159], v[164:167], v[132:135]
	s_setprio 0
	s_barrier
	s_add_i32 s60, s87, s46
	v_lshl_add_u64 v[190:191], v[190:191], 0, s[84:85]
	s_mov_b32 m0, s60
	ds_read_b128 v[164:167], v219 offset:49152
	ds_read_b128 v[168:171], v219 offset:50176
	ds_read_b128 v[172:175], v219 offset:51200
	ds_read_b128 v[176:179], v219 offset:52224
	ds_read_b128 v[204:207], v219 offset:53248
	ds_read_b128 v[208:211], v219 offset:54272
	ds_read_b128 v[212:215], v219 offset:55296
	ds_read_b128 v[220:223], v219 offset:56320
	global_load_lds_dwordx4 v[190:191], off
	s_add_i32 m0, s60, 0x2000
	s_add_u32 s58, s58, 0x80080
	v_lshl_add_u64 v[190:191], v[224:225], 0, s[84:85]
	s_addc_u32 s59, s59, 0
	s_add_i32 s60, s96, s46
	global_load_lds_dwordx4 v[190:191], off
	s_mov_b32 m0, s60
	s_nop 0
	global_load_lds_dwordx4 v2, s[58:59]
	s_add_i32 m0, s60, 0x2000
	s_nop 0
	global_load_lds_dwordx4 v184, s[58:59]
	s_cmp_eq_u32 s86, 28
	s_cbranch_scc0 .Ldefer_1843_peel
	v_lshl_add_u64 v[190:191], v[226:227], 0, s[84:85]
	s_mov_b32 m0, s28
	s_nop 0
	global_load_lds_dwordx4 v[190:191], off
	v_lshl_add_u64 v[190:191], v[228:229], 0, s[84:85]
	s_mov_b32 m0, s77
	s_nop 0
	global_load_lds_dwordx4 v[190:191], off

; #define PG8_STAGE(bufoff, gbase, voff) do { _Pragma("unroll") for (int _i = 0; _i < 2; ++_i) \
;         __builtin_amdgcn_global_load_lds((const unsigned*)((const char*)(gbase) + (voff)[_i]), (PG8_LAS unsigned*)(lds + (bufoff) + ldsw + _i * 8192), 16, 0, 0); } while (0)
; #define PG8_LDA(dst, b, h) do { _Pragma("unroll") for (int m = 0; m < 4; ++m) _Pragma("unroll") for (int k = 0; k < 2; ++k) dst[m][k] = *(const PG8_LAS bf16x8*)(lds + PG8_SA(b, h) + aoff + m * 2048 + k * 1024); } while (0)
; #define PG8_LDB(dst, b, h) do { _Pragma("unroll") for (int n = 0; n < 2; ++n) _Pragma("unroll") for (int k = 0; k < 2; ++k) dst[n][k] = *(const PG8_LAS bf16x8*)(lds + PG8_SB(b, h) + boff + n * 2048 + k * 1024); } while (0)
; #define PG8_WAIT_V(n) asm volatile("s_waitcnt vmcnt(" #n ")" ::: "memory")
; #define PG8_WAIT_L(n) asm volatile("s_waitcnt lgkmcnt(" #n ")" ::: "memory")
; #define PG8_BAR __builtin_amdgcn_s_barrier()
; #define PG8_SCHED __builtin_amdgcn_sched_barrier(0)
; template <class Epi, class Sched, bool ALIGN_EPI = false, bool SP2 = false, bool I8 = false>
; __device__ __forceinline__ void gemm_phase(PG8_LAS unsigned char* lds, const Gemm g, const Sched& S, const Epi& E) {
;     ...
;         for (int t = 0; t < nt; t += 2) {
;             const bool last = (t == nt - 2);
;             const char* a1 = cA + (size_t)(t + 1) * kstep;
;             const char* a2 = last ? nA : cA + (size_t)(t + 2) * kstep; const char* b2 = last ? nB : cB + (size_t)(t + 2) * kstep;
;             const char* a3 = a2 + kstep; const char* b3 = b2 + kstep;
;             if (last && has_next) S.a_ready(nxt);
;             if constexpr (SP2) {
;             PG8_LDB(B0, 0, 0); PG8_LDB(B1, 0, 1); PG8_SCHED; PG8_LDA(At, 0, 0); PG8_STAGE(PG8_SA(1, 1), a1 + hstep, voffA);
;             PG8_WAIT_V(8); PG8_WAIT_L(0); PG8_BAR; PG8_MMA(0, 0, At, B0); PG8_MMA(0, 1, At, B1); PG8_BAR; PG8_SCHED;
;             PG8_LDA(At, 0, 1); PG8_STAGE(PG8_SB(0, 0), b2, voffB); PG8_STAGE(PG8_SB(0, 1), b2 + hstep, voffB); PG8_STAGE(PG8_SA(0, 0), a2, voffA);
;             PG8_WAIT_V(8); PG8_WAIT_L(0); PG8_BAR; PG8_MMA(1, 0, At, B0); PG8_MMA(1, 1, At, B1); PG8_BAR; PG8_SCHED;
.LBB0_1843:
	s_add_u32 s58, s54, 0xfff80080
	s_addc_u32 s59, s55, -1
	s_add_i32 s87, 0, 0x10000
	s_cmp_eq_u32 s86, 28
	s_cselect_b32 s61, s11, s59
	s_cselect_b32 s60, s13, s58
	s_cselect_b32 s59, s34, s49
	s_cselect_b32 s58, s35, s45
	s_add_i32 vcc_lo, 0, 0x14000
	v_add_u32_e32 v40, s87, v217
	v_add_u32_e32 v160, vcc_lo, v217
	ds_read_b128 v[28:31], v40
	ds_read_b128 v[32:35], v40 offset:1024
	ds_read_b128 v[36:39], v40 offset:2048
	ds_read_b128 v[40:43], v40 offset:3072
	ds_read_b128 v[140:143], v160
	ds_read_b128 v[144:147], v160 offset:1024
	ds_read_b128 v[156:159], v160 offset:2048
	ds_read_b128 v[160:163], v160 offset:3072
	v_lshl_add_u64 v[190:191], v[226:227], 0, s[84:85]
	s_mov_b32 m0, s28
	s_nop 0
	global_load_lds_dwordx4 v[190:191], off
	v_lshl_add_u64 v[190:191], v[228:229], 0, s[84:85]
	s_mov_b32 m0, s77
	s_nop 0
	global_load_lds_dwordx4 v[190:191], off
	s_add_i32 m0, s65, 0xc000
	ds_read_b128 v[164:167], v219
	ds_read_b128 v[168:171], v219 offset:1024
	ds_read_b128 v[172:175], v219 offset:2048
	ds_read_b128 v[176:179], v219 offset:3072
	ds_read_b128 v[204:207], v219 offset:4096
	ds_read_b128 v[208:211], v219 offset:5120
	ds_read_b128 v[212:215], v219 offset:6144
	ds_read_b128 v[220:223], v219 offset:7168
	global_load_lds_dwordx4 v186, s[54:55]
	s_add_i32 m0, s65, 0xe000
	s_nop 0
	global_load_lds_dwordx4 v188, s[54:55]
	s_waitcnt vmcnt(8)
	s_waitcnt lgkmcnt(0)
	s_barrier
	s_setprio 1
	s_waitcnt lgkmcnt(0)
	v_mfma_i32_16x16x64_i8 v[152:155], v[28:31], v[164:167], v[152:155]
	v_mfma_i32_16x16x64_i8 v[152:155], v[32:35], v[168:171], v[152:155]
	v_mfma_i32_16x16x64_i8 v[128:131], v[32:35], v[176:179], v[128:131]
	v_mfma_i32_16x16x64_i8 v[128:131], v[28:31], v[172:175], v[128:131]
	v_mfma_i32_16x16x64_i8 v[112:115], v[28:31], v[204:207], v[112:115]
	v_mfma_i32_16x16x64_i8 v[112:115], v[32:35], v[208:211], v[112:115]
	v_mfma_i32_16x16x64_i8 v[96:99], v[32:35], v[220:223], v[96:99]
	v_mfma_i32_16x16x64_i8 v[96:99], v[28:31], v[212:215], v[96:99]
	v_mfma_i32_16x16x64_i8 v[92:95], v[36:39], v[212:215], v[92:95]
	v_mfma_i32_16x16x64_i8 v[92:95], v[40:43], v[220:223], v[92:95]
	v_mfma_i32_16x16x64_i8 v[108:111], v[40:43], v[208:211], v[108:111]
	v_mfma_i32_16x16x64_i8 v[108:111], v[36:39], v[204:207], v[108:111]
	v_mfma_i32_16x16x64_i8 v[124:127], v[36:39], v[172:175], v[124:127]
	v_mfma_i32_16x16x64_i8 v[124:127], v[40:43], v[176:179], v[124:127]
	v_mfma_i32_16x16x64_i8 v[148:151], v[40:43], v[168:171], v[148:151]
	v_mfma_i32_16x16x64_i8 v[148:151], v[36:39], v[164:167], v[148:151]
	v_mfma_i32_16x16x64_i8 v[136:139], v[140:143], v[164:167], v[136:139]
	v_mfma_i32_16x16x64_i8 v[136:139], v[144:147], v[168:171], v[136:139]
	v_mfma_i32_16x16x64_i8 v[120:123], v[144:147], v[176:179], v[120:123]
	v_mfma_i32_16x16x64_i8 v[120:123], v[140:143], v[172:175], v[120:123]
	v_mfma_i32_16x16x64_i8 v[104:107], v[140:143], v[204:207], v[104:107]
	v_mfma_i32_16x16x64_i8 v[104:107], v[144:147], v[208:211], v[104:107]
	v_mfma_i32_16x16x64_i8 v[88:91], v[144:147], v[220:223], v[88:91]
	v_mfma_i32_16x16x64_i8 v[88:91], v[140:143], v[212:215], v[88:91]
	v_mfma_i32_16x16x64_i8 v[84:87], v[156:159], v[212:215], v[84:87]
	v_mfma_i32_16x16x64_i8 v[84:87], v[160:163], v[220:223], v[84:87]
	v_mfma_i32_16x16x64_i8 v[100:103], v[160:163], v[208:211], v[100:103]
	v_mfma_i32_16x16x64_i8 v[100:103], v[156:159], v[204:207], v[100:103]
	v_mfma_i32_16x16x64_i8 v[116:119], v[156:159], v[172:175], v[116:119]
	v_mfma_i32_16x16x64_i8 v[116:119], v[160:163], v[176:179], v[116:119]
	v_mfma_i32_16x16x64_i8 v[132:135], v[160:163], v[168:171], v[132:135]
	v_mfma_i32_16x16x64_i8 v[132:135], v[156:159], v[164:167], v[132:135]
	s_setprio 0
	s_barrier
	s_add_i32 s87, s87, s46
	v_lshl_add_u64 v[190:191], s[58:59], 0, v[2:3]
	s_mov_b32 m0, s87
	ds_read_b128 v[164:167], v219 offset:16384
	ds_read_b128 v[168:171], v219 offset:17408
	ds_read_b128 v[172:175], v219 offset:18432
	ds_read_b128 v[176:179], v219 offset:19456
	ds_read_b128 v[204:207], v219 offset:20480
	ds_read_b128 v[208:211], v219 offset:21504
	ds_read_b128 v[212:215], v219 offset:22528
	ds_read_b128 v[220:223], v219 offset:23552
	global_load_lds_dwordx4 v[190:191], off
	s_add_i32 m0, s87, 0x2000
	s_add_u32 s96, s58, 0x80000
	v_lshl_add_u64 v[224:225], s[58:59], 0, v[184:185]
	s_addc_u32 s97, s59, 0
	s_add_i32 s87, vcc_lo, s46
	global_load_lds_dwordx4 v[224:225], off
	s_mov_b32 m0, s87
	v_lshl_add_u64 v[228:229], s[60:61], 0, v[182:183]
	global_load_lds_dwordx4 v2, s[96:97]
	s_add_i32 m0, s87, 0x2000
	s_nop 0
	global_load_lds_dwordx4 v184, s[96:97]
	v_lshl_add_u64 v[226:227], s[60:61], 0, v[180:181]
	s_waitcnt vmcnt(6)
	s_waitcnt lgkmcnt(0)
	s_barrier
; #define PG8_STAGE(bufoff, gbase, voff) do { _Pragma("unroll") for (int _i = 0; _i < 2; ++_i) \
;         __builtin_amdgcn_global_load_lds((const unsigned*)((const char*)(gbase) + (voff)[_i]), (PG8_LAS unsigned*)(lds + (bufoff) + ldsw + _i * 8192), 16, 0, 0); } while (0)
; #define PG8_LDA(dst, b, h) do { _Pragma("unroll") for (int m = 0; m < 4; ++m) _Pragma("unroll") for (int k = 0; k < 2; ++k) dst[m][k] = *(const PG8_LAS bf16x8*)(lds + PG8_SA(b, h) + aoff + m * 2048 + k * 1024); } while (0)
; #define PG8_LDB(dst, b, h) do { _Pragma("unroll") for (int n = 0; n < 2; ++n) _Pragma("unroll") for (int k = 0; k < 2; ++k) dst[n][k] = *(const PG8_LAS bf16x8*)(lds + PG8_SB(b, h) + boff + n * 2048 + k * 1024); } while (0)
; #define PG8_WAIT_V(n) asm volatile("s_waitcnt vmcnt(" #n ")" ::: "memory")
; #define PG8_WAIT_L(n) asm volatile("s_waitcnt lgkmcnt(" #n ")" ::: "memory")
; #define PG8_BAR __builtin_amdgcn_s_barrier()
; #define PG8_SCHED __builtin_amdgcn_sched_barrier(0)
; template <class Epi, class Sched, bool ALIGN_EPI = false, bool SP2 = false, bool I8 = false>
; __device__ __forceinline__ void gemm_phase(PG8_LAS unsigned char* lds, const Gemm g, const Sched& S, const Epi& E) {
;     ...
;             PG8_WAIT_V(8); PG8_WAIT_L(0); PG8_BAR; PG8_MMA(1, 0, At, B0); PG8_MMA(1, 1, At, B1); PG8_BAR; PG8_SCHED;
;             PG8_LDB(B0, 1, 0); PG8_LDB(B1, 1, 1); PG8_SCHED; PG8_LDA(At, 1, 0); PG8_STAGE(PG8_SA(0, 1), a2 + hstep, voffA);
;             PG8_WAIT_V(8); PG8_WAIT_L(0); PG8_BAR; PG8_MMA(0, 0, At, B0); PG8_MMA(0, 1, At, B1); PG8_BAR; PG8_SCHED;
;             PG8_LDA(At, 1, 1); PG8_STAGE(PG8_SB(1, 0), b3, voffB); PG8_STAGE(PG8_SB(1, 1), b3 + hstep, voffB); PG8_STAGE(PG8_SA(1, 0), a3, voffA);
;             PG8_WAIT_V(8); PG8_WAIT_L(0); PG8_BAR; PG8_MMA(1, 0, At, B0); PG8_MMA(1, 1, At, B1); PG8_BAR; PG8_SCHED;
	s_setprio 1
	s_waitcnt lgkmcnt(0)
	v_mfma_i32_16x16x64_i8 v[80:83], v[28:31], v[164:167], v[80:83]
	v_mfma_i32_16x16x64_i8 v[80:83], v[32:35], v[168:171], v[80:83]
	v_mfma_i32_16x16x64_i8 v[64:67], v[32:35], v[176:179], v[64:67]
	v_mfma_i32_16x16x64_i8 v[64:67], v[28:31], v[172:175], v[64:67]
	v_mfma_i32_16x16x64_i8 v[48:51], v[28:31], v[204:207], v[48:51]
	v_mfma_i32_16x16x64_i8 v[48:51], v[32:35], v[208:211], v[48:51]
	v_mfma_i32_16x16x64_i8 v[16:19], v[32:35], v[220:223], v[16:19]
	v_mfma_i32_16x16x64_i8 v[16:19], v[28:31], v[212:215], v[16:19]
	v_mfma_i32_16x16x64_i8 v[12:15], v[36:39], v[212:215], v[12:15]
	v_mfma_i32_16x16x64_i8 v[12:15], v[40:43], v[220:223], v[12:15]
	v_mfma_i32_16x16x64_i8 v[44:47], v[40:43], v[208:211], v[44:47]
	v_mfma_i32_16x16x64_i8 v[44:47], v[36:39], v[204:207], v[44:47]
	v_mfma_i32_16x16x64_i8 v[60:63], v[36:39], v[172:175], v[60:63]
	v_mfma_i32_16x16x64_i8 v[60:63], v[40:43], v[176:179], v[60:63]
	v_mfma_i32_16x16x64_i8 v[76:79], v[40:43], v[168:171], v[76:79]
	v_mfma_i32_16x16x64_i8 v[76:79], v[36:39], v[164:167], v[76:79]
	v_mfma_i32_16x16x64_i8 v[28:31], v[140:143], v[164:167], v[72:75]
	v_mfma_i32_16x16x64_i8 v[28:31], v[144:147], v[168:171], v[28:31]
	v_mfma_i32_16x16x64_i8 v[36:39], v[144:147], v[176:179], v[56:59]
	v_mfma_i32_16x16x64_i8 v[36:39], v[140:143], v[172:175], v[36:39]
	v_mfma_i32_16x16x64_i8 v[24:27], v[140:143], v[204:207], v[24:27]
	v_mfma_i32_16x16x64_i8 v[24:27], v[144:147], v[208:211], v[24:27]
	v_mfma_i32_16x16x64_i8 v[8:11], v[144:147], v[220:223], v[8:11]
	v_mfma_i32_16x16x64_i8 v[8:11], v[140:143], v[212:215], v[8:11]
	v_mfma_i32_16x16x64_i8 v[4:7], v[156:159], v[212:215], v[4:7]
	v_mfma_i32_16x16x64_i8 v[4:7], v[160:163], v[220:223], v[4:7]
	v_mfma_i32_16x16x64_i8 v[20:23], v[160:163], v[208:211], v[20:23]
	v_mfma_i32_16x16x64_i8 v[20:23], v[156:159], v[204:207], v[20:23]
	v_mfma_i32_16x16x64_i8 v[40:43], v[156:159], v[172:175], v[52:55]
	v_mfma_i32_16x16x64_i8 v[40:43], v[160:163], v[176:179], v[40:43]
	v_mfma_i32_16x16x64_i8 v[32:35], v[160:163], v[168:171], v[68:71]
	v_mfma_i32_16x16x64_i8 v[32:35], v[156:159], v[164:167], v[32:35]
	s_setprio 0
	s_barrier
	s_mov_b32 m0, s65
	s_nop 0
	global_load_lds_dwordx4 v[226:227], off
	s_mov_b32 m0, s67
	s_nop 0
	global_load_lds_dwordx4 v[228:229], off
	s_add_i32 s87, 0, 0x18000
	s_add_i32 s96, 0, 0x1c000
	v_add_u32_e32 v72, s87, v217
	v_add_u32_e32 v160, s96, v217
	ds_read_b128 v[52:55], v72
	ds_read_b128 v[56:59], v72 offset:1024
	ds_read_b128 v[68:71], v72 offset:2048
	ds_read_b128 v[72:75], v72 offset:3072
	ds_read_b128 v[140:143], v160
	ds_read_b128 v[144:147], v160 offset:1024
	ds_read_b128 v[156:159], v160 offset:2048
	ds_read_b128 v[160:163], v160 offset:3072
	s_add_u32 s60, s60, 0x80000
	s_addc_u32 s61, s61, 0
	s_mov_b32 m0, s72
	ds_read_b128 v[164:167], v219 offset:32768
	ds_read_b128 v[168:171], v219 offset:33792
	ds_read_b128 v[172:175], v219 offset:34816
	ds_read_b128 v[176:179], v219 offset:35840
	ds_read_b128 v[204:207], v219 offset:36864
	ds_read_b128 v[208:211], v219 offset:37888
	ds_read_b128 v[212:215], v219 offset:38912
	ds_read_b128 v[220:223], v219 offset:39936
	global_load_lds_dwordx4 v180, s[60:61]
	s_mov_b32 m0, s73
	s_nop 0
	global_load_lds_dwordx4 v182, s[60:61]
	s_waitcnt vmcnt(8)
	s_waitcnt lgkmcnt(0)
	s_barrier
	s_setprio 1
	s_waitcnt lgkmcnt(0)
	v_mfma_i32_16x16x64_i8 v[152:155], v[52:55], v[164:167], v[152:155]
	v_mfma_i32_16x16x64_i8 v[152:155], v[56:59], v[168:171], v[152:155]
	v_mfma_i32_16x16x64_i8 v[128:131], v[56:59], v[176:179], v[128:131]
	v_mfma_i32_16x16x64_i8 v[128:131], v[52:55], v[172:175], v[128:131]
	v_mfma_i32_16x16x64_i8 v[112:115], v[52:55], v[204:207], v[112:115]
	v_mfma_i32_16x16x64_i8 v[112:115], v[56:59], v[208:211], v[112:115]
	v_mfma_i32_16x16x64_i8 v[96:99], v[56:59], v[220:223], v[96:99]
	v_mfma_i32_16x16x64_i8 v[96:99], v[52:55], v[212:215], v[96:99]
	v_mfma_i32_16x16x64_i8 v[92:95], v[68:71], v[212:215], v[92:95]
	v_mfma_i32_16x16x64_i8 v[92:95], v[72:75], v[220:223], v[92:95]
	v_mfma_i32_16x16x64_i8 v[108:111], v[72:75], v[208:211], v[108:111]
	v_mfma_i32_16x16x64_i8 v[108:111], v[68:71], v[204:207], v[108:111]
	v_mfma_i32_16x16x64_i8 v[124:127], v[68:71], v[172:175], v[124:127]
	v_mfma_i32_16x16x64_i8 v[124:127], v[72:75], v[176:179], v[124:127]
	v_mfma_i32_16x16x64_i8 v[148:151], v[72:75], v[168:171], v[148:151]
	v_mfma_i32_16x16x64_i8 v[148:151], v[68:71], v[164:167], v[148:151]
	v_mfma_i32_16x16x64_i8 v[136:139], v[140:143], v[164:167], v[136:139]
	v_mfma_i32_16x16x64_i8 v[136:139], v[144:147], v[168:171], v[136:139]
	v_mfma_i32_16x16x64_i8 v[120:123], v[144:147], v[176:179], v[120:123]
	v_mfma_i32_16x16x64_i8 v[120:123], v[140:143], v[172:175], v[120:123]
	v_mfma_i32_16x16x64_i8 v[104:107], v[140:143], v[204:207], v[104:107]
	v_mfma_i32_16x16x64_i8 v[104:107], v[144:147], v[208:211], v[104:107]
	v_mfma_i32_16x16x64_i8 v[88:91], v[144:147], v[220:223], v[88:91]
	v_mfma_i32_16x16x64_i8 v[88:91], v[140:143], v[212:215], v[88:91]
	v_mfma_i32_16x16x64_i8 v[84:87], v[156:159], v[212:215], v[84:87]
	v_mfma_i32_16x16x64_i8 v[84:87], v[160:163], v[220:223], v[84:87]
	v_mfma_i32_16x16x64_i8 v[100:103], v[160:163], v[208:211], v[100:103]
	v_mfma_i32_16x16x64_i8 v[100:103], v[156:159], v[204:207], v[100:103]
	v_mfma_i32_16x16x64_i8 v[116:119], v[156:159], v[172:175], v[116:119]
	v_mfma_i32_16x16x64_i8 v[116:119], v[160:163], v[176:179], v[116:119]
	v_mfma_i32_16x16x64_i8 v[132:135], v[160:163], v[168:171], v[132:135]
	v_mfma_i32_16x16x64_i8 v[132:135], v[156:159], v[164:167], v[132:135]
	s_setprio 0
	s_barrier
	s_add_i32 s60, s87, s46
	v_lshl_add_u64 v[190:191], v[190:191], 0, s[84:85]
	s_mov_b32 m0, s60
	ds_read_b128 v[164:167], v219 offset:49152
	ds_read_b128 v[168:171], v219 offset:50176
	ds_read_b128 v[172:175], v219 offset:51200
	ds_read_b128 v[176:179], v219 offset:52224
	ds_read_b128 v[204:207], v219 offset:53248
	ds_read_b128 v[208:211], v219 offset:54272
	ds_read_b128 v[212:215], v219 offset:55296
	ds_read_b128 v[220:223], v219 offset:56320
	global_load_lds_dwordx4 v[190:191], off
	s_add_i32 m0, s60, 0x2000
	s_add_u32 s58, s58, 0x80080
	v_lshl_add_u64 v[190:191], v[224:225], 0, s[84:85]
	s_addc_u32 s59, s59, 0
	s_add_i32 s60, s96, s46
	global_load_lds_dwordx4 v[190:191], off
	s_mov_b32 m0, s60
	s_nop 0
	global_load_lds_dwordx4 v2, s[58:59]
	s_add_i32 m0, s60, 0x2000
	s_nop 0
	global_load_lds_dwordx4 v184, s[58:59]
	s_cmp_eq_u32 s86, 28
	s_cbranch_scc0 .Ldefer_1843_body
	v_lshl_add_u64 v[190:191], v[226:227], 0, s[84:85]
	s_mov_b32 m0, s28
	s_nop 0
	global_load_lds_dwordx4 v[190:191], off
	v_lshl_add_u64 v[190:191], v[228:229], 0, s[84:85]
	s_mov_b32 m0, s77
	s_nop 0
	global_load_lds_dwordx4 v[190:191], off
